# combo25 + FFT run-time twiddle multiplies read (cos,sin) directly with op_sel/neg_lo instead of building a (-sin,sin) pair per use (93 sites, 2 VALU fewer each)
# speedup vs baseline: 1.0030x; 1.0005x over previous
.Lmy_fft_hj:
	v_mov_b32 v66, 0
	s_movk_i32 s5, 0x200
	v_add_u32_e32 v0, v66, v0
	v_cvt_f32_i32_e32 v68, v0
	v_ashrrev_i32_e32 v66, 5, v0
	v_lshlrev_b32_e32 v67, 3, v0
	v_add_u32_e32 v69, 0x400, v0
	v_add_u32_e32 v70, 0x800, v0
	v_add_u32_e32 v71, 0xc00, v0
	v_add_u32_e32 v72, 0x1000, v0
	v_add_u32_e32 v73, 0x1400, v0
	v_add_u32_e32 v74, 0x1800, v0
	v_add_u32_e32 v75, 0x1c00, v0
	v_add_u32_e32 v76, 0x2000, v0
	v_add_u32_e32 v77, 0x2400, v0
	v_add_u32_e32 v78, 0x2800, v0
	v_add_u32_e32 v79, 0x2c00, v0
	v_add_u32_e32 v80, 0x3000, v0
	v_add_u32_e32 v81, 0x3400, v0
	v_add_u32_e32 v82, 0x3800, v0
	v_add_u32_e32 v0, 0x3c00, v0
	v_lshlrev_b32_e32 v66, 3, v66
	v_ashrrev_i32_e32 v69, 5, v69
	v_ashrrev_i32_e32 v70, 5, v70
	v_ashrrev_i32_e32 v71, 5, v71
	v_ashrrev_i32_e32 v72, 5, v72
	v_ashrrev_i32_e32 v73, 5, v73
	v_ashrrev_i32_e32 v74, 5, v74
	v_ashrrev_i32_e32 v75, 5, v75
	v_ashrrev_i32_e32 v83, 5, v76
	v_ashrrev_i32_e32 v84, 5, v77
	v_ashrrev_i32_e32 v85, 5, v78
	v_ashrrev_i32_e32 v86, 5, v79
	v_ashrrev_i32_e32 v87, 5, v80
	v_ashrrev_i32_e32 v88, 5, v81
	v_ashrrev_i32_e32 v89, 5, v82
	v_ashrrev_i32_e32 v90, 5, v0
	v_lshlrev_b32_e32 v0, 3, v0
	v_add3_u32 v171, 0, v66, v67
	v_lshlrev_b32_e32 v66, 3, v69
	v_lshlrev_b32_e32 v69, 3, v70
	v_lshlrev_b32_e32 v70, 3, v71
	v_lshlrev_b32_e32 v71, 3, v72
	v_lshlrev_b32_e32 v72, 3, v73
	v_lshlrev_b32_e32 v73, 3, v74
	v_lshlrev_b32_e32 v74, 3, v75
	v_lshlrev_b32_e32 v75, 3, v83
	v_lshlrev_b32_e32 v83, 3, v84
	v_lshlrev_b32_e32 v84, 3, v85
	v_lshlrev_b32_e32 v85, 3, v86
	v_lshlrev_b32_e32 v86, 3, v87
	v_lshlrev_b32_e32 v87, 3, v88
	v_lshlrev_b32_e32 v88, 3, v89
	v_lshlrev_b32_e32 v89, 3, v90
	v_add3_u32 v186, 0, v89, v0
	v_mul_f32_e32 v0, 0x38800000, v68
	v_add3_u32 v172, 0, v66, v67
	v_add3_u32 v173, 0, v69, v67
	v_add3_u32 v174, 0, v70, v67
	v_add3_u32 v175, 0, v71, v67
	v_add3_u32 v176, 0, v72, v67
	v_add3_u32 v177, 0, v73, v67
	v_add3_u32 v178, 0, v74, v67
	v_sin_f32_e32 v67, v0
	v_cos_f32_e32 v66, v0
	v_lshlrev_b32_e32 v76, 3, v76
	v_add3_u32 v179, 0, v75, v76
	v_xor_b32_e32 v68, 0x80000000, v67
	v_mov_b32_e32 v69, v67
	v_pk_mul_f32 v[70:71], v[68:69], v[66:67] op_sel:[0,1] op_sel_hi:[1,0]
	v_lshlrev_b32_e32 v78, 3, v78
	v_pk_fma_f32 v[70:71], v[66:67], v[66:67], v[70:71] op_sel_hi:[1,0,1]
	v_lshlrev_b32_e32 v79, 3, v79
	v_pk_mul_f32 v[74:75], v[68:69], v[70:71] op_sel:[0,1] op_sel_hi:[1,0]
	v_add3_u32 v181, 0, v84, v78
	v_pk_fma_f32 v[74:75], v[70:71], v[66:67], v[74:75] op_sel_hi:[1,0,1]
	v_add3_u32 v182, 0, v85, v79
	v_pk_mul_f32 v[78:79], v[68:69], v[74:75] op_sel:[0,1] op_sel_hi:[1,0]
	v_lshlrev_b32_e32 v77, 3, v77
	v_lshlrev_b32_e32 v82, 3, v82
	v_pk_fma_f32 v[78:79], v[74:75], v[66:67], v[78:79] op_sel_hi:[1,0,1]
	v_add3_u32 v180, 0, v83, v77
	v_add3_u32 v185, 0, v88, v82
	v_pk_mul_f32 v[82:83], v[68:69], v[78:79] op_sel:[0,1] op_sel_hi:[1,0]
	v_lshlrev_b32_e32 v80, 3, v80
	v_lshlrev_b32_e32 v81, 3, v81
	v_pk_fma_f32 v[82:83], v[78:79], v[66:67], v[82:83] op_sel_hi:[1,0,1]
	v_add3_u32 v183, 0, v86, v80
	v_add3_u32 v184, 0, v87, v81
	v_pk_mul_f32 v[86:87], v[68:69], v[82:83] op_sel:[0,1] op_sel_hi:[1,0]
	s_waitcnt vmcnt(31)
	v_lshlrev_b32_e32 v126, 16, v105
	v_pk_fma_f32 v[86:87], v[82:83], v[66:67], v[86:87] op_sel_hi:[1,0,1]
	s_waitcnt vmcnt(30)
	v_lshlrev_b32_e32 v127, 16, v127
	v_pk_mul_f32 v[90:91], v[68:69], v[86:87] op_sel:[0,1] op_sel_hi:[1,0]
	s_waitcnt vmcnt(29)
	v_lshlrev_b32_e32 v129, 16, v128
	v_pk_fma_f32 v[90:91], v[86:87], v[66:67], v[90:91] op_sel_hi:[1,0,1]
	s_waitcnt vmcnt(24)
	v_lshlrev_b32_e32 v128, 16, v134
	v_pk_mul_f32 v[94:95], v[68:69], v[90:91] op_sel:[0,1] op_sel_hi:[1,0]
	v_lshlrev_b32_e32 v130, 16, v130
	v_pk_fma_f32 v[94:95], v[90:91], v[66:67], v[94:95] op_sel_hi:[1,0,1]
	v_lshlrev_b32_e32 v131, 16, v131
	v_pk_mul_f32 v[98:99], v[68:69], v[94:95] op_sel:[0,1] op_sel_hi:[1,0]
	v_lshlrev_b32_e32 v132, 16, v132
	v_pk_fma_f32 v[98:99], v[94:95], v[66:67], v[98:99] op_sel_hi:[1,0,1]
	v_lshlrev_b32_e32 v133, 16, v133
	v_pk_mul_f32 v[102:103], v[68:69], v[98:99] op_sel:[0,1] op_sel_hi:[1,0]
	s_waitcnt vmcnt(22)
	v_lshlrev_b32_e32 v135, 16, v135
	v_pk_fma_f32 v[102:103], v[98:99], v[66:67], v[102:103] op_sel_hi:[1,0,1]
	v_lshlrev_b32_e32 v134, 16, v136
	v_pk_mul_f32 v[108:109], v[68:69], v[102:103] op_sel:[0,1] op_sel_hi:[1,0]
	s_waitcnt vmcnt(21)
	v_lshlrev_b32_e32 v136, 16, v137
	v_pk_fma_f32 v[108:109], v[102:103], v[66:67], v[108:109] op_sel_hi:[1,0,1]
	s_waitcnt vmcnt(20)
	v_lshlrev_b32_e32 v137, 16, v138
	v_pk_mul_f32 v[112:113], v[68:69], v[108:109] op_sel:[0,1] op_sel_hi:[1,0]
	s_waitcnt vmcnt(19)
	v_lshlrev_b32_e32 v138, 16, v139
	s_waitcnt vmcnt(18)
	v_lshlrev_b32_e32 v139, 16, v140
	s_waitcnt vmcnt(17)
	v_lshlrev_b32_e32 v140, 16, v141
	s_waitcnt vmcnt(16)
	v_lshlrev_b32_e32 v141, 16, v142
	v_pk_fma_f32 v[112:113], v[108:109], v[66:67], v[112:113] op_sel_hi:[1,0,1]
	v_pk_add_f32 v[142:143], v[126:127], 0 op_sel_hi:[1,0]
	v_pk_add_f32 v[144:145], v[128:129], 0 op_sel_hi:[1,0]
	v_pk_mul_f32 v[146:147], v[128:129], s[36:37]
	v_pk_add_f32 v[148:149], v[130:131], 0 op_sel_hi:[1,0]
	v_pk_mul_f32 v[150:151], v[130:131], s[16:17]
	v_pk_add_f32 v[152:153], v[132:133], 0 op_sel_hi:[1,0]
	v_pk_mul_f32 v[154:155], v[132:133], s[38:39]
	v_pk_add_f32 v[156:157], v[134:135], 0 op_sel_hi:[1,0]
	v_xor_b32_e32 v159, 0x80000000, v134
	v_mov_b32_e32 v158, v135
	v_pk_add_f32 v[134:135], v[136:137], 0 op_sel_hi:[1,0]
	v_pk_mul_f32 v[160:161], v[136:137], s[38:39]
	v_pk_add_f32 v[162:163], v[138:139], 0 op_sel_hi:[1,0]
	v_pk_mul_f32 v[164:165], v[138:139], s[16:17]
	v_pk_add_f32 v[166:167], v[140:141], 0 op_sel_hi:[1,0]
	v_pk_mul_f32 v[168:169], v[140:141], s[36:37]
	v_pk_mul_f32 v[116:117], v[68:69], v[112:113] op_sel:[0,1] op_sel_hi:[1,0]
	v_pk_fma_f32 v[128:129], v[128:129], s[6:7], v[146:147] op_sel:[0,0,1] op_sel_hi:[1,0,0]
	v_pk_fma_f32 v[130:131], v[130:131], s[10:11], v[150:151] op_sel:[0,0,1] op_sel_hi:[1,0,0]
	v_pk_fma_f32 v[132:133], v[132:133], s[14:15], v[154:155] op_sel:[0,0,1] op_sel_hi:[1,0,0]
	v_pk_fma_f32 v[136:137], v[136:137], s[4:5], v[160:161] op_sel:[0,0,1] op_sel_hi:[1,0,0]
	v_pk_fma_f32 v[138:139], v[138:139], s[8:9], v[164:165] op_sel:[0,0,1] op_sel_hi:[1,0,0]
	v_pk_fma_f32 v[140:141], v[140:141], s[12:13], v[168:169] op_sel:[0,0,1] op_sel_hi:[1,0,0]
	v_pk_add_f32 v[146:147], v[142:143], v[156:157]
	v_pk_add_f32 v[150:151], v[144:145], v[134:135]
	v_pk_add_f32 v[134:135], v[144:145], v[134:135] neg_lo:[0,1] neg_hi:[0,1]
	v_pk_add_f32 v[144:145], v[148:149], v[162:163]
	v_pk_add_f32 v[160:161], v[148:149], v[162:163] op_sel:[1,1] op_sel_hi:[0,0] neg_lo:[0,1] neg_hi:[1,0]
	v_pk_add_f32 v[154:155], v[152:153], v[166:167]
	v_pk_add_f32 v[152:153], v[152:153], v[166:167] neg_lo:[0,1] neg_hi:[0,1]
	v_pk_fma_f32 v[116:117], v[112:113], v[66:67], v[116:117] op_sel_hi:[1,0,1]
	v_pk_add_f32 v[142:143], v[142:143], v[156:157] neg_lo:[0,1] neg_hi:[0,1]
	v_pk_add_f32 v[156:157], v[158:159], v[126:127]
	v_pk_add_f32 v[126:127], v[126:127], v[158:159] neg_lo:[0,1] neg_hi:[0,1]
	v_pk_mul_f32 v[158:159], v[134:135], s[16:17]
	v_pk_mul_f32 v[148:149], v[152:153], s[16:17]
	v_pk_add_f32 v[162:163], v[128:129], v[136:137]
	v_pk_add_f32 v[128:129], v[128:129], v[136:137] neg_lo:[0,1] neg_hi:[0,1]
	v_pk_add_f32 v[136:137], v[130:131], v[138:139]
	v_pk_add_f32 v[130:131], v[130:131], v[138:139] neg_lo:[0,1] neg_hi:[0,1]
	v_pk_add_f32 v[138:139], v[132:133], v[140:141]
	v_pk_add_f32 v[132:133], v[132:133], v[140:141] neg_lo:[0,1] neg_hi:[0,1]
	v_pk_add_f32 v[140:141], v[146:147], v[144:145]
	v_pk_add_f32 v[144:145], v[146:147], v[144:145] neg_lo:[0,1] neg_hi:[0,1]
	v_pk_add_f32 v[146:147], v[150:151], v[154:155]
	v_pk_add_f32 v[150:151], v[150:151], v[154:155] neg_lo:[0,1] neg_hi:[0,1]
	v_pk_add_f32 v[96:97], v[94:95], 0 neg_lo:[1,1] neg_hi:[1,1]
	v_pk_mul_f32 v[120:121], v[68:69], v[116:117] op_sel:[0,1] op_sel_hi:[1,0]
	v_pk_fma_f32 v[134:135], v[134:135], s[10:11], v[158:159] op_sel:[0,0,1] op_sel_hi:[1,0,0]
	v_pk_fma_f32 v[148:149], v[152:153], s[8:9], v[148:149] op_sel:[0,0,1] op_sel_hi:[1,0,0]
	v_pk_mul_f32 v[152:153], v[128:129], s[16:17]
	v_xor_b32_e32 v155, 0x80000000, v130
	v_mov_b32_e32 v154, v131
	v_pk_mul_f32 v[130:131], v[132:133], s[16:17]
	v_xor_b32_e32 v159, 0x80000000, v150
	v_mov_b32_e32 v158, v151
	v_pk_add_f32 v[150:151], v[142:143], v[160:161]
	v_pk_add_f32 v[142:143], v[142:143], v[160:161] neg_lo:[0,1] neg_hi:[0,1]
	v_pk_add_f32 v[160:161], v[156:157], v[136:137]
	v_pk_add_f32 v[136:137], v[156:157], v[136:137] neg_lo:[0,1] neg_hi:[0,1]
	v_pk_add_f32 v[156:157], v[162:163], v[138:139]
	v_pk_add_f32 v[138:139], v[162:163], v[138:139] neg_lo:[0,1] neg_hi:[0,1]
	v_mov_b32_e32 v0, v67
	v_pk_add_f32 v[72:73], v[70:71], 0 neg_lo:[1,1] neg_hi:[1,1]
	v_pk_add_f32 v[80:81], v[78:79], 0 neg_lo:[1,1] neg_hi:[1,1]
	v_mov_b32_e32 v96, v95
	v_pk_add_f32 v[100:101], v[98:99], 0 neg_lo:[1,1] neg_hi:[1,1]
	v_pk_add_f32 v[114:115], v[112:113], 0 neg_lo:[1,1] neg_hi:[1,1]
	v_pk_fma_f32 v[120:121], v[116:117], v[66:67], v[120:121] op_sel_hi:[1,0,1]
	v_pk_add_f32 v[162:163], v[140:141], v[146:147]
	v_pk_add_f32 v[140:141], v[140:141], v[146:147] neg_lo:[0,1] neg_hi:[0,1]
	v_pk_fma_f32 v[128:129], v[128:129], s[10:11], v[152:153] op_sel:[0,0,1] op_sel_hi:[1,0,0]
	v_pk_fma_f32 v[130:131], v[132:133], s[8:9], v[130:131] op_sel:[0,0,1] op_sel_hi:[1,0,0]
	v_pk_add_f32 v[132:133], v[134:135], v[148:149]
	v_pk_add_f32 v[134:135], v[134:135], v[148:149] neg_lo:[0,1] neg_hi:[0,1]
	v_xor_b32_e32 v147, 0x80000000, v138
	v_mov_b32_e32 v146, v139
	v_pk_add_f32 v[152:153], v[160:161], v[156:157]
	v_mov_b32_e32 v72, v71
	v_pk_add_f32 v[76:77], v[74:75], 0 neg_lo:[1,1] neg_hi:[1,1]
	v_mov_b32_e32 v80, v79
	v_pk_add_f32 v[84:85], v[82:83], 0 neg_lo:[1,1] neg_hi:[1,1]
	v_mov_b32_e32 v100, v99
	v_pk_add_f32 v[106:107], v[102:103], 0 neg_lo:[1,1] neg_hi:[1,1]
	v_mov_b32_e32 v114, v113
	v_pk_mul_f32 v[68:69], v[68:69], v[120:121] op_sel:[0,1] op_sel_hi:[1,0]
	v_pk_add_f32 v[138:139], v[126:127], v[154:155]
	v_pk_add_f32 v[126:127], v[126:127], v[154:155] neg_lo:[0,1] neg_hi:[0,1]
	v_pk_add_f32 v[148:149], v[144:145], v[158:159]
	v_pk_add_f32 v[144:145], v[144:145], v[158:159] neg_lo:[0,1] neg_hi:[0,1]
	v_pk_add_f32 v[154:155], v[160:161], v[156:157] neg_lo:[0,1] neg_hi:[0,1]
	v_pk_mul_f32 v[96:97], v[140:141], v[96:97] op_sel:[1,0] op_sel_hi:[0,1]
	v_xor_b32_e32 v157, 0x80000000, v134
	v_mov_b32_e32 v156, v135
	v_pk_add_f32 v[134:135], v[128:129], v[130:131]
	v_pk_add_f32 v[128:129], v[128:129], v[130:131] neg_lo:[0,1] neg_hi:[0,1]
	v_pk_add_f32 v[130:131], v[150:151], v[132:133]
	v_pk_add_f32 v[132:133], v[150:151], v[132:133] neg_lo:[0,1] neg_hi:[0,1]
	v_pk_add_f32 v[150:151], v[136:137], v[146:147]
	v_pk_add_f32 v[136:137], v[136:137], v[146:147] neg_lo:[0,1] neg_hi:[0,1]
	v_pk_mul_f32 v[146:147], v[0:1], v[152:153] op_sel:[0,1] op_sel_hi:[0,0] neg_hi:[1,0]
	v_mov_b32_e32 v76, v75
	v_mov_b32_e32 v84, v83
	v_pk_add_f32 v[88:89], v[86:87], 0 neg_lo:[1,1] neg_hi:[1,1]
	v_pk_add_f32 v[92:93], v[90:91], 0 neg_lo:[1,1] neg_hi:[1,1]
	v_mov_b32_e32 v106, v103
	v_pk_fma_f32 v[68:69], v[120:121], v[66:67], v[68:69] op_sel_hi:[1,0,1]
	v_pk_mul_f32 v[80:81], v[148:149], v[80:81] op_sel:[1,0] op_sel_hi:[0,1]
	v_pk_fma_f32 v[94:95], v[140:141], v[94:95], v[96:97] op_sel_hi:[1,0,1]
	v_pk_mul_f32 v[96:97], v[154:155], v[100:101] op_sel:[1,0] op_sel_hi:[0,1]
	v_pk_mul_f32 v[100:101], v[144:145], v[114:115] op_sel:[1,0] op_sel_hi:[0,1]
	v_xor_b32_e32 v115, 0x80000000, v128
	v_mov_b32_e32 v114, v129
	v_pk_add_f32 v[128:129], v[142:143], v[156:157]
	v_pk_add_f32 v[140:141], v[142:143], v[156:157] neg_lo:[0,1] neg_hi:[0,1]
	v_pk_add_f32 v[142:143], v[138:139], v[134:135]
	v_pk_fma_f32 v[66:67], v[152:153], v[66:67], v[146:147] op_sel_hi:[1,0,1]
	v_pk_mul_f32 v[72:73], v[130:131], v[72:73] op_sel:[1,0] op_sel_hi:[0,1]
	v_mov_b32_e32 v88, v87
	v_mov_b32_e32 v92, v91
	v_pk_add_f32 v[110:111], v[108:109], 0 neg_lo:[1,1] neg_hi:[1,1]
	v_pk_add_f32 v[118:119], v[116:117], 0 neg_lo:[1,1] neg_hi:[1,1]
	v_pk_add_f32 v[122:123], v[120:121], 0 neg_lo:[1,1] neg_hi:[1,1]
	v_pk_add_f32 v[124:125], v[68:69], 0 neg_lo:[1,1] neg_hi:[1,1]
	ds_write_b64 v171, v[162:163]
	v_pk_fma_f32 v[78:79], v[148:149], v[78:79], v[80:81] op_sel_hi:[1,0,1]
	v_pk_mul_f32 v[80:81], v[150:151], v[84:85] op_sel:[1,0] op_sel_hi:[0,1]
	v_pk_fma_f32 v[84:85], v[154:155], v[98:99], v[96:97] op_sel_hi:[1,0,1]
	v_pk_mul_f32 v[96:97], v[132:133], v[106:107] op_sel:[1,0] op_sel_hi:[0,1]
	v_pk_add_f32 v[106:107], v[126:127], v[114:115]
	ds_write_b64 v172, v[66:67] offset:8192
	v_pk_fma_f32 v[66:67], v[130:131], v[70:71], v[72:73] op_sel_hi:[1,0,1]
	v_pk_mul_f32 v[70:71], v[142:143], v[76:77] op_sel:[1,0] op_sel_hi:[0,1]
	v_mov_b32_e32 v110, v109
	v_mov_b32_e32 v118, v117
	v_mov_b32_e32 v122, v121
	v_mov_b32_e32 v124, v69
	v_pk_add_f32 v[134:135], v[138:139], v[134:135] neg_lo:[0,1] neg_hi:[0,1]
	v_pk_fma_f32 v[98:99], v[144:145], v[112:113], v[100:101] op_sel_hi:[1,0,1]
	v_pk_add_f32 v[112:113], v[126:127], v[114:115] neg_lo:[0,1] neg_hi:[0,1]
	v_pk_mul_f32 v[76:77], v[128:129], v[88:89] op_sel:[1,0] op_sel_hi:[0,1]
	ds_write_b64 v173, v[66:67] offset:16384
	v_pk_fma_f32 v[66:67], v[142:143], v[74:75], v[70:71] op_sel_hi:[1,0,1]
	v_pk_mul_f32 v[74:75], v[106:107], v[92:93] op_sel:[1,0] op_sel_hi:[0,1]
	s_mov_b64 s[48:49], 0
	s_and_b64 vcc, exec, vcc
	v_pk_mul_f32 v[100:101], v[136:137], v[118:119] op_sel:[1,0] op_sel_hi:[0,1]
	v_pk_fma_f32 v[72:73], v[150:151], v[82:83], v[80:81] op_sel_hi:[1,0,1]
	v_pk_fma_f32 v[80:81], v[132:133], v[102:103], v[96:97] op_sel_hi:[1,0,1]
	v_pk_mul_f32 v[82:83], v[134:135], v[110:111] op_sel:[1,0] op_sel_hi:[0,1]
	v_pk_mul_f32 v[96:97], v[140:141], v[122:123] op_sel:[1,0] op_sel_hi:[0,1]
	v_pk_fma_f32 v[70:71], v[128:129], v[86:87], v[76:77] op_sel_hi:[1,0,1]
	v_pk_mul_f32 v[86:87], v[112:113], v[124:125] op_sel:[1,0] op_sel_hi:[0,1]
	ds_write_b64 v174, v[66:67] offset:24576
	ds_write_b64 v175, v[78:79] offset:32768
	ds_write_b64 v176, v[72:73] offset:40960
	ds_write_b64 v177, v[70:71] offset:49152
	v_pk_fma_f32 v[66:67], v[106:107], v[90:91], v[74:75] op_sel_hi:[1,0,1]
	v_pk_fma_f32 v[88:89], v[136:137], v[116:117], v[100:101] op_sel_hi:[1,0,1]
	v_pk_fma_f32 v[76:77], v[134:135], v[108:109], v[82:83] op_sel_hi:[1,0,1]
	v_pk_fma_f32 v[82:83], v[140:141], v[120:121], v[96:97] op_sel_hi:[1,0,1]
	v_pk_fma_f32 v[68:69], v[112:113], v[68:69], v[86:87] op_sel_hi:[1,0,1]
	ds_write_b64 v178, v[66:67] offset:57344
	ds_write_b64 v179, v[94:95]
	ds_write_b64 v180, v[84:85]
	ds_write_b64 v181, v[80:81]
	ds_write_b64 v182, v[76:77]
	ds_write_b64 v183, v[98:99]
	ds_write_b64 v184, v[88:89]
	ds_write_b64 v185, v[82:83]
	ds_write_b64 v186, v[68:69]
	s_cbranch_vccz .LBB0_362
	s_waitcnt lgkmcnt(0)
	s_barrier
	v_mov_b32 v0, 0
	s_mov_b32 s5, s14
	v_add_u32_e32 v74, v0, v170
	v_lshlrev_b32_e32 v0, 5, v74
	v_and_b32_e32 v71, 0xfffffc00, v0
	v_or_b32_e32 v75, 0x80, v71
	v_and_b32_e32 v70, 31, v74
	v_ashrrev_i32_e32 v75, 2, v75
	v_lshlrev_b32_e32 v78, 3, v71
	v_lshlrev_b32_e32 v79, 3, v70
	v_add_u32_e32 v75, 0, v75
	v_add3_u32 v111, v75, v78, v79
	v_or_b32_e32 v75, 0xa0, v71
	v_ashrrev_i32_e32 v75, 2, v75
	v_add_u32_e32 v75, 0, v75
	v_add3_u32 v110, v75, v78, v79
	v_or_b32_e32 v75, 0xc0, v71
	v_ashrrev_i32_e32 v75, 2, v75
	v_add_u32_e32 v75, 0, v75
	v_add3_u32 v109, v75, v78, v79
	v_or_b32_e32 v75, 0xe0, v71
	v_ashrrev_i32_e32 v75, 2, v75
	v_add_u32_e32 v75, 0, v75
	v_add3_u32 v108, v75, v78, v79
	v_or_b32_e32 v75, 0x100, v71
	v_ashrrev_i32_e32 v75, 2, v75
	v_add_u32_e32 v75, 0, v75
	v_add3_u32 v107, v75, v78, v79
	v_or_b32_e32 v75, 0x120, v71
	v_ashrrev_i32_e32 v75, 2, v75
	v_add_u32_e32 v75, 0, v75
	v_add3_u32 v106, v75, v78, v79
	v_or_b32_e32 v75, 0x140, v71
	v_ashrrev_i32_e32 v75, 2, v75
	v_add_u32_e32 v75, 0, v75
	v_add3_u32 v105, v75, v78, v79
	v_or_b32_e32 v75, 0x160, v71
	v_ashrrev_i32_e32 v75, 2, v75
	v_add_u32_e32 v75, 0, v75
	v_add3_u32 v103, v75, v78, v79
	v_or_b32_e32 v75, 0x180, v71
	v_ashrrev_i32_e32 v75, 2, v75
	v_add_u32_e32 v75, 0, v75
	v_add3_u32 v102, v75, v78, v79
	v_or_b32_e32 v75, 0x1a0, v71
	v_ashrrev_i32_e32 v75, 2, v75
	v_add_u32_e32 v75, 0, v75
	v_add3_u32 v101, v75, v78, v79
	v_or_b32_e32 v75, 0x1c0, v71
	v_ashrrev_i32_e32 v75, 2, v75
	v_add_u32_e32 v75, 0, v75
	v_add3_u32 v100, v75, v78, v79
	v_or_b32_e32 v75, 0x1e0, v71
	v_ashrrev_i32_e32 v75, 2, v75
	v_add_u32_e32 v75, 0, v75
	v_add3_u32 v99, v75, v78, v79
	v_or_b32_e32 v75, 0x200, v71
	v_ashrrev_i32_e32 v75, 2, v75
	v_add_u32_e32 v75, 0, v75
	v_add3_u32 v98, v75, v78, v79
	v_or_b32_e32 v75, 0x220, v71
	v_ashrrev_i32_e32 v75, 2, v75
	v_add_u32_e32 v75, 0, v75
	v_add3_u32 v97, v75, v78, v79
	v_or_b32_e32 v75, 0x240, v71
	v_ashrrev_i32_e32 v75, 2, v75
	v_add_u32_e32 v75, 0, v75
	v_add3_u32 v96, v75, v78, v79
	v_or_b32_e32 v75, 0x260, v71
	v_ashrrev_i32_e32 v75, 2, v75
	v_add_u32_e32 v75, 0, v75
	v_add3_u32 v95, v75, v78, v79
	v_or_b32_e32 v75, 0x280, v71
	v_or_b32_e32 v67, 32, v71
	v_ashrrev_i32_e32 v75, 2, v75
	v_ashrrev_i32_e32 v67, 2, v67
	v_add_u32_e32 v75, 0, v75
	v_add_u32_e32 v67, 0, v67
	v_add3_u32 v94, v75, v78, v79
	v_or_b32_e32 v75, 0x2a0, v71
	v_add3_u32 v114, v67, v78, v79
	v_or_b32_e32 v67, 64, v71
	v_ashrrev_i32_e32 v75, 2, v75
	v_ashrrev_i32_e32 v67, 2, v67
	v_add_u32_e32 v75, 0, v75
	v_add_u32_e32 v67, 0, v67
	v_add3_u32 v93, v75, v78, v79
	v_or_b32_e32 v75, 0x2c0, v71
	v_ashrrev_i32_e32 v66, 2, v71
	v_add3_u32 v113, v67, v78, v79
	v_or_b32_e32 v67, 0x60, v71
	v_ashrrev_i32_e32 v75, 2, v75
	v_add_u32_e32 v66, 0, v66
	v_ashrrev_i32_e32 v67, 2, v67
	v_add_u32_e32 v75, 0, v75
	v_add3_u32 v66, v66, v78, v79
	v_add_u32_e32 v67, 0, v67
	v_add3_u32 v92, v75, v78, v79
	v_or_b32_e32 v75, 0x2e0, v71
	v_add3_u32 v112, v67, v78, v79
	ds_read_b64 v[66:67], v66
	ds_read_b64 v[68:69], v114 offset:256
	ds_read_b64 v[72:73], v113 offset:512
	ds_read_b64 v[76:77], v112 offset:768
	ds_read_b64 v[80:81], v111 offset:1024
	ds_read_b64 v[82:83], v110 offset:1280
	ds_read_b64 v[116:117], v109 offset:1536
	ds_read_b64 v[118:119], v108 offset:1792
	ds_read_b64 v[120:121], v107 offset:2048
	ds_read_b64 v[122:123], v106 offset:2304
	ds_read_b64 v[124:125], v105 offset:2560
	ds_read_b64 v[126:127], v103 offset:2816
	ds_read_b64 v[128:129], v102 offset:3072
	ds_read_b64 v[130:131], v101 offset:3328
	ds_read_b64 v[132:133], v100 offset:3584
	ds_read_b64 v[134:135], v99 offset:3840
	ds_read_b64 v[136:137], v98 offset:4096
	ds_read_b64 v[138:139], v97 offset:4352
	ds_read_b64 v[140:141], v96 offset:4608
	ds_read_b64 v[142:143], v95 offset:4864
	v_ashrrev_i32_e32 v75, 2, v75
	v_add_u32_e32 v75, 0, v75
	v_add3_u32 v91, v75, v78, v79
	v_or_b32_e32 v75, 0x300, v71
	v_ashrrev_i32_e32 v75, 2, v75
	s_waitcnt lgkmcnt(3)
	v_pk_add_f32 v[168:169], v[66:67], v[136:137]
	v_pk_add_f32 v[66:67], v[66:67], v[136:137] neg_lo:[0,1] neg_hi:[0,1]
	s_waitcnt lgkmcnt(2)
	v_pk_add_f32 v[136:137], v[68:69], v[138:139]
	v_pk_add_f32 v[68:69], v[68:69], v[138:139] neg_lo:[0,1] neg_hi:[0,1]
	v_add_u32_e32 v75, 0, v75
	v_pk_mul_f32 v[138:139], v[68:69], s[18:19]
	v_add3_u32 v90, v75, v78, v79
	v_or_b32_e32 v75, 0x320, v71
	v_pk_fma_f32 v[68:69], v[68:69], s[20:21], v[138:139] op_sel:[0,0,1] op_sel_hi:[1,0,0]
	s_waitcnt lgkmcnt(1)
	v_pk_add_f32 v[138:139], v[72:73], v[140:141]
	v_pk_add_f32 v[72:73], v[72:73], v[140:141] neg_lo:[0,1] neg_hi:[0,1]
	v_ashrrev_i32_e32 v75, 2, v75
	v_pk_mul_f32 v[140:141], v[72:73], s[4:5]
	ds_read_b64 v[144:145], v94 offset:5120
	ds_read_b64 v[146:147], v93 offset:5376
	ds_read_b64 v[148:149], v92 offset:5632
	ds_read_b64 v[150:151], v91 offset:5888
	v_add_u32_e32 v75, 0, v75
	v_pk_fma_f32 v[72:73], v[72:73], s[6:7], v[140:141] op_sel:[0,0,1] op_sel_hi:[1,0,0]
	s_waitcnt lgkmcnt(4)
	v_pk_add_f32 v[140:141], v[76:77], v[142:143]
	v_pk_add_f32 v[76:77], v[76:77], v[142:143] neg_lo:[0,1] neg_hi:[0,1]
	v_add3_u32 v89, v75, v78, v79
	v_or_b32_e32 v75, 0x340, v71
	v_pk_mul_f32 v[142:143], v[76:77], s[22:23]
	v_ashrrev_i32_e32 v75, 2, v75
	v_pk_fma_f32 v[76:77], v[76:77], s[24:25], v[142:143] op_sel:[0,0,1] op_sel_hi:[1,0,0]
	s_waitcnt lgkmcnt(3)
	v_pk_add_f32 v[142:143], v[80:81], v[144:145]
	v_pk_add_f32 v[80:81], v[80:81], v[144:145] neg_lo:[0,1] neg_hi:[0,1]
	s_mov_b32 s9, s10
	v_add_u32_e32 v75, 0, v75
	v_pk_mul_f32 v[144:145], v[80:81], s[8:9]
	v_add3_u32 v88, v75, v78, v79
	v_or_b32_e32 v75, 0x360, v71
	v_pk_fma_f32 v[80:81], v[80:81], s[10:11], v[144:145] op_sel:[0,0,1] op_sel_hi:[1,0,0]
	s_waitcnt lgkmcnt(2)
	v_pk_add_f32 v[144:145], v[82:83], v[146:147]
	v_pk_add_f32 v[82:83], v[82:83], v[146:147] neg_lo:[0,1] neg_hi:[0,1]
	s_mov_b32 s27, s24
	v_ashrrev_i32_e32 v75, 2, v75
	v_pk_mul_f32 v[146:147], v[82:83], s[26:27]
	s_mov_b32 s0, s23
	v_add_u32_e32 v75, 0, v75
	v_pk_fma_f32 v[82:83], v[82:83], s[0:1], v[146:147] op_sel:[0,0,1] op_sel_hi:[1,0,0]
	s_waitcnt lgkmcnt(1)
	v_pk_add_f32 v[146:147], v[116:117], v[148:149]
	v_pk_add_f32 v[116:117], v[116:117], v[148:149] neg_lo:[0,1] neg_hi:[0,1]
	s_mov_b32 s13, s6
	v_add3_u32 v87, v75, v78, v79
	v_or_b32_e32 v75, 0x380, v71
	v_pk_mul_f32 v[148:149], v[116:117], s[12:13]
	ds_read_b64 v[152:153], v90 offset:6144
	ds_read_b64 v[154:155], v89 offset:6400
	ds_read_b64 v[156:157], v88 offset:6656
	ds_read_b64 v[158:159], v87 offset:6912
	v_ashrrev_i32_e32 v75, 2, v75
	v_pk_fma_f32 v[116:117], v[116:117], s[14:15], v[148:149] op_sel:[0,0,1] op_sel_hi:[1,0,0]
	s_waitcnt lgkmcnt(4)
	v_pk_add_f32 v[148:149], v[118:119], v[150:151]
	v_pk_add_f32 v[118:119], v[118:119], v[150:151] neg_lo:[0,1] neg_hi:[0,1]
	s_mov_b32 s35, s20
	v_add_u32_e32 v75, 0, v75
	v_pk_mul_f32 v[150:151], v[118:119], s[34:35]
	s_mov_b32 s48, s19
	v_add3_u32 v86, v75, v78, v79
	v_or_b32_e32 v75, 0x3a0, v71
	v_or_b32_e32 v71, 0x3c0, v71
	v_pk_fma_f32 v[118:119], v[118:119], s[48:49], v[150:151] op_sel:[0,0,1] op_sel_hi:[1,0,0]
	s_waitcnt lgkmcnt(3)
	v_pk_add_f32 v[150:151], v[120:121], v[152:153]
	v_pk_add_f32 v[152:153], v[120:121], v[152:153] op_sel:[1,1] op_sel_hi:[0,0] neg_lo:[0,1] neg_hi:[1,0]
	v_ashrrev_i32_e32 v71, 2, v71
	s_waitcnt lgkmcnt(2)
	v_pk_add_f32 v[120:121], v[122:123], v[154:155]
	v_pk_add_f32 v[122:123], v[122:123], v[154:155] neg_lo:[0,1] neg_hi:[0,1]
	v_add_u32_e32 v71, 0, v71
	v_or_b32_e32 v0, 0x3e0, v0
	v_pk_mul_f32 v[154:155], v[122:123], s[34:35]
	v_ashrrev_i32_e32 v75, 2, v75
	v_add3_u32 v84, v71, v78, v79
	v_ashrrev_i32_e32 v71, 2, v0
	v_pk_fma_f32 v[122:123], v[122:123], s[18:19], v[154:155] op_sel:[0,0,1] op_sel_hi:[1,0,0]
	s_waitcnt lgkmcnt(1)
	v_pk_add_f32 v[154:155], v[124:125], v[156:157]
	v_pk_add_f32 v[124:125], v[124:125], v[156:157] neg_lo:[0,1] neg_hi:[0,1]
	v_add_u32_e32 v75, 0, v75
	v_add_u32_e32 v71, 0, v71
	v_lshlrev_b32_e32 v0, 3, v0
	v_pk_mul_f32 v[156:157], v[124:125], s[12:13]
	v_add3_u32 v85, v75, v78, v79
	v_add3_u32 v0, v71, v0, v79
	ds_read_b64 v[160:161], v86 offset:7168
	ds_read_b64 v[162:163], v85 offset:7424
	ds_read_b64 v[164:165], v84 offset:7680
	ds_read_b64 v[166:167], v0
	v_pk_fma_f32 v[124:125], v[124:125], s[4:5], v[156:157] op_sel:[0,0,1] op_sel_hi:[1,0,0]
	s_waitcnt lgkmcnt(4)
	v_pk_add_f32 v[156:157], v[126:127], v[158:159]
	v_pk_add_f32 v[126:127], v[126:127], v[158:159] neg_lo:[0,1] neg_hi:[0,1]
	v_lshlrev_b32_e32 v70, 4, v70
	v_pk_mul_f32 v[158:159], v[126:127], s[26:27]
	v_cvt_f32_u32_e32 v75, v70
	v_pk_fma_f32 v[126:127], v[126:127], s[22:23], v[158:159] op_sel:[0,0,1] op_sel_hi:[1,0,0]
	s_waitcnt lgkmcnt(3)
	v_pk_add_f32 v[158:159], v[128:129], v[160:161]
	v_pk_add_f32 v[128:129], v[128:129], v[160:161] neg_lo:[0,1] neg_hi:[0,1]
	v_and_b32_e32 v74, 0x1fffffe0, v74
	v_pk_mul_f32 v[160:161], v[128:129], s[8:9]
	v_mul_f32_e32 v115, 0x38800000, v75
	v_pk_fma_f32 v[128:129], v[128:129], s[8:9], v[160:161] op_sel:[0,0,1] op_sel_hi:[1,0,0]
	s_waitcnt lgkmcnt(2)
	v_pk_add_f32 v[160:161], v[130:131], v[162:163]
	v_pk_add_f32 v[130:131], v[130:131], v[162:163] neg_lo:[0,1] neg_hi:[0,1]
	v_lshl_add_u32 v74, v74, 3, 0
	v_pk_mul_f32 v[162:163], v[130:131], s[22:23]
	v_sin_f32_e32 v75, v115
	v_pk_fma_f32 v[130:131], v[130:131], s[26:27], v[162:163] op_sel:[0,0,1] op_sel_hi:[1,0,0]
	s_waitcnt lgkmcnt(1)
	v_pk_add_f32 v[162:163], v[132:133], v[164:165]
	v_pk_add_f32 v[132:133], v[132:133], v[164:165] neg_lo:[0,1] neg_hi:[0,1]
	v_add3_u32 v74, v74, v78, v79
	v_pk_mul_f32 v[164:165], v[132:133], s[4:5]
	v_xor_b32_e32 v78, 0x80000000, v75
	v_pk_fma_f32 v[132:133], v[132:133], s[12:13], v[164:165] op_sel:[0,0,1] op_sel_hi:[1,0,0]
	s_waitcnt lgkmcnt(0)
	v_pk_add_f32 v[164:165], v[134:135], v[166:167]
	v_pk_add_f32 v[134:135], v[134:135], v[166:167] neg_lo:[0,1] neg_hi:[0,1]
	v_mov_b32_e32 v79, v75
	v_pk_mul_f32 v[166:167], v[134:135], s[18:19]
	s_mov_b32 s50, s19
	v_pk_fma_f32 v[134:135], v[134:135], s[34:35], v[166:167] op_sel:[0,0,1] op_sel_hi:[1,0,0]
	v_pk_add_f32 v[166:167], v[168:169], v[150:151]
	v_pk_add_f32 v[150:151], v[168:169], v[150:151] neg_lo:[0,1] neg_hi:[0,1]
	v_pk_add_f32 v[168:169], v[136:137], v[120:121]
	v_pk_add_f32 v[120:121], v[136:137], v[120:121] neg_lo:[0,1] neg_hi:[0,1]
	s_mov_b32 s51, s18
	v_pk_mul_f32 v[136:137], v[120:121], s[4:5]
	s_mov_b32 s52, s23
	v_pk_fma_f32 v[120:121], v[120:121], s[6:7], v[136:137] op_sel:[0,0,1] op_sel_hi:[1,0,0]
	v_pk_add_f32 v[136:137], v[138:139], v[154:155]
	v_pk_add_f32 v[138:139], v[138:139], v[154:155] neg_lo:[0,1] neg_hi:[0,1]
	s_mov_b32 s53, s22
	v_pk_mul_f32 v[154:155], v[138:139], s[8:9]
	s_nop 0
	v_pk_fma_f32 v[138:139], v[138:139], s[10:11], v[154:155] op_sel:[0,0,1] op_sel_hi:[1,0,0]
	v_pk_add_f32 v[154:155], v[140:141], v[156:157]
	v_pk_add_f32 v[140:141], v[140:141], v[156:157] neg_lo:[0,1] neg_hi:[0,1]
	s_nop 0
	v_pk_mul_f32 v[156:157], v[140:141], s[12:13]
	s_nop 0
	v_pk_fma_f32 v[140:141], v[140:141], s[14:15], v[156:157] op_sel:[0,0,1] op_sel_hi:[1,0,0]
	v_pk_add_f32 v[156:157], v[142:143], v[158:159]
	v_pk_add_f32 v[158:159], v[142:143], v[158:159] op_sel:[1,1] op_sel_hi:[0,0] neg_lo:[0,1] neg_hi:[1,0]
	s_nop 0
	v_pk_add_f32 v[142:143], v[144:145], v[160:161]
	v_pk_add_f32 v[144:145], v[144:145], v[160:161] neg_lo:[0,1] neg_hi:[0,1]
	s_nop 0
	v_pk_mul_f32 v[160:161], v[144:145], s[12:13]
	s_nop 0
	v_pk_fma_f32 v[144:145], v[144:145], s[4:5], v[160:161] op_sel:[0,0,1] op_sel_hi:[1,0,0]
	v_pk_add_f32 v[160:161], v[146:147], v[162:163]
	v_pk_add_f32 v[146:147], v[146:147], v[162:163] neg_lo:[0,1] neg_hi:[0,1]
	s_nop 0
	v_pk_mul_f32 v[162:163], v[146:147], s[8:9]
	s_nop 0
	v_pk_fma_f32 v[146:147], v[146:147], s[8:9], v[162:163] op_sel:[0,0,1] op_sel_hi:[1,0,0]
	v_pk_add_f32 v[162:163], v[148:149], v[164:165]
	v_pk_add_f32 v[148:149], v[148:149], v[164:165] neg_lo:[0,1] neg_hi:[0,1]
	s_nop 0
	v_pk_mul_f32 v[164:165], v[148:149], s[4:5]
	s_nop 0
	v_pk_fma_f32 v[148:149], v[148:149], s[12:13], v[164:165] op_sel:[0,0,1] op_sel_hi:[1,0,0]
	v_pk_add_f32 v[164:165], v[66:67], v[152:153]
	v_pk_add_f32 v[66:67], v[66:67], v[152:153] neg_lo:[0,1] neg_hi:[0,1]
	v_pk_add_f32 v[152:153], v[68:69], v[122:123]
	v_pk_add_f32 v[68:69], v[68:69], v[122:123] neg_lo:[0,1] neg_hi:[0,1]
	s_nop 0
	v_pk_mul_f32 v[122:123], v[68:69], s[4:5]
	s_nop 0
	v_pk_fma_f32 v[68:69], v[68:69], s[6:7], v[122:123] op_sel:[0,0,1] op_sel_hi:[1,0,0]
	v_pk_add_f32 v[122:123], v[72:73], v[124:125]
	v_pk_add_f32 v[72:73], v[72:73], v[124:125] neg_lo:[0,1] neg_hi:[0,1]
	s_nop 0
	v_pk_mul_f32 v[124:125], v[72:73], s[8:9]
	s_nop 0
	v_pk_fma_f32 v[72:73], v[72:73], s[10:11], v[124:125] op_sel:[0,0,1] op_sel_hi:[1,0,0]
	v_pk_add_f32 v[124:125], v[76:77], v[126:127]
	v_pk_add_f32 v[76:77], v[76:77], v[126:127] neg_lo:[0,1] neg_hi:[0,1]
	s_nop 0
	v_pk_mul_f32 v[126:127], v[76:77], s[12:13]
	s_nop 0
	v_pk_fma_f32 v[76:77], v[76:77], s[14:15], v[126:127] op_sel:[0,0,1] op_sel_hi:[1,0,0]
	v_pk_add_f32 v[126:127], v[80:81], v[128:129]
	v_pk_add_f32 v[128:129], v[80:81], v[128:129] op_sel:[1,1] op_sel_hi:[0,0] neg_lo:[0,1] neg_hi:[1,0]
	s_nop 0
	v_pk_add_f32 v[80:81], v[82:83], v[130:131]
	v_pk_add_f32 v[82:83], v[82:83], v[130:131] neg_lo:[0,1] neg_hi:[0,1]
	s_nop 0
	v_pk_mul_f32 v[130:131], v[82:83], s[12:13]
	s_nop 0
	v_pk_fma_f32 v[82:83], v[82:83], s[4:5], v[130:131] op_sel:[0,0,1] op_sel_hi:[1,0,0]
	v_pk_add_f32 v[130:131], v[116:117], v[132:133]
	v_pk_add_f32 v[116:117], v[116:117], v[132:133] neg_lo:[0,1] neg_hi:[0,1]
	s_nop 0
	v_pk_mul_f32 v[132:133], v[116:117], s[8:9]
	s_nop 0
	v_pk_fma_f32 v[116:117], v[116:117], s[8:9], v[132:133] op_sel:[0,0,1] op_sel_hi:[1,0,0]
	v_pk_add_f32 v[132:133], v[118:119], v[134:135]
	v_pk_add_f32 v[118:119], v[118:119], v[134:135] neg_lo:[0,1] neg_hi:[0,1]
	s_nop 0
	v_pk_mul_f32 v[134:135], v[118:119], s[4:5]
	s_nop 0
	v_pk_fma_f32 v[118:119], v[118:119], s[12:13], v[134:135] op_sel:[0,0,1] op_sel_hi:[1,0,0]
	v_pk_add_f32 v[134:135], v[166:167], v[156:157]
	v_pk_add_f32 v[156:157], v[166:167], v[156:157] neg_lo:[0,1] neg_hi:[0,1]
	v_pk_add_f32 v[166:167], v[168:169], v[142:143]
	v_pk_add_f32 v[142:143], v[168:169], v[142:143] neg_lo:[0,1] neg_hi:[0,1]
	s_nop 0
	v_pk_mul_f32 v[168:169], v[142:143], s[8:9]
	s_nop 0
	v_pk_fma_f32 v[142:143], v[142:143], s[10:11], v[168:169] op_sel:[0,0,1] op_sel_hi:[1,0,0]
	v_pk_add_f32 v[168:169], v[136:137], v[160:161]
	v_pk_add_f32 v[160:161], v[136:137], v[160:161] op_sel:[1,1] op_sel_hi:[0,0] neg_lo:[0,1] neg_hi:[1,0]
	s_nop 0
	v_pk_add_f32 v[136:137], v[154:155], v[162:163]
	v_pk_add_f32 v[154:155], v[154:155], v[162:163] neg_lo:[0,1] neg_hi:[0,1]
	s_nop 0
	v_pk_mul_f32 v[162:163], v[154:155], s[8:9]
	s_nop 0
	v_pk_fma_f32 v[154:155], v[154:155], s[8:9], v[162:163] op_sel:[0,0,1] op_sel_hi:[1,0,0]
	v_pk_add_f32 v[162:163], v[150:151], v[158:159]
	v_pk_add_f32 v[150:151], v[150:151], v[158:159] neg_lo:[0,1] neg_hi:[0,1]
	v_pk_add_f32 v[158:159], v[120:121], v[144:145]
	v_pk_add_f32 v[120:121], v[120:121], v[144:145] neg_lo:[0,1] neg_hi:[0,1]
	s_nop 0
	v_pk_mul_f32 v[144:145], v[120:121], s[8:9]
	s_nop 0
	v_pk_fma_f32 v[120:121], v[120:121], s[10:11], v[144:145] op_sel:[0,0,1] op_sel_hi:[1,0,0]
	v_pk_add_f32 v[144:145], v[138:139], v[146:147]
	v_pk_add_f32 v[146:147], v[138:139], v[146:147] op_sel:[1,1] op_sel_hi:[0,0] neg_lo:[0,1] neg_hi:[1,0]
	s_nop 0
	v_pk_add_f32 v[138:139], v[140:141], v[148:149]
	v_pk_add_f32 v[140:141], v[140:141], v[148:149] neg_lo:[0,1] neg_hi:[0,1]
	s_nop 0
	v_pk_mul_f32 v[148:149], v[140:141], s[8:9]
	s_nop 0
	v_pk_fma_f32 v[140:141], v[140:141], s[8:9], v[148:149] op_sel:[0,0,1] op_sel_hi:[1,0,0]
	v_pk_add_f32 v[148:149], v[164:165], v[126:127]
	v_pk_add_f32 v[126:127], v[164:165], v[126:127] neg_lo:[0,1] neg_hi:[0,1]
	v_pk_add_f32 v[164:165], v[152:153], v[80:81]
	v_pk_add_f32 v[80:81], v[152:153], v[80:81] neg_lo:[0,1] neg_hi:[0,1]
	s_nop 0
	v_pk_mul_f32 v[152:153], v[80:81], s[8:9]
	s_nop 0
	v_pk_fma_f32 v[80:81], v[80:81], s[10:11], v[152:153] op_sel:[0,0,1] op_sel_hi:[1,0,0]
	v_pk_add_f32 v[152:153], v[122:123], v[130:131]
	v_pk_add_f32 v[130:131], v[122:123], v[130:131] op_sel:[1,1] op_sel_hi:[0,0] neg_lo:[0,1] neg_hi:[1,0]
	s_nop 0
	v_pk_add_f32 v[122:123], v[124:125], v[132:133]
	v_pk_add_f32 v[124:125], v[124:125], v[132:133] neg_lo:[0,1] neg_hi:[0,1]
	s_nop 0
	v_pk_mul_f32 v[132:133], v[124:125], s[8:9]
	s_nop 0
	v_pk_fma_f32 v[124:125], v[124:125], s[8:9], v[132:133] op_sel:[0,0,1] op_sel_hi:[1,0,0]
	v_pk_add_f32 v[132:133], v[66:67], v[128:129]
	v_pk_add_f32 v[66:67], v[66:67], v[128:129] neg_lo:[0,1] neg_hi:[0,1]
	v_pk_add_f32 v[128:129], v[68:69], v[82:83]
	v_pk_add_f32 v[68:69], v[68:69], v[82:83] neg_lo:[0,1] neg_hi:[0,1]
	s_nop 0
	v_pk_mul_f32 v[82:83], v[68:69], s[8:9]
	s_nop 0
	v_pk_fma_f32 v[68:69], v[68:69], s[10:11], v[82:83] op_sel:[0,0,1] op_sel_hi:[1,0,0]
	v_pk_add_f32 v[82:83], v[72:73], v[116:117]
	v_pk_add_f32 v[116:117], v[72:73], v[116:117] op_sel:[1,1] op_sel_hi:[0,0] neg_lo:[0,1] neg_hi:[1,0]
	s_nop 0
	v_pk_add_f32 v[72:73], v[76:77], v[118:119]
	v_pk_add_f32 v[76:77], v[76:77], v[118:119] neg_lo:[0,1] neg_hi:[0,1]
	v_pk_add_f32 v[174:175], v[66:67], v[116:117]
	v_pk_mul_f32 v[118:119], v[76:77], s[8:9]
	v_pk_add_f32 v[116:117], v[66:67], v[116:117] neg_lo:[0,1] neg_hi:[0,1]
	v_pk_fma_f32 v[76:77], v[76:77], s[8:9], v[118:119] op_sel:[0,0,1] op_sel_hi:[1,0,0]
	v_pk_add_f32 v[118:119], v[134:135], v[168:169]
	v_pk_add_f32 v[134:135], v[134:135], v[168:169] neg_lo:[0,1] neg_hi:[0,1]
	v_pk_add_f32 v[168:169], v[166:167], v[136:137]
	v_pk_add_f32 v[166:167], v[166:167], v[136:137] op_sel:[1,1] op_sel_hi:[0,0] neg_lo:[0,1] neg_hi:[1,0]
	v_pk_add_f32 v[180:181], v[118:119], v[168:169]
	v_pk_add_f32 v[136:137], v[156:157], v[160:161]
	v_pk_add_f32 v[156:157], v[156:157], v[160:161] neg_lo:[0,1] neg_hi:[0,1]
	v_pk_add_f32 v[160:161], v[142:143], v[154:155]
	v_pk_add_f32 v[154:155], v[142:143], v[154:155] op_sel:[1,1] op_sel_hi:[0,0] neg_lo:[0,1] neg_hi:[1,0]
	v_pk_add_f32 v[66:67], v[68:69], v[76:77] neg_lo:[0,1] neg_hi:[0,1]
	v_pk_add_f32 v[142:143], v[162:163], v[144:145]
	v_pk_add_f32 v[144:145], v[162:163], v[144:145] neg_lo:[0,1] neg_hi:[0,1]
	v_pk_add_f32 v[162:163], v[158:159], v[138:139]
	v_pk_add_f32 v[158:159], v[158:159], v[138:139] op_sel:[1,1] op_sel_hi:[0,0] neg_lo:[0,1] neg_hi:[1,0]
	ds_write_b64 v74, v[180:181]
	v_pk_add_f32 v[138:139], v[150:151], v[146:147]
	v_pk_add_f32 v[146:147], v[150:151], v[146:147] neg_lo:[0,1] neg_hi:[0,1]
	v_pk_add_f32 v[150:151], v[120:121], v[140:141]
	v_pk_add_f32 v[140:141], v[120:121], v[140:141] op_sel:[1,1] op_sel_hi:[0,0] neg_lo:[0,1] neg_hi:[1,0]
	v_cos_f32_e32 v74, v115
	v_pk_add_f32 v[120:121], v[148:149], v[152:153]
	v_pk_add_f32 v[148:149], v[148:149], v[152:153] neg_lo:[0,1] neg_hi:[0,1]
	v_pk_add_f32 v[152:153], v[164:165], v[122:123]
	v_pk_add_f32 v[164:165], v[164:165], v[122:123] op_sel:[1,1] op_sel_hi:[0,0] neg_lo:[0,1] neg_hi:[1,0]
	v_xor_b32_e32 v179, 0x80000000, v66
	v_pk_add_f32 v[122:123], v[126:127], v[130:131]
	v_pk_add_f32 v[126:127], v[126:127], v[130:131] neg_lo:[0,1] neg_hi:[0,1]
	v_pk_add_f32 v[130:131], v[80:81], v[124:125]
	v_pk_add_f32 v[124:125], v[80:81], v[124:125] op_sel:[1,1] op_sel_hi:[0,0] neg_lo:[0,1] neg_hi:[1,0]
	v_mov_b32_e32 v178, v67
	v_pk_add_f32 v[80:81], v[132:133], v[82:83]
	v_pk_add_f32 v[132:133], v[132:133], v[82:83] neg_lo:[0,1] neg_hi:[0,1]
	v_pk_add_f32 v[176:177], v[68:69], v[76:77]
	v_pk_add_f32 v[118:119], v[118:119], v[168:169] neg_lo:[0,1] neg_hi:[0,1]
	v_pk_add_f32 v[168:169], v[134:135], v[166:167]
	v_pk_add_f32 v[82:83], v[134:135], v[166:167] neg_lo:[0,1] neg_hi:[0,1]
	v_pk_add_f32 v[134:135], v[136:137], v[160:161]
	v_pk_add_f32 v[136:137], v[136:137], v[160:161] neg_lo:[0,1] neg_hi:[0,1]
	v_pk_add_f32 v[160:161], v[156:157], v[154:155]
	v_pk_add_f32 v[68:69], v[156:157], v[154:155] neg_lo:[0,1] neg_hi:[0,1]
	v_pk_add_f32 v[154:155], v[142:143], v[162:163]
	v_pk_add_f32 v[142:143], v[142:143], v[162:163] neg_lo:[0,1] neg_hi:[0,1]
	v_pk_add_f32 v[156:157], v[144:145], v[158:159]
	v_pk_add_f32 v[76:77], v[144:145], v[158:159] neg_lo:[0,1] neg_hi:[0,1]
	v_pk_add_f32 v[144:145], v[138:139], v[150:151]
	v_pk_add_f32 v[138:139], v[138:139], v[150:151] neg_lo:[0,1] neg_hi:[0,1]
	v_pk_add_f32 v[150:151], v[146:147], v[140:141]
	v_pk_add_f32 v[66:67], v[146:147], v[140:141] neg_lo:[0,1] neg_hi:[0,1]
	v_pk_add_f32 v[140:141], v[120:121], v[152:153]
	v_pk_add_f32 v[162:163], v[116:117], v[178:179]
	v_pk_add_f32 v[70:71], v[116:117], v[178:179] neg_lo:[0,1] neg_hi:[0,1]
	v_mov_b32_e32 v116, v75
	v_pk_mul_f32 v[116:117], v[116:117], v[140:141] op_sel:[0,1] op_sel_hi:[0,0] neg_hi:[1,0]
	v_pk_fma_f32 v[116:117], v[140:141], v[74:75], v[116:117] op_sel_hi:[1,0,1]
	ds_write_b64 v114, v[116:117] offset:256
	v_pk_mul_f32 v[114:115], v[78:79], v[74:75] op_sel:[0,1] op_sel_hi:[1,0]
	v_pk_add_f32 v[172:173], v[128:129], v[72:73]
	v_pk_fma_f32 v[114:115], v[74:75], v[74:75], v[114:115] op_sel_hi:[1,0,1]
	v_pk_add_f32 v[128:129], v[128:129], v[72:73] op_sel:[1,1] op_sel_hi:[0,0] neg_lo:[0,1] neg_hi:[1,0]
	v_pk_add_f32 v[116:117], v[114:115], 0 neg_lo:[1,1] neg_hi:[1,1]
	v_mov_b32_e32 v116, v115
	v_pk_mul_f32 v[116:117], v[116:117], v[154:155] op_sel:[0,1] op_sel_hi:[1,0]
	v_pk_fma_f32 v[116:117], v[154:155], v[114:115], v[116:117] op_sel_hi:[1,0,1]
	ds_write_b64 v113, v[116:117] offset:512
	v_pk_mul_f32 v[116:117], v[78:79], v[114:115] op_sel:[0,1] op_sel_hi:[1,0]
	v_pk_add_f32 v[120:121], v[120:121], v[152:153] neg_lo:[0,1] neg_hi:[0,1]
	v_pk_fma_f32 v[114:115], v[114:115], v[74:75], v[116:117] op_sel_hi:[1,0,1]
	v_pk_add_f32 v[152:153], v[122:123], v[130:131]
	v_pk_add_f32 v[116:117], v[114:115], 0 neg_lo:[1,1] neg_hi:[1,1]
	v_pk_add_f32 v[122:123], v[122:123], v[130:131] neg_lo:[0,1] neg_hi:[0,1]
	v_pk_add_f32 v[130:131], v[126:127], v[124:125]
	v_pk_add_f32 v[72:73], v[126:127], v[124:125] neg_lo:[0,1] neg_hi:[0,1]
	v_pk_add_f32 v[124:125], v[80:81], v[172:173]
	v_mov_b32_e32 v116, v115
	v_pk_mul_f32 v[116:117], v[116:117], v[124:125] op_sel:[0,1] op_sel_hi:[1,0]
	v_pk_add_f32 v[126:127], v[80:81], v[172:173] neg_lo:[0,1] neg_hi:[0,1]
	v_pk_fma_f32 v[116:117], v[124:125], v[114:115], v[116:117] op_sel_hi:[1,0,1]
	ds_write_b64 v112, v[116:117] offset:768
	v_pk_mul_f32 v[112:113], v[78:79], v[114:115] op_sel:[0,1] op_sel_hi:[1,0]
	v_pk_add_f32 v[158:159], v[132:133], v[128:129]
	v_pk_fma_f32 v[112:113], v[114:115], v[74:75], v[112:113] op_sel_hi:[1,0,1]
	v_pk_add_f32 v[80:81], v[132:133], v[128:129] neg_lo:[0,1] neg_hi:[0,1]
	v_pk_add_f32 v[114:115], v[112:113], 0 neg_lo:[1,1] neg_hi:[1,1]
	v_pk_add_f32 v[128:129], v[174:175], v[176:177]
	v_mov_b32_e32 v114, v113
	v_pk_mul_f32 v[114:115], v[114:115], v[134:135] op_sel:[0,1] op_sel_hi:[1,0]
	v_pk_add_f32 v[146:147], v[148:149], v[164:165]
	v_pk_fma_f32 v[114:115], v[134:135], v[112:113], v[114:115] op_sel_hi:[1,0,1]
	ds_write_b64 v111, v[114:115] offset:1024
	v_pk_mul_f32 v[114:115], v[78:79], v[112:113] op_sel:[0,1] op_sel_hi:[1,0]
	v_pk_add_f32 v[132:133], v[174:175], v[176:177] neg_lo:[0,1] neg_hi:[0,1]
	v_pk_fma_f32 v[112:113], v[112:113], v[74:75], v[114:115] op_sel_hi:[1,0,1]
	v_pk_add_f32 v[148:149], v[148:149], v[164:165] neg_lo:[0,1] neg_hi:[0,1]
	v_pk_add_f32 v[114:115], v[112:113], 0 neg_lo:[1,1] neg_hi:[1,1]
	s_nop 0
	v_mov_b32_e32 v114, v113
	v_pk_mul_f32 v[114:115], v[114:115], v[152:153] op_sel:[0,1] op_sel_hi:[1,0]
	s_nop 0
	v_pk_fma_f32 v[114:115], v[152:153], v[112:113], v[114:115] op_sel_hi:[1,0,1]
	ds_write_b64 v110, v[114:115] offset:1280
	v_pk_mul_f32 v[110:111], v[78:79], v[112:113] op_sel:[0,1] op_sel_hi:[1,0]
	s_nop 0
	v_pk_fma_f32 v[110:111], v[112:113], v[74:75], v[110:111] op_sel_hi:[1,0,1]
	s_nop 0
	v_pk_add_f32 v[112:113], v[110:111], 0 neg_lo:[1,1] neg_hi:[1,1]
	s_nop 0
	v_mov_b32_e32 v112, v111
	v_pk_mul_f32 v[112:113], v[112:113], v[144:145] op_sel:[0,1] op_sel_hi:[1,0]
	s_nop 0
	v_pk_fma_f32 v[112:113], v[144:145], v[110:111], v[112:113] op_sel_hi:[1,0,1]
	ds_write_b64 v109, v[112:113] offset:1536
	v_pk_mul_f32 v[112:113], v[78:79], v[110:111] op_sel:[0,1] op_sel_hi:[1,0]
	s_nop 0
	v_pk_fma_f32 v[110:111], v[110:111], v[74:75], v[112:113] op_sel_hi:[1,0,1]
	s_nop 0
	v_pk_add_f32 v[112:113], v[110:111], 0 neg_lo:[1,1] neg_hi:[1,1]
	s_nop 0
	v_mov_b32_e32 v112, v111
	v_pk_mul_f32 v[112:113], v[112:113], v[128:129] op_sel:[0,1] op_sel_hi:[1,0]
	s_nop 0
	v_pk_fma_f32 v[112:113], v[128:129], v[110:111], v[112:113] op_sel_hi:[1,0,1]
	ds_write_b64 v108, v[112:113] offset:1792
	v_pk_mul_f32 v[108:109], v[78:79], v[110:111] op_sel:[0,1] op_sel_hi:[1,0]
	s_nop 0
	v_pk_fma_f32 v[108:109], v[110:111], v[74:75], v[108:109] op_sel_hi:[1,0,1]
	s_nop 0
	v_pk_add_f32 v[110:111], v[108:109], 0 neg_lo:[1,1] neg_hi:[1,1]
	s_nop 0
	v_mov_b32_e32 v110, v109
	v_pk_mul_f32 v[110:111], v[110:111], v[168:169] op_sel:[0,1] op_sel_hi:[1,0]
	s_nop 0
	v_pk_fma_f32 v[110:111], v[168:169], v[108:109], v[110:111] op_sel_hi:[1,0,1]
	ds_write_b64 v107, v[110:111] offset:2048
	v_pk_mul_f32 v[110:111], v[78:79], v[108:109] op_sel:[0,1] op_sel_hi:[1,0]
	s_nop 0
	v_pk_fma_f32 v[108:109], v[108:109], v[74:75], v[110:111] op_sel_hi:[1,0,1]
	s_nop 0
	v_pk_add_f32 v[110:111], v[108:109], 0 neg_lo:[1,1] neg_hi:[1,1]
	s_nop 0
	v_mov_b32_e32 v110, v109
	v_pk_mul_f32 v[110:111], v[110:111], v[146:147] op_sel:[0,1] op_sel_hi:[1,0]
	s_nop 0
	v_pk_fma_f32 v[110:111], v[146:147], v[108:109], v[110:111] op_sel_hi:[1,0,1]
	ds_write_b64 v106, v[110:111] offset:2304
	v_pk_mul_f32 v[106:107], v[78:79], v[108:109] op_sel:[0,1] op_sel_hi:[1,0]
	s_nop 0
	v_pk_fma_f32 v[106:107], v[108:109], v[74:75], v[106:107] op_sel_hi:[1,0,1]
	s_nop 0
	v_pk_add_f32 v[108:109], v[106:107], 0 neg_lo:[1,1] neg_hi:[1,1]
	s_nop 0
	v_mov_b32_e32 v108, v107
	v_pk_mul_f32 v[108:109], v[108:109], v[156:157] op_sel:[0,1] op_sel_hi:[1,0]
	s_nop 0
	v_pk_fma_f32 v[108:109], v[156:157], v[106:107], v[108:109] op_sel_hi:[1,0,1]
	ds_write_b64 v105, v[108:109] offset:2560
	v_pk_mul_f32 v[108:109], v[78:79], v[106:107] op_sel:[0,1] op_sel_hi:[1,0]
	s_nop 0
	v_pk_fma_f32 v[106:107], v[106:107], v[74:75], v[108:109] op_sel_hi:[1,0,1]
	s_nop 0
	v_pk_add_f32 v[108:109], v[106:107], 0 neg_lo:[1,1] neg_hi:[1,1]
	s_nop 0
	v_mov_b32_e32 v108, v107
	v_pk_mul_f32 v[108:109], v[108:109], v[158:159] op_sel:[0,1] op_sel_hi:[1,0]
	s_nop 0
	v_pk_fma_f32 v[108:109], v[158:159], v[106:107], v[108:109] op_sel_hi:[1,0,1]
	ds_write_b64 v103, v[108:109] offset:2816
	v_pk_mul_f32 v[108:109], v[78:79], v[106:107] op_sel:[0,1] op_sel_hi:[1,0]
	s_nop 0
	v_pk_fma_f32 v[106:107], v[106:107], v[74:75], v[108:109] op_sel_hi:[1,0,1]
	s_nop 0
	v_pk_add_f32 v[108:109], v[106:107], 0 neg_lo:[1,1] neg_hi:[1,1]
	s_nop 0
	v_mov_b32_e32 v108, v107
	v_pk_mul_f32 v[108:109], v[108:109], v[160:161] op_sel:[0,1] op_sel_hi:[1,0]
	s_nop 0
	v_pk_fma_f32 v[108:109], v[160:161], v[106:107], v[108:109] op_sel_hi:[1,0,1]
	ds_write_b64 v102, v[108:109] offset:3072
	v_pk_mul_f32 v[102:103], v[78:79], v[106:107] op_sel:[0,1] op_sel_hi:[1,0]
	s_nop 0
	v_pk_fma_f32 v[102:103], v[106:107], v[74:75], v[102:103] op_sel_hi:[1,0,1]
	s_nop 0
	v_pk_add_f32 v[106:107], v[102:103], 0 neg_lo:[1,1] neg_hi:[1,1]
	s_nop 0
	v_mov_b32_e32 v106, v103
	v_pk_mul_f32 v[106:107], v[106:107], v[130:131] op_sel:[0,1] op_sel_hi:[1,0]
	s_nop 0
	v_pk_fma_f32 v[106:107], v[130:131], v[102:103], v[106:107] op_sel_hi:[1,0,1]
	ds_write_b64 v101, v[106:107] offset:3328
	v_pk_mul_f32 v[106:107], v[78:79], v[102:103] op_sel:[0,1] op_sel_hi:[1,0]
	s_nop 0
	v_pk_fma_f32 v[102:103], v[102:103], v[74:75], v[106:107] op_sel_hi:[1,0,1]
	s_nop 0
	v_pk_add_f32 v[106:107], v[102:103], 0 neg_lo:[1,1] neg_hi:[1,1]
	s_nop 0
	v_mov_b32_e32 v106, v103
	v_pk_mul_f32 v[106:107], v[150:151], v[106:107] op_sel:[1,0] op_sel_hi:[0,1]
	v_pk_fma_f32 v[106:107], v[150:151], v[102:103], v[106:107] op_sel_hi:[1,0,1]
	ds_write_b64 v100, v[106:107] offset:3584
	v_pk_mul_f32 v[100:101], v[78:79], v[102:103] op_sel:[0,1] op_sel_hi:[1,0]
	s_nop 0
	v_pk_fma_f32 v[100:101], v[102:103], v[74:75], v[100:101] op_sel_hi:[1,0,1]
	s_nop 0
	v_pk_add_f32 v[102:103], v[100:101], 0 neg_lo:[1,1] neg_hi:[1,1]
	s_nop 0
	v_mov_b32_e32 v102, v101
	v_pk_mul_f32 v[102:103], v[162:163], v[102:103] op_sel:[1,0] op_sel_hi:[0,1]
	v_pk_fma_f32 v[102:103], v[162:163], v[100:101], v[102:103] op_sel_hi:[1,0,1]
	ds_write_b64 v99, v[102:103] offset:3840
	v_pk_mul_f32 v[102:103], v[78:79], v[100:101] op_sel:[0,1] op_sel_hi:[1,0]
	s_nop 0
	v_pk_fma_f32 v[100:101], v[100:101], v[74:75], v[102:103] op_sel_hi:[1,0,1]
	s_nop 0
	v_pk_add_f32 v[102:103], v[100:101], 0 neg_lo:[1,1] neg_hi:[1,1]
	s_nop 0
	v_mov_b32_e32 v102, v101
	v_pk_mul_f32 v[102:103], v[118:119], v[102:103] op_sel:[1,0] op_sel_hi:[0,1]
	v_pk_fma_f32 v[102:103], v[118:119], v[100:101], v[102:103] op_sel_hi:[1,0,1]
	ds_write_b64 v98, v[102:103] offset:4096
	v_pk_mul_f32 v[98:99], v[78:79], v[100:101] op_sel:[0,1] op_sel_hi:[1,0]
	s_nop 0
	v_pk_fma_f32 v[98:99], v[100:101], v[74:75], v[98:99] op_sel_hi:[1,0,1]
	s_nop 0
	v_pk_add_f32 v[100:101], v[98:99], 0 neg_lo:[1,1] neg_hi:[1,1]
	s_nop 0
	v_mov_b32_e32 v100, v99
	v_pk_mul_f32 v[100:101], v[120:121], v[100:101] op_sel:[1,0] op_sel_hi:[0,1]
	v_pk_fma_f32 v[100:101], v[120:121], v[98:99], v[100:101] op_sel_hi:[1,0,1]
	ds_write_b64 v97, v[100:101] offset:4352
	v_pk_mul_f32 v[100:101], v[78:79], v[98:99] op_sel:[0,1] op_sel_hi:[1,0]
	s_nop 0
	v_pk_fma_f32 v[98:99], v[98:99], v[74:75], v[100:101] op_sel_hi:[1,0,1]
	s_nop 0
	v_pk_add_f32 v[100:101], v[98:99], 0 neg_lo:[1,1] neg_hi:[1,1]
	s_nop 0
	v_mov_b32_e32 v100, v99
	v_pk_mul_f32 v[100:101], v[142:143], v[100:101] op_sel:[1,0] op_sel_hi:[0,1]
	v_pk_fma_f32 v[100:101], v[142:143], v[98:99], v[100:101] op_sel_hi:[1,0,1]
	ds_write_b64 v96, v[100:101] offset:4608
	v_pk_mul_f32 v[96:97], v[78:79], v[98:99] op_sel:[0,1] op_sel_hi:[1,0]
	s_nop 0
	v_pk_fma_f32 v[96:97], v[98:99], v[74:75], v[96:97] op_sel_hi:[1,0,1]
	s_nop 0
	v_pk_add_f32 v[98:99], v[96:97], 0 neg_lo:[1,1] neg_hi:[1,1]
	s_nop 0
	v_mov_b32_e32 v98, v97
	v_pk_mul_f32 v[98:99], v[126:127], v[98:99] op_sel:[1,0] op_sel_hi:[0,1]
	v_pk_fma_f32 v[98:99], v[126:127], v[96:97], v[98:99] op_sel_hi:[1,0,1]
	ds_write_b64 v95, v[98:99] offset:4864
	v_pk_mul_f32 v[98:99], v[78:79], v[96:97] op_sel:[0,1] op_sel_hi:[1,0]
	s_nop 0
	v_pk_fma_f32 v[96:97], v[96:97], v[74:75], v[98:99] op_sel_hi:[1,0,1]
	s_nop 0
	v_pk_add_f32 v[98:99], v[96:97], 0 neg_lo:[1,1] neg_hi:[1,1]
	s_nop 0
	v_mov_b32_e32 v98, v97
	v_pk_mul_f32 v[98:99], v[136:137], v[98:99] op_sel:[1,0] op_sel_hi:[0,1]
	v_pk_fma_f32 v[98:99], v[136:137], v[96:97], v[98:99] op_sel_hi:[1,0,1]
	ds_write_b64 v94, v[98:99] offset:5120
	v_pk_mul_f32 v[94:95], v[78:79], v[96:97] op_sel:[0,1] op_sel_hi:[1,0]
	s_nop 0
	v_pk_fma_f32 v[94:95], v[96:97], v[74:75], v[94:95] op_sel_hi:[1,0,1]
	s_nop 0
	v_pk_add_f32 v[96:97], v[94:95], 0 neg_lo:[1,1] neg_hi:[1,1]
	s_nop 0
	v_mov_b32_e32 v96, v95
	v_pk_mul_f32 v[96:97], v[122:123], v[96:97] op_sel:[1,0] op_sel_hi:[0,1]
	v_pk_fma_f32 v[96:97], v[122:123], v[94:95], v[96:97] op_sel_hi:[1,0,1]
	ds_write_b64 v93, v[96:97] offset:5376
	v_pk_mul_f32 v[96:97], v[78:79], v[94:95] op_sel:[0,1] op_sel_hi:[1,0]
	s_nop 0
	v_pk_fma_f32 v[94:95], v[94:95], v[74:75], v[96:97] op_sel_hi:[1,0,1]
	s_nop 0
	v_pk_add_f32 v[96:97], v[94:95], 0 neg_lo:[1,1] neg_hi:[1,1]
	s_nop 0
	v_mov_b32_e32 v96, v95
	v_pk_mul_f32 v[96:97], v[138:139], v[96:97] op_sel:[1,0] op_sel_hi:[0,1]
	v_pk_fma_f32 v[96:97], v[138:139], v[94:95], v[96:97] op_sel_hi:[1,0,1]
	ds_write_b64 v92, v[96:97] offset:5632
	v_pk_mul_f32 v[92:93], v[78:79], v[94:95] op_sel:[0,1] op_sel_hi:[1,0]
	s_nop 0
	v_pk_fma_f32 v[92:93], v[94:95], v[74:75], v[92:93] op_sel_hi:[1,0,1]
	s_nop 0
	v_pk_add_f32 v[94:95], v[92:93], 0 neg_lo:[1,1] neg_hi:[1,1]
	s_nop 0
	v_mov_b32_e32 v94, v93
	v_pk_mul_f32 v[94:95], v[132:133], v[94:95] op_sel:[1,0] op_sel_hi:[0,1]
	v_pk_fma_f32 v[94:95], v[132:133], v[92:93], v[94:95] op_sel_hi:[1,0,1]
	ds_write_b64 v91, v[94:95] offset:5888
	v_pk_mul_f32 v[94:95], v[78:79], v[92:93] op_sel:[0,1] op_sel_hi:[1,0]
	s_nop 0
	v_pk_fma_f32 v[92:93], v[92:93], v[74:75], v[94:95] op_sel_hi:[1,0,1]
	s_nop 0
	v_pk_add_f32 v[94:95], v[92:93], 0 neg_lo:[1,1] neg_hi:[1,1]
	s_nop 0
	v_mov_b32_e32 v94, v93
	v_pk_mul_f32 v[94:95], v[82:83], v[94:95] op_sel:[1,0] op_sel_hi:[0,1]
	v_pk_fma_f32 v[82:83], v[82:83], v[92:93], v[94:95] op_sel_hi:[1,0,1]
	ds_write_b64 v90, v[82:83] offset:6144
	v_pk_mul_f32 v[82:83], v[78:79], v[92:93] op_sel:[0,1] op_sel_hi:[1,0]
	s_nop 0
	v_pk_fma_f32 v[82:83], v[92:93], v[74:75], v[82:83] op_sel_hi:[1,0,1]
	s_nop 0
	v_pk_add_f32 v[90:91], v[82:83], 0 neg_lo:[1,1] neg_hi:[1,1]
	s_nop 0
	v_mov_b32_e32 v90, v83
	v_pk_mul_f32 v[90:91], v[148:149], v[90:91] op_sel:[1,0] op_sel_hi:[0,1]
	v_pk_fma_f32 v[90:91], v[148:149], v[82:83], v[90:91] op_sel_hi:[1,0,1]
	ds_write_b64 v89, v[90:91] offset:6400
	v_pk_mul_f32 v[90:91], v[78:79], v[82:83] op_sel:[0,1] op_sel_hi:[1,0]
	s_nop 0
	v_pk_fma_f32 v[82:83], v[82:83], v[74:75], v[90:91] op_sel_hi:[1,0,1]
	s_nop 0
	v_pk_add_f32 v[90:91], v[82:83], 0 neg_lo:[1,1] neg_hi:[1,1]
	s_nop 0
	v_mov_b32_e32 v90, v83
	v_pk_mul_f32 v[90:91], v[76:77], v[90:91] op_sel:[1,0] op_sel_hi:[0,1]
	v_pk_fma_f32 v[76:77], v[76:77], v[82:83], v[90:91] op_sel_hi:[1,0,1]
	ds_write_b64 v88, v[76:77] offset:6656
	v_pk_mul_f32 v[76:77], v[78:79], v[82:83] op_sel:[0,1] op_sel_hi:[1,0]
	s_nop 0
	v_pk_fma_f32 v[76:77], v[82:83], v[74:75], v[76:77] op_sel_hi:[1,0,1]
	s_nop 0
	v_pk_add_f32 v[82:83], v[76:77], 0 neg_lo:[1,1] neg_hi:[1,1]
	s_nop 0
	v_mov_b32_e32 v82, v77
	v_pk_mul_f32 v[82:83], v[80:81], v[82:83] op_sel:[1,0] op_sel_hi:[0,1]
	v_pk_fma_f32 v[80:81], v[80:81], v[76:77], v[82:83] op_sel_hi:[1,0,1]
	ds_write_b64 v87, v[80:81] offset:6912
	v_pk_mul_f32 v[80:81], v[78:79], v[76:77] op_sel:[0,1] op_sel_hi:[1,0]
	s_nop 0
	v_pk_fma_f32 v[76:77], v[76:77], v[74:75], v[80:81] op_sel_hi:[1,0,1]
	s_nop 0
	v_pk_add_f32 v[80:81], v[76:77], 0 neg_lo:[1,1] neg_hi:[1,1]
	s_nop 0
	v_mov_b32_e32 v80, v77
	v_pk_mul_f32 v[80:81], v[68:69], v[80:81] op_sel:[1,0] op_sel_hi:[0,1]
	v_pk_fma_f32 v[68:69], v[68:69], v[76:77], v[80:81] op_sel_hi:[1,0,1]
	ds_write_b64 v86, v[68:69] offset:7168
	v_pk_mul_f32 v[68:69], v[78:79], v[76:77] op_sel:[0,1] op_sel_hi:[1,0]
	s_nop 0
	v_pk_fma_f32 v[68:69], v[76:77], v[74:75], v[68:69] op_sel_hi:[1,0,1]
	s_nop 0
	v_pk_add_f32 v[76:77], v[68:69], 0 neg_lo:[1,1] neg_hi:[1,1]
	s_nop 0
	v_mov_b32_e32 v76, v69
	v_pk_mul_f32 v[76:77], v[72:73], v[76:77] op_sel:[1,0] op_sel_hi:[0,1]
	v_pk_fma_f32 v[72:73], v[72:73], v[68:69], v[76:77] op_sel_hi:[1,0,1]
	ds_write_b64 v85, v[72:73] offset:7424
	v_pk_mul_f32 v[72:73], v[78:79], v[68:69] op_sel:[0,1] op_sel_hi:[1,0]
	s_nop 0
	v_pk_fma_f32 v[68:69], v[68:69], v[74:75], v[72:73] op_sel_hi:[1,0,1]
	s_nop 0
	v_pk_add_f32 v[72:73], v[68:69], 0 neg_lo:[1,1] neg_hi:[1,1]
	s_nop 0
	v_mov_b32_e32 v72, v69
	v_pk_mul_f32 v[72:73], v[66:67], v[72:73] op_sel:[1,0] op_sel_hi:[0,1]
	v_pk_fma_f32 v[66:67], v[66:67], v[68:69], v[72:73] op_sel_hi:[1,0,1]
	ds_write_b64 v84, v[66:67] offset:7680
	v_pk_mul_f32 v[66:67], v[78:79], v[68:69] op_sel:[0,1] op_sel_hi:[1,0]
	s_nop 0
	v_pk_fma_f32 v[66:67], v[68:69], v[74:75], v[66:67] op_sel_hi:[1,0,1]
	s_nop 0
	v_pk_add_f32 v[68:69], v[66:67], 0 neg_lo:[1,1] neg_hi:[1,1]
	s_nop 0
	v_mov_b32_e32 v68, v67
	v_pk_mul_f32 v[68:69], v[70:71], v[68:69] op_sel:[1,0] op_sel_hi:[0,1]
	v_pk_fma_f32 v[66:67], v[70:71], v[66:67], v[68:69] op_sel_hi:[1,0,1]
	ds_write_b64 v0, v[66:67]
	s_waitcnt lgkmcnt(0)
	s_barrier
	ds_read2_b64 v[66:69], v104 offset1:1
	ds_read2_b64 v[70:73], v104 offset0:2 offset1:3
	ds_read2_b64 v[74:77], v104 offset0:4 offset1:5
	ds_read2_b64 v[78:81], v104 offset0:6 offset1:7
	ds_read2_b64 v[82:85], v104 offset0:8 offset1:9
	ds_read2_b64 v[86:89], v104 offset0:10 offset1:11
	ds_read2_b64 v[90:93], v104 offset0:12 offset1:13
	ds_read2_b64 v[94:97], v104 offset0:14 offset1:15
	ds_read2_b64 v[98:101], v104 offset0:16 offset1:17
	ds_read2_b64 v[106:109], v104 offset0:18 offset1:19
	ds_read2_b64 v[110:113], v104 offset0:20 offset1:21
	ds_read2_b64 v[114:117], v104 offset0:22 offset1:23
	ds_read2_b64 v[118:121], v104 offset0:24 offset1:25
	ds_read2_b64 v[122:125], v104 offset0:26 offset1:27
	ds_read2_b64 v[126:129], v104 offset0:28 offset1:29
	ds_read2_b64 v[130:133], v104 offset0:30 offset1:31
	s_waitcnt lgkmcnt(7)
	v_pk_add_f32 v[102:103], v[66:67], v[98:99]
	v_pk_add_f32 v[66:67], v[66:67], v[98:99] neg_lo:[0,1] neg_hi:[0,1]
	v_pk_add_f32 v[98:99], v[68:69], v[100:101]
	v_pk_add_f32 v[68:69], v[68:69], v[100:101] neg_lo:[0,1] neg_hi:[0,1]
	global_load_dwordx2 v[134:135], v[2:3], off
	global_load_dwordx2 v[136:137], v[4:5], off
	global_load_dwordx2 v[138:139], v[6:7], off
	v_pk_mul_f32 v[100:101], v[68:69], s[18:19]
	global_load_dwordx2 v[148:149], v[14:15], off
	global_load_dwordx2 v[154:155], v[16:17], off
	v_pk_fma_f32 v[68:69], v[68:69], s[20:21], v[100:101] op_sel:[0,0,1] op_sel_hi:[1,0,0]
	s_waitcnt lgkmcnt(6)
	v_pk_add_f32 v[100:101], v[70:71], v[106:107]
	v_pk_add_f32 v[70:71], v[70:71], v[106:107] neg_lo:[0,1] neg_hi:[0,1]
	global_load_dwordx2 v[158:159], v[18:19], off
	v_pk_mul_f32 v[106:107], v[70:71], s[4:5]
	global_load_dwordx2 v[160:161], v[28:29], off
	global_load_dwordx2 v[164:165], v[32:33], off
	v_pk_fma_f32 v[70:71], v[70:71], s[6:7], v[106:107] op_sel:[0,0,1] op_sel_hi:[1,0,0]
	v_pk_add_f32 v[106:107], v[72:73], v[108:109]
	v_pk_add_f32 v[72:73], v[72:73], v[108:109] neg_lo:[0,1] neg_hi:[0,1]
	global_load_dwordx2 v[168:169], v[36:37], off
	v_pk_mul_f32 v[108:109], v[72:73], s[22:23]
	global_load_dwordx2 v[172:173], v[44:45], off
	v_pk_fma_f32 v[72:73], v[72:73], s[24:25], v[108:109] op_sel:[0,0,1] op_sel_hi:[1,0,0]
	s_waitcnt lgkmcnt(5)
	v_pk_add_f32 v[108:109], v[74:75], v[110:111]
	v_pk_add_f32 v[74:75], v[74:75], v[110:111] neg_lo:[0,1] neg_hi:[0,1]
	global_load_dwordx2 v[174:175], v[52:53], off
	v_pk_mul_f32 v[110:111], v[74:75], s[8:9]
	global_load_dwordx2 v[176:177], v[60:61], off
	v_pk_fma_f32 v[74:75], v[74:75], s[10:11], v[110:111] op_sel:[0,0,1] op_sel_hi:[1,0,0]
	v_pk_add_f32 v[110:111], v[76:77], v[112:113]
	v_pk_add_f32 v[76:77], v[76:77], v[112:113] neg_lo:[0,1] neg_hi:[0,1]
	s_nop 0
	v_pk_mul_f32 v[112:113], v[76:77], s[26:27]
	s_nop 0
	v_pk_fma_f32 v[76:77], v[76:77], s[0:1], v[112:113] op_sel:[0,0,1] op_sel_hi:[1,0,0]
	s_waitcnt lgkmcnt(4)
	v_pk_add_f32 v[112:113], v[78:79], v[114:115]
	v_pk_add_f32 v[78:79], v[78:79], v[114:115] neg_lo:[0,1] neg_hi:[0,1]
	s_nop 0
	v_pk_mul_f32 v[114:115], v[78:79], s[12:13]
	s_nop 0
	v_pk_fma_f32 v[78:79], v[78:79], s[14:15], v[114:115] op_sel:[0,0,1] op_sel_hi:[1,0,0]
	v_pk_add_f32 v[114:115], v[80:81], v[116:117]
	v_pk_add_f32 v[80:81], v[80:81], v[116:117] neg_lo:[0,1] neg_hi:[0,1]
	s_nop 0
	v_pk_mul_f32 v[116:117], v[80:81], s[34:35]
	s_nop 0
	v_pk_fma_f32 v[80:81], v[80:81], s[48:49], v[116:117] op_sel:[0,0,1] op_sel_hi:[1,0,0]
	s_waitcnt lgkmcnt(3)
	v_pk_add_f32 v[116:117], v[82:83], v[118:119]
	v_pk_add_f32 v[118:119], v[82:83], v[118:119] op_sel:[1,1] op_sel_hi:[0,0] neg_lo:[0,1] neg_hi:[1,0]
	s_nop 0
	v_pk_add_f32 v[82:83], v[84:85], v[120:121]
	v_pk_add_f32 v[84:85], v[84:85], v[120:121] neg_lo:[0,1] neg_hi:[0,1]
	s_nop 0
	v_pk_mul_f32 v[120:121], v[84:85], s[34:35]
	s_nop 0
	v_pk_fma_f32 v[84:85], v[84:85], s[18:19], v[120:121] op_sel:[0,0,1] op_sel_hi:[1,0,0]
	s_waitcnt lgkmcnt(2)
	v_pk_add_f32 v[120:121], v[86:87], v[122:123]
	v_pk_add_f32 v[86:87], v[86:87], v[122:123] neg_lo:[0,1] neg_hi:[0,1]
	s_nop 0
	v_pk_mul_f32 v[122:123], v[86:87], s[12:13]
	s_nop 0
	v_pk_fma_f32 v[86:87], v[86:87], s[4:5], v[122:123] op_sel:[0,0,1] op_sel_hi:[1,0,0]
	v_pk_add_f32 v[122:123], v[88:89], v[124:125]
	v_pk_add_f32 v[88:89], v[88:89], v[124:125] neg_lo:[0,1] neg_hi:[0,1]
	s_nop 0
	v_pk_mul_f32 v[124:125], v[88:89], s[26:27]
	s_nop 0
	v_pk_fma_f32 v[88:89], v[88:89], s[22:23], v[124:125] op_sel:[0,0,1] op_sel_hi:[1,0,0]
	s_waitcnt lgkmcnt(1)
	v_pk_add_f32 v[124:125], v[90:91], v[126:127]
	v_pk_add_f32 v[90:91], v[90:91], v[126:127] neg_lo:[0,1] neg_hi:[0,1]
	s_nop 0
	v_pk_mul_f32 v[126:127], v[90:91], s[8:9]
	s_nop 0
	v_pk_fma_f32 v[90:91], v[90:91], s[8:9], v[126:127] op_sel:[0,0,1] op_sel_hi:[1,0,0]
	v_pk_add_f32 v[126:127], v[92:93], v[128:129]
	v_pk_add_f32 v[92:93], v[92:93], v[128:129] neg_lo:[0,1] neg_hi:[0,1]
	s_nop 0
	v_pk_mul_f32 v[128:129], v[92:93], s[22:23]
	s_nop 0
	v_pk_fma_f32 v[92:93], v[92:93], s[26:27], v[128:129] op_sel:[0,0,1] op_sel_hi:[1,0,0]
	s_waitcnt lgkmcnt(0)
	v_pk_add_f32 v[128:129], v[94:95], v[130:131]
	v_pk_add_f32 v[94:95], v[94:95], v[130:131] neg_lo:[0,1] neg_hi:[0,1]
	s_nop 0
	v_pk_mul_f32 v[130:131], v[94:95], s[4:5]
	s_nop 0
	v_pk_fma_f32 v[94:95], v[94:95], s[12:13], v[130:131] op_sel:[0,0,1] op_sel_hi:[1,0,0]
	v_pk_add_f32 v[130:131], v[96:97], v[132:133]
	v_pk_add_f32 v[96:97], v[96:97], v[132:133] neg_lo:[0,1] neg_hi:[0,1]
	s_nop 0
	v_pk_mul_f32 v[132:133], v[96:97], s[18:19]
	s_nop 0
	v_pk_fma_f32 v[96:97], v[96:97], s[34:35], v[132:133] op_sel:[0,0,1] op_sel_hi:[1,0,0]
	v_pk_add_f32 v[132:133], v[102:103], v[116:117]
	v_pk_add_f32 v[102:103], v[102:103], v[116:117] neg_lo:[0,1] neg_hi:[0,1]
	v_pk_add_f32 v[116:117], v[98:99], v[82:83]
	v_pk_add_f32 v[82:83], v[98:99], v[82:83] neg_lo:[0,1] neg_hi:[0,1]
	s_nop 0
	v_pk_mul_f32 v[98:99], v[82:83], s[4:5]
	s_nop 0
	v_pk_fma_f32 v[82:83], v[82:83], s[6:7], v[98:99] op_sel:[0,0,1] op_sel_hi:[1,0,0]
	v_pk_add_f32 v[98:99], v[100:101], v[120:121]
	v_pk_add_f32 v[100:101], v[100:101], v[120:121] neg_lo:[0,1] neg_hi:[0,1]
	s_nop 0
	v_pk_mul_f32 v[120:121], v[100:101], s[8:9]
	s_nop 0
	v_pk_fma_f32 v[100:101], v[100:101], s[10:11], v[120:121] op_sel:[0,0,1] op_sel_hi:[1,0,0]
	v_pk_add_f32 v[120:121], v[106:107], v[122:123]
	v_pk_add_f32 v[106:107], v[106:107], v[122:123] neg_lo:[0,1] neg_hi:[0,1]
	s_nop 0
	v_pk_mul_f32 v[122:123], v[106:107], s[12:13]
	s_nop 0
	v_pk_fma_f32 v[106:107], v[106:107], s[14:15], v[122:123] op_sel:[0,0,1] op_sel_hi:[1,0,0]
	v_pk_add_f32 v[122:123], v[108:109], v[124:125]
	v_pk_add_f32 v[124:125], v[108:109], v[124:125] op_sel:[1,1] op_sel_hi:[0,0] neg_lo:[0,1] neg_hi:[1,0]
	s_nop 0
	v_pk_add_f32 v[108:109], v[110:111], v[126:127]
	v_pk_add_f32 v[110:111], v[110:111], v[126:127] neg_lo:[0,1] neg_hi:[0,1]
	s_nop 0
	v_pk_mul_f32 v[126:127], v[110:111], s[12:13]
	s_nop 0
	v_pk_fma_f32 v[110:111], v[110:111], s[4:5], v[126:127] op_sel:[0,0,1] op_sel_hi:[1,0,0]
	v_pk_add_f32 v[126:127], v[112:113], v[128:129]
	v_pk_add_f32 v[112:113], v[112:113], v[128:129] neg_lo:[0,1] neg_hi:[0,1]
	s_nop 0
	v_pk_mul_f32 v[128:129], v[112:113], s[8:9]
	s_nop 0
	v_pk_fma_f32 v[112:113], v[112:113], s[8:9], v[128:129] op_sel:[0,0,1] op_sel_hi:[1,0,0]
	v_pk_add_f32 v[128:129], v[114:115], v[130:131]
	v_pk_add_f32 v[114:115], v[114:115], v[130:131] neg_lo:[0,1] neg_hi:[0,1]
	s_nop 0
	v_pk_mul_f32 v[130:131], v[114:115], s[4:5]
	s_nop 0
	v_pk_fma_f32 v[114:115], v[114:115], s[12:13], v[130:131] op_sel:[0,0,1] op_sel_hi:[1,0,0]
	v_pk_add_f32 v[130:131], v[66:67], v[118:119]
	v_pk_add_f32 v[66:67], v[66:67], v[118:119] neg_lo:[0,1] neg_hi:[0,1]
	v_pk_add_f32 v[118:119], v[68:69], v[84:85]
	v_pk_add_f32 v[68:69], v[68:69], v[84:85] neg_lo:[0,1] neg_hi:[0,1]
	s_nop 0
	v_pk_mul_f32 v[84:85], v[68:69], s[4:5]
	s_nop 0
	v_pk_fma_f32 v[68:69], v[68:69], s[6:7], v[84:85] op_sel:[0,0,1] op_sel_hi:[1,0,0]
	v_pk_add_f32 v[84:85], v[70:71], v[86:87]
	v_pk_add_f32 v[70:71], v[70:71], v[86:87] neg_lo:[0,1] neg_hi:[0,1]
	s_nop 0
	v_pk_mul_f32 v[86:87], v[70:71], s[8:9]
	s_nop 0
	v_pk_fma_f32 v[70:71], v[70:71], s[10:11], v[86:87] op_sel:[0,0,1] op_sel_hi:[1,0,0]
	v_pk_add_f32 v[86:87], v[72:73], v[88:89]
	v_pk_add_f32 v[72:73], v[72:73], v[88:89] neg_lo:[0,1] neg_hi:[0,1]
	s_nop 0
	v_pk_mul_f32 v[88:89], v[72:73], s[12:13]
	s_nop 0
	v_pk_fma_f32 v[72:73], v[72:73], s[14:15], v[88:89] op_sel:[0,0,1] op_sel_hi:[1,0,0]
	v_pk_add_f32 v[88:89], v[74:75], v[90:91]
	v_pk_add_f32 v[90:91], v[74:75], v[90:91] op_sel:[1,1] op_sel_hi:[0,0] neg_lo:[0,1] neg_hi:[1,0]
	s_mov_b32 s15, s4
	v_pk_add_f32 v[74:75], v[76:77], v[92:93]
	v_pk_add_f32 v[76:77], v[76:77], v[92:93] neg_lo:[0,1] neg_hi:[0,1]
	s_nop 0
	v_pk_mul_f32 v[92:93], v[76:77], s[12:13]
	s_nop 0
	v_pk_fma_f32 v[76:77], v[76:77], s[4:5], v[92:93] op_sel:[0,0,1] op_sel_hi:[1,0,0]
	v_pk_add_f32 v[92:93], v[78:79], v[94:95]
	v_pk_add_f32 v[78:79], v[78:79], v[94:95] neg_lo:[0,1] neg_hi:[0,1]
	s_nop 0
	v_pk_mul_f32 v[94:95], v[78:79], s[8:9]
	s_nop 0
	v_pk_fma_f32 v[78:79], v[78:79], s[8:9], v[94:95] op_sel:[0,0,1] op_sel_hi:[1,0,0]
	v_pk_add_f32 v[94:95], v[80:81], v[96:97]
	v_pk_add_f32 v[80:81], v[80:81], v[96:97] neg_lo:[0,1] neg_hi:[0,1]
	s_nop 0
	v_pk_mul_f32 v[96:97], v[80:81], s[4:5]
	s_nop 0
	v_pk_fma_f32 v[80:81], v[80:81], s[12:13], v[96:97] op_sel:[0,0,1] op_sel_hi:[1,0,0]
	v_pk_add_f32 v[96:97], v[132:133], v[122:123]
	v_pk_add_f32 v[122:123], v[132:133], v[122:123] neg_lo:[0,1] neg_hi:[0,1]
	v_pk_add_f32 v[132:133], v[116:117], v[108:109]
	v_pk_add_f32 v[108:109], v[116:117], v[108:109] neg_lo:[0,1] neg_hi:[0,1]
	s_nop 0
	v_pk_mul_f32 v[116:117], v[108:109], s[8:9]
	s_nop 0
	v_pk_fma_f32 v[108:109], v[108:109], s[10:11], v[116:117] op_sel:[0,0,1] op_sel_hi:[1,0,0]
	v_pk_add_f32 v[116:117], v[98:99], v[126:127]
	v_pk_add_f32 v[126:127], v[98:99], v[126:127] op_sel:[1,1] op_sel_hi:[0,0] neg_lo:[0,1] neg_hi:[1,0]
	s_nop 0
	v_pk_add_f32 v[98:99], v[120:121], v[128:129]
	v_pk_add_f32 v[120:121], v[120:121], v[128:129] neg_lo:[0,1] neg_hi:[0,1]
	s_nop 0
	v_pk_mul_f32 v[128:129], v[120:121], s[8:9]
	s_nop 0
	v_pk_fma_f32 v[120:121], v[120:121], s[8:9], v[128:129] op_sel:[0,0,1] op_sel_hi:[1,0,0]
	v_pk_add_f32 v[128:129], v[102:103], v[124:125]
	v_pk_add_f32 v[102:103], v[102:103], v[124:125] neg_lo:[0,1] neg_hi:[0,1]
	v_pk_add_f32 v[124:125], v[82:83], v[110:111]
	v_pk_add_f32 v[82:83], v[82:83], v[110:111] neg_lo:[0,1] neg_hi:[0,1]
	s_nop 0
	v_pk_mul_f32 v[110:111], v[82:83], s[8:9]
	s_nop 0
	v_pk_fma_f32 v[82:83], v[82:83], s[10:11], v[110:111] op_sel:[0,0,1] op_sel_hi:[1,0,0]
	v_pk_add_f32 v[110:111], v[100:101], v[112:113]
	v_pk_add_f32 v[112:113], v[100:101], v[112:113] op_sel:[1,1] op_sel_hi:[0,0] neg_lo:[0,1] neg_hi:[1,0]
	s_nop 0
	v_pk_add_f32 v[100:101], v[106:107], v[114:115]
	v_pk_add_f32 v[106:107], v[106:107], v[114:115] neg_lo:[0,1] neg_hi:[0,1]
	s_nop 0
	v_pk_mul_f32 v[114:115], v[106:107], s[8:9]
	s_nop 0
	v_pk_fma_f32 v[106:107], v[106:107], s[8:9], v[114:115] op_sel:[0,0,1] op_sel_hi:[1,0,0]
	v_pk_add_f32 v[114:115], v[130:131], v[88:89]
	v_pk_add_f32 v[88:89], v[130:131], v[88:89] neg_lo:[0,1] neg_hi:[0,1]
	v_pk_add_f32 v[130:131], v[118:119], v[74:75]
	v_pk_add_f32 v[74:75], v[118:119], v[74:75] neg_lo:[0,1] neg_hi:[0,1]
	s_nop 0
	v_pk_mul_f32 v[118:119], v[74:75], s[8:9]
	s_nop 0
	v_pk_fma_f32 v[74:75], v[74:75], s[10:11], v[118:119] op_sel:[0,0,1] op_sel_hi:[1,0,0]
	v_pk_add_f32 v[118:119], v[84:85], v[92:93]
	v_pk_add_f32 v[92:93], v[84:85], v[92:93] op_sel:[1,1] op_sel_hi:[0,0] neg_lo:[0,1] neg_hi:[1,0]
	s_nop 0
	v_pk_add_f32 v[84:85], v[86:87], v[94:95]
	v_pk_add_f32 v[86:87], v[86:87], v[94:95] neg_lo:[0,1] neg_hi:[0,1]
	v_pk_add_f32 v[140:141], v[88:89], v[92:93]
	v_pk_mul_f32 v[94:95], v[86:87], s[8:9]
	v_pk_add_f32 v[88:89], v[88:89], v[92:93] neg_lo:[0,1] neg_hi:[0,1]
	v_pk_fma_f32 v[86:87], v[86:87], s[8:9], v[94:95] op_sel:[0,0,1] op_sel_hi:[1,0,0]
	v_pk_add_f32 v[94:95], v[66:67], v[90:91]
	v_pk_add_f32 v[66:67], v[66:67], v[90:91] neg_lo:[0,1] neg_hi:[0,1]
	v_pk_add_f32 v[90:91], v[68:69], v[76:77]
	v_pk_add_f32 v[68:69], v[68:69], v[76:77] neg_lo:[0,1] neg_hi:[0,1]
	v_pk_add_f32 v[92:93], v[74:75], v[86:87]
	v_pk_mul_f32 v[76:77], v[68:69], s[8:9]
	v_pk_add_f32 v[142:143], v[74:75], v[86:87] op_sel:[1,1] op_sel_hi:[0,0] neg_lo:[0,1] neg_hi:[1,0]
	v_pk_fma_f32 v[68:69], v[68:69], s[10:11], v[76:77] op_sel:[0,0,1] op_sel_hi:[1,0,0]
	v_pk_add_f32 v[76:77], v[70:71], v[78:79]
	v_pk_add_f32 v[78:79], v[70:71], v[78:79] op_sel:[1,1] op_sel_hi:[0,0] neg_lo:[0,1] neg_hi:[1,0]
	global_load_dwordx2 v[86:87], v[10:11], off
	v_pk_add_f32 v[70:71], v[72:73], v[80:81]
	v_pk_add_f32 v[72:73], v[72:73], v[80:81] neg_lo:[0,1] neg_hi:[0,1]
	v_pk_mul_f32 v[80:81], v[72:73], s[8:9]
	v_pk_fma_f32 v[72:73], v[72:73], s[8:9], v[80:81] op_sel:[0,0,1] op_sel_hi:[1,0,0]
	v_pk_add_f32 v[80:81], v[96:97], v[116:117]
	v_pk_add_f32 v[96:97], v[96:97], v[116:117] neg_lo:[0,1] neg_hi:[0,1]
	v_pk_add_f32 v[116:117], v[132:133], v[98:99]
	v_pk_add_f32 v[132:133], v[132:133], v[98:99] op_sel:[1,1] op_sel_hi:[0,0] neg_lo:[0,1] neg_hi:[1,0]
	v_pk_add_f32 v[74:75], v[94:95], v[76:77]
	v_pk_add_f32 v[98:99], v[122:123], v[126:127]
	v_pk_add_f32 v[122:123], v[122:123], v[126:127] neg_lo:[0,1] neg_hi:[0,1]
	v_pk_add_f32 v[126:127], v[108:109], v[120:121]
	v_pk_add_f32 v[120:121], v[108:109], v[120:121] op_sel:[1,1] op_sel_hi:[0,0] neg_lo:[0,1] neg_hi:[1,0]
	v_pk_add_f32 v[76:77], v[94:95], v[76:77] neg_lo:[0,1] neg_hi:[0,1]
	v_pk_add_f32 v[108:109], v[128:129], v[110:111]
	v_pk_add_f32 v[110:111], v[128:129], v[110:111] neg_lo:[0,1] neg_hi:[0,1]
	v_pk_add_f32 v[128:129], v[124:125], v[100:101]
	v_pk_add_f32 v[124:125], v[124:125], v[100:101] op_sel:[1,1] op_sel_hi:[0,0] neg_lo:[0,1] neg_hi:[1,0]
	global_load_dwordx2 v[94:95], v[12:13], off
	v_pk_add_f32 v[100:101], v[102:103], v[112:113]
	v_pk_add_f32 v[102:103], v[102:103], v[112:113] neg_lo:[0,1] neg_hi:[0,1]
	v_pk_add_f32 v[112:113], v[82:83], v[106:107]
	v_pk_add_f32 v[106:107], v[82:83], v[106:107] op_sel:[1,1] op_sel_hi:[0,0] neg_lo:[0,1] neg_hi:[1,0]
	v_pk_add_f32 v[146:147], v[66:67], v[78:79]
	v_pk_add_f32 v[82:83], v[114:115], v[118:119]
	v_pk_add_f32 v[114:115], v[114:115], v[118:119] neg_lo:[0,1] neg_hi:[0,1]
	v_pk_add_f32 v[118:119], v[130:131], v[84:85]
	v_pk_add_f32 v[130:131], v[130:131], v[84:85] op_sel:[1,1] op_sel_hi:[0,0] neg_lo:[0,1] neg_hi:[1,0]
	v_pk_add_f32 v[78:79], v[66:67], v[78:79] neg_lo:[0,1] neg_hi:[0,1]
	global_load_dwordx2 v[84:85], v[8:9], off
	v_pk_add_f32 v[152:153], v[68:69], v[72:73] op_sel:[1,1] op_sel_hi:[0,0] neg_lo:[0,1] neg_hi:[1,0]
	v_pk_add_f32 v[150:151], v[68:69], v[72:73]
	v_pk_add_f32 v[156:157], v[80:81], v[116:117]
	v_pk_add_f32 v[80:81], v[80:81], v[116:117] neg_lo:[0,1] neg_hi:[0,1]
	v_pk_add_f32 v[116:117], v[96:97], v[132:133]
	v_pk_add_f32 v[68:69], v[96:97], v[132:133] neg_lo:[0,1] neg_hi:[0,1]
	v_pk_add_f32 v[96:97], v[98:99], v[126:127]
	v_pk_add_f32 v[98:99], v[98:99], v[126:127] neg_lo:[0,1] neg_hi:[0,1]
	v_pk_add_f32 v[126:127], v[122:123], v[120:121]
	v_pk_add_f32 v[66:67], v[122:123], v[120:121] neg_lo:[0,1] neg_hi:[0,1]
	global_load_dwordx2 v[120:121], v[20:21], off
	v_pk_add_f32 v[122:123], v[108:109], v[128:129]
	v_pk_add_f32 v[108:109], v[108:109], v[128:129] neg_lo:[0,1] neg_hi:[0,1]
	v_pk_add_f32 v[128:129], v[110:111], v[124:125]
	v_pk_add_f32 v[72:73], v[110:111], v[124:125] neg_lo:[0,1] neg_hi:[0,1]
	global_load_dwordx2 v[110:111], v[22:23], off
	v_pk_add_f32 v[144:145], v[90:91], v[70:71]
	v_pk_add_f32 v[90:91], v[90:91], v[70:71] op_sel:[1,1] op_sel_hi:[0,0] neg_lo:[0,1] neg_hi:[1,0]
	v_pk_add_f32 v[124:125], v[100:101], v[112:113]
	v_pk_add_f32 v[100:101], v[100:101], v[112:113] neg_lo:[0,1] neg_hi:[0,1]
	v_pk_add_f32 v[112:113], v[102:103], v[106:107]
	v_pk_add_f32 v[70:71], v[102:103], v[106:107] neg_lo:[0,1] neg_hi:[0,1]
	global_load_dwordx2 v[102:103], v[24:25], off
	v_pk_add_f32 v[106:107], v[82:83], v[118:119]
	v_pk_add_f32 v[82:83], v[82:83], v[118:119] neg_lo:[0,1] neg_hi:[0,1]
	v_pk_add_f32 v[118:119], v[114:115], v[130:131]
	v_pk_add_f32 v[114:115], v[114:115], v[130:131] neg_lo:[0,1] neg_hi:[0,1]
	global_load_dwordx2 v[130:131], v[26:27], off
	v_pk_add_f32 v[162:163], v[76:77], v[90:91]
	v_pk_add_f32 v[76:77], v[76:77], v[90:91] neg_lo:[0,1] neg_hi:[0,1]
	v_pk_add_f32 v[90:91], v[146:147], v[150:151]
	v_pk_add_f32 v[146:147], v[146:147], v[150:151] neg_lo:[0,1] neg_hi:[0,1]
	v_pk_add_f32 v[150:151], v[78:79], v[152:153]
	v_pk_add_f32 v[78:79], v[78:79], v[152:153] neg_lo:[0,1] neg_hi:[0,1]
	global_load_dwordx2 v[152:153], v[34:35], off
	s_waitcnt vmcnt(19)
	v_pk_mul_f32 v[166:167], v[156:157], v[134:135] op_sel:[1,1] op_sel_hi:[0,1] neg_lo:[0,1]
	v_pk_add_f32 v[132:133], v[140:141], v[92:93]
	v_pk_fma_f32 v[134:135], v[156:157], v[134:135], v[166:167] op_sel_hi:[1,0,1]
	s_waitcnt vmcnt(18)
	global_load_dwordx2 v[166:167], v[38:39], off
	v_pk_mul_f32 v[156:157], v[106:107], v[136:137] op_sel:[1,1] op_sel_hi:[0,1] neg_lo:[0,1]
	v_pk_add_f32 v[92:93], v[140:141], v[92:93] neg_lo:[0,1] neg_hi:[0,1]
	v_pk_fma_f32 v[106:107], v[106:107], v[136:137], v[156:157] op_sel_hi:[1,0,1]
	s_waitcnt vmcnt(18)
	global_load_dwordx2 v[156:157], v[40:41], off
	v_pk_mul_f32 v[136:137], v[122:123], v[138:139] op_sel:[1,1] op_sel_hi:[0,1] neg_lo:[0,1]
	v_pk_add_f32 v[140:141], v[88:89], v[142:143]
	v_pk_fma_f32 v[122:123], v[122:123], v[138:139], v[136:137] op_sel_hi:[1,0,1]
	global_load_dwordx2 v[136:137], v[42:43], off
	v_pk_add_f32 v[88:89], v[88:89], v[142:143] neg_lo:[0,1] neg_hi:[0,1]
	v_pk_add_f32 v[142:143], v[74:75], v[144:145]
	v_pk_add_f32 v[74:75], v[74:75], v[144:145] neg_lo:[0,1] neg_hi:[0,1]
	global_load_dwordx2 v[144:145], v[30:31], off
	s_mov_b32 s11, s8
	s_waitcnt vmcnt(9)
	v_pk_mul_f32 v[138:139], v[142:143], v[84:85] op_sel:[1,1] op_sel_hi:[0,1] neg_lo:[0,1]
	s_nop 0
	v_pk_fma_f32 v[84:85], v[142:143], v[84:85], v[138:139] op_sel_hi:[1,0,1]
	global_load_dwordx2 v[142:143], v[46:47], off
	v_pk_mul_f32 v[138:139], v[96:97], v[86:87] op_sel:[1,1] op_sel_hi:[0,1] neg_lo:[0,1]
	s_nop 0
	v_pk_fma_f32 v[86:87], v[96:97], v[86:87], v[138:139] op_sel_hi:[1,0,1]
	global_load_dwordx2 v[138:139], v[48:49], off
	v_pk_mul_f32 v[96:97], v[132:133], v[94:95] op_sel:[1,1] op_sel_hi:[0,1] neg_lo:[0,1]
	s_nop 0
	v_pk_fma_f32 v[94:95], v[132:133], v[94:95], v[96:97] op_sel_hi:[1,0,1]
	global_load_dwordx2 v[96:97], v[50:51], off
	v_pk_mul_f32 v[132:133], v[124:125], v[148:149] op_sel:[1,1] op_sel_hi:[0,1] neg_lo:[0,1]
	s_nop 0
	v_pk_fma_f32 v[124:125], v[124:125], v[148:149], v[132:133] op_sel_hi:[1,0,1]
	global_load_dwordx2 v[148:149], v[54:55], off
	v_pk_mul_f32 v[132:133], v[90:91], v[154:155] op_sel:[1,1] op_sel_hi:[0,1] neg_lo:[0,1]
	s_nop 0
	v_pk_fma_f32 v[90:91], v[90:91], v[154:155], v[132:133] op_sel_hi:[1,0,1]
	global_load_dwordx2 v[154:155], v[56:57], off
	v_pk_mul_f32 v[132:133], v[116:117], v[158:159] op_sel:[1,1] op_sel_hi:[0,1] neg_lo:[0,1]
	v_pk_fma_f32 v[116:117], v[116:117], v[158:159], v[132:133] op_sel_hi:[1,0,1]
	global_load_dwordx2 v[132:133], v[58:59], off
	s_waitcnt vmcnt(14)
	v_pk_mul_f32 v[158:159], v[118:119], v[120:121] op_sel:[1,1] op_sel_hi:[0,1] neg_lo:[0,1]
	v_pk_fma_f32 v[118:119], v[118:119], v[120:121], v[158:159] op_sel_hi:[1,0,1]
	s_waitcnt vmcnt(13)
	global_load_dwordx2 v[158:159], v[62:63], off
	v_pk_mul_f32 v[120:121], v[128:129], v[110:111] op_sel:[1,1] op_sel_hi:[0,1] neg_lo:[0,1]
	v_pk_fma_f32 v[110:111], v[128:129], v[110:111], v[120:121] op_sel_hi:[1,0,1]
	global_load_dwordx2 v[128:129], v[64:65], off
	s_waitcnt vmcnt(14)
	v_pk_mul_f32 v[120:121], v[162:163], v[102:103] op_sel:[1,1] op_sel_hi:[0,1] neg_lo:[0,1]
	v_mov_b32 v0, 0
	s_nop 0
	v_pk_fma_f32 v[102:103], v[162:163], v[102:103], v[120:121] op_sel_hi:[1,0,1]
	s_waitcnt vmcnt(13)
	v_pk_mul_f32 v[120:121], v[126:127], v[130:131] op_sel:[1,1] op_sel_hi:[0,1] neg_lo:[0,1]
	v_pk_fma_f32 v[120:121], v[126:127], v[130:131], v[120:121] op_sel_hi:[1,0,1]
	v_pk_mul_f32 v[126:127], v[140:141], v[160:161] op_sel:[1,1] op_sel_hi:[0,1] neg_lo:[0,1]
	v_pk_fma_f32 v[126:127], v[140:141], v[160:161], v[126:127] op_sel_hi:[1,0,1]
	s_waitcnt vmcnt(12)
	v_pk_mul_f32 v[140:141], v[80:81], v[152:153] op_sel:[1,1] op_sel_hi:[0,1] neg_lo:[0,1]
	v_pk_fma_f32 v[80:81], v[80:81], v[152:153], v[140:141] op_sel_hi:[1,0,1]
	v_pk_mul_f32 v[140:141], v[82:83], v[168:169] op_sel:[1,1] op_sel_hi:[0,1] neg_lo:[0,1]
	v_pk_fma_f32 v[82:83], v[82:83], v[168:169], v[140:141] op_sel_hi:[1,0,1]
	s_waitcnt vmcnt(11)
	v_pk_mul_f32 v[140:141], v[108:109], v[166:167] op_sel:[1,1] op_sel_hi:[0,1] neg_lo:[0,1]
	v_pk_fma_f32 v[108:109], v[108:109], v[166:167], v[140:141] op_sel_hi:[1,0,1]
	s_waitcnt vmcnt(10)
	v_pk_mul_f32 v[140:141], v[74:75], v[156:157] op_sel:[1,1] op_sel_hi:[0,1] neg_lo:[0,1]
	v_pk_fma_f32 v[74:75], v[74:75], v[156:157], v[140:141] op_sel_hi:[1,0,1]
	s_waitcnt vmcnt(9)
	v_pk_mul_f32 v[140:141], v[98:99], v[136:137] op_sel:[1,1] op_sel_hi:[0,1] neg_lo:[0,1]
	v_pk_fma_f32 v[98:99], v[98:99], v[136:137], v[140:141] op_sel_hi:[1,0,1]
	v_pk_mul_f32 v[136:137], v[92:93], v[172:173] op_sel:[1,1] op_sel_hi:[0,1] neg_lo:[0,1]
	v_pk_fma_f32 v[92:93], v[92:93], v[172:173], v[136:137] op_sel_hi:[1,0,1]
	s_waitcnt vmcnt(8)
	v_pk_mul_f32 v[130:131], v[112:113], v[144:145] op_sel:[1,1] op_sel_hi:[0,1] neg_lo:[0,1]
	v_pk_fma_f32 v[112:113], v[112:113], v[144:145], v[130:131] op_sel_hi:[1,0,1]
	s_waitcnt vmcnt(7)
	v_pk_mul_f32 v[136:137], v[100:101], v[142:143] op_sel:[1,1] op_sel_hi:[0,1] neg_lo:[0,1]
	v_pk_fma_f32 v[100:101], v[100:101], v[142:143], v[136:137] op_sel_hi:[1,0,1]
	v_xor_b32_e32 v130, 0x80000000, v165
	s_waitcnt vmcnt(6)
	v_pk_mul_f32 v[136:137], v[146:147], v[138:139] op_sel:[1,1] op_sel_hi:[0,1] neg_lo:[0,1]
	v_pk_fma_f32 v[136:137], v[146:147], v[138:139], v[136:137] op_sel_hi:[1,0,1]
	v_mov_b32_e32 v131, v165
	s_waitcnt vmcnt(5)
	v_pk_mul_f32 v[138:139], v[68:69], v[96:97] op_sel:[1,1] op_sel_hi:[0,1] neg_lo:[0,1]
	v_pk_fma_f32 v[68:69], v[68:69], v[96:97], v[138:139] op_sel_hi:[1,0,1]
	v_pk_mul_f32 v[96:97], v[114:115], v[174:175] op_sel:[1,1] op_sel_hi:[0,1] neg_lo:[0,1]
	v_pk_fma_f32 v[96:97], v[114:115], v[174:175], v[96:97] op_sel_hi:[1,0,1]
	s_waitcnt vmcnt(4)
	v_pk_mul_f32 v[114:115], v[72:73], v[148:149] op_sel:[1,1] op_sel_hi:[0,1] neg_lo:[0,1]
	v_pk_fma_f32 v[72:73], v[72:73], v[148:149], v[114:115] op_sel_hi:[1,0,1]
	v_pk_mul_f32 v[130:131], v[150:151], v[130:131] op_sel:[1,0] op_sel_hi:[0,1]
	s_waitcnt vmcnt(3)
	v_pk_mul_f32 v[114:115], v[76:77], v[154:155] op_sel:[1,1] op_sel_hi:[0,1] neg_lo:[0,1]
	v_pk_fma_f32 v[76:77], v[76:77], v[154:155], v[114:115] op_sel_hi:[1,0,1]
	s_waitcnt vmcnt(2)
	v_pk_mul_f32 v[114:115], v[66:67], v[132:133] op_sel:[1,1] op_sel_hi:[0,1] neg_lo:[0,1]
	v_pk_fma_f32 v[66:67], v[66:67], v[132:133], v[114:115] op_sel_hi:[1,0,1]
	v_pk_mul_f32 v[114:115], v[88:89], v[176:177] op_sel:[1,1] op_sel_hi:[0,1] neg_lo:[0,1]
	v_pk_fma_f32 v[88:89], v[88:89], v[176:177], v[114:115] op_sel_hi:[1,0,1]
	s_waitcnt vmcnt(1)
	v_pk_mul_f32 v[114:115], v[70:71], v[158:159] op_sel:[1,1] op_sel_hi:[0,1] neg_lo:[0,1]
	v_pk_fma_f32 v[70:71], v[70:71], v[158:159], v[114:115] op_sel_hi:[1,0,1]
	s_waitcnt vmcnt(0)
	v_pk_mul_f32 v[114:115], v[78:79], v[128:129] op_sel:[1,1] op_sel_hi:[0,1] neg_lo:[0,1]
	v_pk_fma_f32 v[78:79], v[78:79], v[128:129], v[114:115] op_sel_hi:[1,0,1]
	v_pk_add_f32 v[128:129], v[106:107], v[82:83]
	v_pk_add_f32 v[82:83], v[106:107], v[82:83] neg_lo:[0,1] neg_hi:[0,1]
	v_pk_fma_f32 v[130:131], v[150:151], v[164:165], v[130:131] op_sel_hi:[1,0,1]
	v_pk_mul_f32 v[106:107], v[82:83], s[50:51]
	v_pk_add_f32 v[114:115], v[134:135], v[80:81]
	v_pk_fma_f32 v[82:83], v[82:83], s[20:21], v[106:107] op_sel:[0,0,1] op_sel_hi:[1,0,0]
	v_pk_add_f32 v[106:107], v[122:123], v[108:109]
	v_pk_add_f32 v[108:109], v[122:123], v[108:109] neg_lo:[0,1] neg_hi:[0,1]
	s_mov_b32 s21, s34
	v_pk_mul_f32 v[122:123], v[108:109], s[14:15]
	v_pk_add_f32 v[80:81], v[134:135], v[80:81] neg_lo:[0,1] neg_hi:[0,1]
	v_pk_fma_f32 v[108:109], v[108:109], s[6:7], v[122:123] op_sel:[0,0,1] op_sel_hi:[1,0,0]
	v_pk_add_f32 v[122:123], v[84:85], v[74:75]
	v_pk_add_f32 v[74:75], v[84:85], v[74:75] neg_lo:[0,1] neg_hi:[0,1]
	s_mov_b32 s7, s12
	v_pk_mul_f32 v[84:85], v[74:75], s[52:53]
	v_add_u32_e32 v0, v0, v170
	v_pk_fma_f32 v[74:75], v[74:75], s[24:25], v[84:85] op_sel:[0,0,1] op_sel_hi:[1,0,0]
	v_pk_add_f32 v[84:85], v[86:87], v[98:99]
	v_pk_add_f32 v[86:87], v[86:87], v[98:99] neg_lo:[0,1] neg_hi:[0,1]
	s_mov_b32 s25, s26
	v_pk_mul_f32 v[98:99], v[86:87], s[10:11]
	v_lshlrev_b32_e32 v105, 5, v0
	v_pk_fma_f32 v[86:87], v[86:87], s[10:11], v[98:99] op_sel:[0,0,1] op_sel_hi:[1,0,0]
	v_pk_add_f32 v[98:99], v[94:95], v[92:93]
	v_pk_add_f32 v[92:93], v[94:95], v[92:93] neg_lo:[0,1] neg_hi:[0,1]
	s_nop 0
	v_pk_mul_f32 v[94:95], v[92:93], s[24:25]
	s_nop 0
	v_pk_fma_f32 v[92:93], v[92:93], s[0:1], v[94:95] op_sel:[0,0,1] op_sel_hi:[1,0,0]
	v_pk_add_f32 v[94:95], v[124:125], v[100:101]
	v_pk_add_f32 v[100:101], v[124:125], v[100:101] neg_lo:[0,1] neg_hi:[0,1]
	s_nop 0
	v_pk_mul_f32 v[124:125], v[100:101], s[6:7]
	s_nop 0
	v_pk_fma_f32 v[100:101], v[100:101], s[14:15], v[124:125] op_sel:[0,0,1] op_sel_hi:[1,0,0]
	v_pk_add_f32 v[124:125], v[90:91], v[136:137]
	v_pk_add_f32 v[90:91], v[90:91], v[136:137] neg_lo:[0,1] neg_hi:[0,1]
	s_nop 0
	v_pk_mul_f32 v[132:133], v[90:91], s[20:21]
	s_nop 0
	v_pk_fma_f32 v[90:91], v[90:91], s[48:49], v[132:133] op_sel:[0,0,1] op_sel_hi:[1,0,0]
	v_pk_add_f32 v[132:133], v[116:117], v[68:69]
	v_pk_add_f32 v[116:117], v[116:117], v[68:69] op_sel:[1,1] op_sel_hi:[0,0] neg_lo:[1,0] neg_hi:[0,1]
	s_nop 0
	v_pk_add_f32 v[68:69], v[118:119], v[96:97]
	v_pk_add_f32 v[96:97], v[118:119], v[96:97] neg_lo:[0,1] neg_hi:[0,1]
	s_nop 0
	v_pk_mul_f32 v[118:119], v[96:97], s[20:21]
	s_nop 0
	v_pk_fma_f32 v[96:97], v[96:97], s[18:19], v[118:119] op_sel:[0,0,1] op_sel_hi:[1,0,0]
	v_pk_add_f32 v[118:119], v[110:111], v[72:73]
	v_pk_add_f32 v[72:73], v[110:111], v[72:73] neg_lo:[0,1] neg_hi:[0,1]
	s_nop 0
	v_pk_mul_f32 v[110:111], v[72:73], s[6:7]
	s_nop 0
	v_pk_fma_f32 v[72:73], v[72:73], s[4:5], v[110:111] op_sel:[0,0,1] op_sel_hi:[1,0,0]
	v_pk_add_f32 v[110:111], v[102:103], v[76:77]
	v_pk_add_f32 v[76:77], v[102:103], v[76:77] neg_lo:[0,1] neg_hi:[0,1]
	s_nop 0
	v_pk_mul_f32 v[102:103], v[76:77], s[24:25]
	s_nop 0
	v_pk_fma_f32 v[76:77], v[76:77], s[22:23], v[102:103] op_sel:[0,0,1] op_sel_hi:[1,0,0]
	v_pk_add_f32 v[102:103], v[120:121], v[66:67]
	v_pk_add_f32 v[66:67], v[120:121], v[66:67] neg_lo:[0,1] neg_hi:[0,1]
	s_nop 0
	v_pk_mul_f32 v[120:121], v[66:67], s[10:11]
	s_nop 0
	v_pk_fma_f32 v[66:67], v[66:67], s[8:9], v[120:121] op_sel:[0,0,1] op_sel_hi:[1,0,0]
	v_pk_add_f32 v[120:121], v[126:127], v[88:89]
	v_pk_add_f32 v[88:89], v[126:127], v[88:89] neg_lo:[0,1] neg_hi:[0,1]
	s_nop 0
	v_pk_mul_f32 v[126:127], v[88:89], s[52:53]
	s_nop 0
	v_pk_fma_f32 v[88:89], v[88:89], s[26:27], v[126:127] op_sel:[0,0,1] op_sel_hi:[1,0,0]
	v_pk_add_f32 v[126:127], v[112:113], v[70:71]
	v_pk_add_f32 v[70:71], v[112:113], v[70:71] neg_lo:[0,1] neg_hi:[0,1]
	s_nop 0
	v_pk_mul_f32 v[112:113], v[70:71], s[14:15]
	s_nop 0
	v_pk_fma_f32 v[70:71], v[70:71], s[12:13], v[112:113] op_sel:[0,0,1] op_sel_hi:[1,0,0]
	v_pk_add_f32 v[112:113], v[130:131], v[78:79]
	v_pk_add_f32 v[78:79], v[130:131], v[78:79] neg_lo:[0,1] neg_hi:[0,1]
	s_nop 0
	v_pk_mul_f32 v[130:131], v[78:79], s[50:51]
	s_nop 0
	v_pk_fma_f32 v[78:79], v[78:79], s[34:35], v[130:131] op_sel:[0,0,1] op_sel_hi:[1,0,0]
	v_pk_add_f32 v[130:131], v[114:115], v[132:133]
	v_pk_add_f32 v[114:115], v[114:115], v[132:133] neg_lo:[0,1] neg_hi:[0,1]
	v_pk_add_f32 v[132:133], v[128:129], v[68:69]
	v_pk_add_f32 v[68:69], v[128:129], v[68:69] neg_lo:[0,1] neg_hi:[0,1]
	s_nop 0
	v_pk_mul_f32 v[128:129], v[68:69], s[14:15]
	s_nop 0
	v_pk_fma_f32 v[68:69], v[68:69], s[6:7], v[128:129] op_sel:[0,0,1] op_sel_hi:[1,0,0]
	v_pk_add_f32 v[128:129], v[106:107], v[118:119]
	v_pk_add_f32 v[106:107], v[106:107], v[118:119] neg_lo:[0,1] neg_hi:[0,1]
	s_nop 0
	v_pk_mul_f32 v[118:119], v[106:107], s[10:11]
	s_nop 0
	v_pk_fma_f32 v[106:107], v[106:107], s[10:11], v[118:119] op_sel:[0,0,1] op_sel_hi:[1,0,0]
	v_pk_add_f32 v[118:119], v[122:123], v[110:111]
	v_pk_add_f32 v[110:111], v[122:123], v[110:111] neg_lo:[0,1] neg_hi:[0,1]
	s_nop 0
	v_pk_mul_f32 v[122:123], v[110:111], s[6:7]
	s_nop 0
	v_pk_fma_f32 v[110:111], v[110:111], s[14:15], v[122:123] op_sel:[0,0,1] op_sel_hi:[1,0,0]
	v_pk_add_f32 v[122:123], v[84:85], v[102:103]
	v_pk_add_f32 v[102:103], v[84:85], v[102:103] op_sel:[1,1] op_sel_hi:[0,0] neg_lo:[1,0] neg_hi:[0,1]
	s_nop 0
	v_pk_add_f32 v[84:85], v[98:99], v[120:121]
	v_pk_add_f32 v[98:99], v[98:99], v[120:121] neg_lo:[0,1] neg_hi:[0,1]
	s_nop 0
	v_pk_mul_f32 v[120:121], v[98:99], s[6:7]
	s_nop 0
	v_pk_fma_f32 v[98:99], v[98:99], s[4:5], v[120:121] op_sel:[0,0,1] op_sel_hi:[1,0,0]
	v_pk_add_f32 v[120:121], v[94:95], v[126:127]
	v_pk_add_f32 v[94:95], v[94:95], v[126:127] neg_lo:[0,1] neg_hi:[0,1]
	s_nop 0
	v_pk_mul_f32 v[126:127], v[94:95], s[10:11]
	s_nop 0
	v_pk_fma_f32 v[94:95], v[94:95], s[8:9], v[126:127] op_sel:[0,0,1] op_sel_hi:[1,0,0]
	v_pk_add_f32 v[126:127], v[124:125], v[112:113]
	v_pk_add_f32 v[112:113], v[124:125], v[112:113] neg_lo:[0,1] neg_hi:[0,1]
	s_nop 0
	v_pk_mul_f32 v[124:125], v[112:113], s[14:15]
	s_nop 0
	v_pk_fma_f32 v[112:113], v[112:113], s[12:13], v[124:125] op_sel:[0,0,1] op_sel_hi:[1,0,0]
	v_pk_add_f32 v[124:125], v[80:81], v[116:117]
	v_pk_add_f32 v[80:81], v[80:81], v[116:117] neg_lo:[0,1] neg_hi:[0,1]
	v_pk_add_f32 v[116:117], v[82:83], v[96:97]
	v_pk_add_f32 v[82:83], v[82:83], v[96:97] neg_lo:[0,1] neg_hi:[0,1]
	s_nop 0
	v_pk_mul_f32 v[96:97], v[82:83], s[14:15]
	s_nop 0
	v_pk_fma_f32 v[82:83], v[82:83], s[6:7], v[96:97] op_sel:[0,0,1] op_sel_hi:[1,0,0]
	v_pk_add_f32 v[96:97], v[108:109], v[72:73]
	v_pk_add_f32 v[72:73], v[108:109], v[72:73] neg_lo:[0,1] neg_hi:[0,1]
	s_nop 0
	v_pk_mul_f32 v[108:109], v[72:73], s[10:11]
	s_nop 0
	v_pk_fma_f32 v[72:73], v[72:73], s[10:11], v[108:109] op_sel:[0,0,1] op_sel_hi:[1,0,0]
	v_pk_add_f32 v[108:109], v[74:75], v[76:77]
	v_pk_add_f32 v[74:75], v[74:75], v[76:77] neg_lo:[0,1] neg_hi:[0,1]
	s_nop 0
	v_pk_mul_f32 v[76:77], v[74:75], s[6:7]
	s_nop 0
	v_pk_fma_f32 v[74:75], v[74:75], s[14:15], v[76:77] op_sel:[0,0,1] op_sel_hi:[1,0,0]
	v_pk_add_f32 v[76:77], v[86:87], v[66:67]
	v_pk_add_f32 v[86:87], v[86:87], v[66:67] op_sel:[1,1] op_sel_hi:[0,0] neg_lo:[1,0] neg_hi:[0,1]
	s_nop 0
	v_pk_add_f32 v[66:67], v[92:93], v[88:89]
	v_pk_add_f32 v[88:89], v[92:93], v[88:89] neg_lo:[0,1] neg_hi:[0,1]
	s_nop 0
	v_pk_mul_f32 v[92:93], v[88:89], s[6:7]
	s_nop 0
	v_pk_fma_f32 v[88:89], v[88:89], s[4:5], v[92:93] op_sel:[0,0,1] op_sel_hi:[1,0,0]
	v_pk_add_f32 v[92:93], v[100:101], v[70:71]
	v_pk_add_f32 v[70:71], v[100:101], v[70:71] neg_lo:[0,1] neg_hi:[0,1]
	s_nop 0
	v_pk_mul_f32 v[100:101], v[70:71], s[10:11]
	s_nop 0
	v_pk_fma_f32 v[70:71], v[70:71], s[8:9], v[100:101] op_sel:[0,0,1] op_sel_hi:[1,0,0]
	v_pk_add_f32 v[100:101], v[90:91], v[78:79]
	v_pk_add_f32 v[78:79], v[90:91], v[78:79] neg_lo:[0,1] neg_hi:[0,1]
	s_nop 0
	v_pk_mul_f32 v[90:91], v[78:79], s[14:15]
	s_nop 0
	v_pk_fma_f32 v[78:79], v[78:79], s[12:13], v[90:91] op_sel:[0,0,1] op_sel_hi:[1,0,0]
	v_pk_add_f32 v[90:91], v[130:131], v[122:123]
	v_pk_add_f32 v[122:123], v[130:131], v[122:123] neg_lo:[0,1] neg_hi:[0,1]
	v_pk_add_f32 v[130:131], v[132:133], v[84:85]
	v_pk_add_f32 v[84:85], v[132:133], v[84:85] neg_lo:[0,1] neg_hi:[0,1]
	s_nop 0
	v_pk_mul_f32 v[132:133], v[84:85], s[10:11]
	s_nop 0
	v_pk_fma_f32 v[84:85], v[84:85], s[10:11], v[132:133] op_sel:[0,0,1] op_sel_hi:[1,0,0]
	v_pk_add_f32 v[132:133], v[128:129], v[120:121]
	v_pk_add_f32 v[128:129], v[128:129], v[120:121] op_sel:[1,1] op_sel_hi:[0,0] neg_lo:[1,0] neg_hi:[0,1]
	s_nop 0
	v_pk_add_f32 v[120:121], v[118:119], v[126:127]
	v_pk_add_f32 v[118:119], v[118:119], v[126:127] neg_lo:[0,1] neg_hi:[0,1]
	s_nop 0
	v_pk_mul_f32 v[126:127], v[118:119], s[10:11]
	s_nop 0
	v_pk_fma_f32 v[118:119], v[118:119], s[8:9], v[126:127] op_sel:[0,0,1] op_sel_hi:[1,0,0]
	v_pk_add_f32 v[126:127], v[114:115], v[102:103]
	v_pk_add_f32 v[102:103], v[114:115], v[102:103] neg_lo:[0,1] neg_hi:[0,1]
	v_pk_add_f32 v[114:115], v[68:69], v[98:99]
	v_pk_add_f32 v[68:69], v[68:69], v[98:99] neg_lo:[0,1] neg_hi:[0,1]
	s_nop 0
	v_pk_mul_f32 v[98:99], v[68:69], s[10:11]
	s_nop 0
	v_pk_fma_f32 v[68:69], v[68:69], s[10:11], v[98:99] op_sel:[0,0,1] op_sel_hi:[1,0,0]
	v_pk_add_f32 v[98:99], v[106:107], v[94:95]
	v_pk_add_f32 v[106:107], v[106:107], v[94:95] op_sel:[1,1] op_sel_hi:[0,0] neg_lo:[1,0] neg_hi:[0,1]
	s_nop 0
	v_pk_add_f32 v[94:95], v[110:111], v[112:113]
	v_pk_add_f32 v[110:111], v[110:111], v[112:113] neg_lo:[0,1] neg_hi:[0,1]
	s_nop 0
	v_pk_mul_f32 v[112:113], v[110:111], s[10:11]
	s_nop 0
	v_pk_fma_f32 v[110:111], v[110:111], s[8:9], v[112:113] op_sel:[0,0,1] op_sel_hi:[1,0,0]
	v_pk_add_f32 v[112:113], v[124:125], v[76:77]
	v_pk_add_f32 v[76:77], v[124:125], v[76:77] neg_lo:[0,1] neg_hi:[0,1]
	v_pk_add_f32 v[124:125], v[116:117], v[66:67]
	v_pk_add_f32 v[66:67], v[116:117], v[66:67] neg_lo:[0,1] neg_hi:[0,1]
	s_nop 0
	v_pk_mul_f32 v[116:117], v[66:67], s[10:11]
	s_nop 0
	v_pk_fma_f32 v[66:67], v[66:67], s[10:11], v[116:117] op_sel:[0,0,1] op_sel_hi:[1,0,0]
	v_pk_add_f32 v[116:117], v[96:97], v[92:93]
	v_pk_add_f32 v[96:97], v[96:97], v[92:93] op_sel:[1,1] op_sel_hi:[0,0] neg_lo:[1,0] neg_hi:[0,1]
	v_pk_add_f32 v[134:135], v[112:113], v[116:117]
	v_pk_add_f32 v[92:93], v[108:109], v[100:101]
	v_pk_add_f32 v[100:101], v[108:109], v[100:101] neg_lo:[0,1] neg_hi:[0,1]
	v_pk_add_f32 v[112:113], v[112:113], v[116:117] neg_lo:[0,1] neg_hi:[0,1]
	v_pk_mul_f32 v[108:109], v[100:101], s[10:11]
	v_pk_add_f32 v[116:117], v[124:125], v[92:93]
	v_pk_fma_f32 v[100:101], v[100:101], s[8:9], v[108:109] op_sel:[0,0,1] op_sel_hi:[1,0,0]
	v_pk_add_f32 v[108:109], v[80:81], v[86:87]
	v_pk_add_f32 v[80:81], v[80:81], v[86:87] neg_lo:[0,1] neg_hi:[0,1]
	v_pk_add_f32 v[86:87], v[82:83], v[88:89]
	v_pk_add_f32 v[82:83], v[82:83], v[88:89] neg_lo:[0,1] neg_hi:[0,1]
	s_nop 0
	v_pk_mul_f32 v[88:89], v[82:83], s[10:11]
	s_nop 0
	v_pk_fma_f32 v[82:83], v[82:83], s[10:11], v[88:89] op_sel:[0,0,1] op_sel_hi:[1,0,0]
	v_pk_add_f32 v[88:89], v[72:73], v[70:71]
	v_pk_add_f32 v[72:73], v[72:73], v[70:71] op_sel:[1,1] op_sel_hi:[0,0] neg_lo:[1,0] neg_hi:[0,1]
	v_pk_add_f32 v[136:137], v[108:109], v[88:89]
	v_pk_add_f32 v[70:71], v[74:75], v[78:79]
	v_pk_add_f32 v[74:75], v[74:75], v[78:79] neg_lo:[0,1] neg_hi:[0,1]
	v_pk_add_f32 v[88:89], v[108:109], v[88:89] neg_lo:[0,1] neg_hi:[0,1]
	v_pk_mul_f32 v[78:79], v[74:75], s[10:11]
	v_pk_add_f32 v[108:109], v[86:87], v[70:71]
	v_pk_fma_f32 v[74:75], v[74:75], s[8:9], v[78:79] op_sel:[0,0,1] op_sel_hi:[1,0,0]
	v_pk_add_f32 v[78:79], v[90:91], v[132:133]
	v_pk_add_f32 v[90:91], v[90:91], v[132:133] neg_lo:[0,1] neg_hi:[0,1]
	v_pk_add_f32 v[132:133], v[130:131], v[120:121]
	v_pk_add_f32 v[130:131], v[130:131], v[120:121] op_sel:[1,1] op_sel_hi:[0,0] neg_lo:[1,0] neg_hi:[0,1]
	v_pk_add_f32 v[138:139], v[80:81], v[72:73] neg_lo:[0,1] neg_hi:[0,1]
	v_pk_add_f32 v[120:121], v[122:123], v[128:129]
	v_pk_add_f32 v[122:123], v[122:123], v[128:129] neg_lo:[0,1] neg_hi:[0,1]
	v_pk_add_f32 v[128:129], v[84:85], v[118:119]
	v_pk_add_f32 v[118:119], v[84:85], v[118:119] op_sel:[1,1] op_sel_hi:[0,0] neg_lo:[1,0] neg_hi:[0,1]
	v_pk_add_f32 v[140:141], v[82:83], v[74:75]
	v_pk_add_f32 v[84:85], v[126:127], v[98:99]
	v_pk_add_f32 v[98:99], v[126:127], v[98:99] neg_lo:[0,1] neg_hi:[0,1]
	v_pk_add_f32 v[126:127], v[114:115], v[94:95]
	v_pk_add_f32 v[114:115], v[114:115], v[94:95] op_sel:[1,1] op_sel_hi:[0,0] neg_lo:[1,0] neg_hi:[0,1]
	v_pk_add_f32 v[142:143], v[78:79], v[132:133]
	v_pk_add_f32 v[94:95], v[102:103], v[106:107]
	v_pk_add_f32 v[102:103], v[102:103], v[106:107] neg_lo:[0,1] neg_hi:[0,1]
	v_pk_add_f32 v[106:107], v[68:69], v[110:111]
	v_pk_add_f32 v[110:111], v[68:69], v[110:111] op_sel:[1,1] op_sel_hi:[0,0] neg_lo:[1,0] neg_hi:[0,1]
	v_pk_add_f32 v[132:133], v[78:79], v[132:133] neg_lo:[0,1] neg_hi:[0,1]
	v_pk_add_f32 v[92:93], v[124:125], v[92:93] op_sel:[1,1] op_sel_hi:[0,0] neg_lo:[1,0] neg_hi:[0,1]
	v_pk_add_f32 v[124:125], v[76:77], v[96:97]
	v_pk_add_f32 v[76:77], v[76:77], v[96:97] neg_lo:[0,1] neg_hi:[0,1]
	v_pk_add_f32 v[96:97], v[66:67], v[100:101]
	v_pk_add_f32 v[100:101], v[66:67], v[100:101] op_sel:[1,1] op_sel_hi:[0,0] neg_lo:[1,0] neg_hi:[0,1]
	v_pk_add_f32 v[70:71], v[86:87], v[70:71] op_sel:[1,1] op_sel_hi:[0,0] neg_lo:[1,0] neg_hi:[0,1]
	v_pk_add_f32 v[74:75], v[82:83], v[74:75] op_sel:[1,1] op_sel_hi:[0,0] neg_lo:[1,0] neg_hi:[0,1]
	v_pk_add_f32 v[86:87], v[80:81], v[72:73]
	v_pk_add_f32 v[144:145], v[90:91], v[130:131]
	v_pk_add_f32 v[82:83], v[90:91], v[130:131] neg_lo:[0,1] neg_hi:[0,1]
	v_pk_add_f32 v[90:91], v[120:121], v[128:129]
	v_pk_add_f32 v[120:121], v[120:121], v[128:129] neg_lo:[0,1] neg_hi:[0,1]
	v_pk_add_f32 v[128:129], v[122:123], v[118:119]
	v_pk_add_f32 v[68:69], v[122:123], v[118:119] neg_lo:[0,1] neg_hi:[0,1]
	v_pk_add_f32 v[118:119], v[84:85], v[126:127]
	v_pk_add_f32 v[122:123], v[84:85], v[126:127] neg_lo:[0,1] neg_hi:[0,1]
	v_pk_add_f32 v[126:127], v[98:99], v[114:115]
	v_pk_add_f32 v[78:79], v[98:99], v[114:115] neg_lo:[0,1] neg_hi:[0,1]
	v_pk_add_f32 v[98:99], v[94:95], v[106:107]
	v_pk_add_f32 v[94:95], v[94:95], v[106:107] neg_lo:[0,1] neg_hi:[0,1]
	v_pk_add_f32 v[106:107], v[102:103], v[110:111]
	v_pk_add_f32 v[66:67], v[102:103], v[110:111] neg_lo:[0,1] neg_hi:[0,1]
	v_pk_add_f32 v[102:103], v[134:135], v[116:117]
	v_pk_add_f32 v[110:111], v[134:135], v[116:117] neg_lo:[0,1] neg_hi:[0,1]
	v_pk_add_f32 v[116:117], v[88:89], v[70:71]
	v_pk_add_f32 v[80:81], v[88:89], v[70:71] neg_lo:[0,1] neg_hi:[0,1]
	v_lshlrev_b32_e32 v70, 4, v0
	v_and_b32_e32 v70, 0x1f0, v70
	v_pk_add_f32 v[114:115], v[112:113], v[92:93]
	v_pk_add_f32 v[84:85], v[112:113], v[92:93] neg_lo:[0,1] neg_hi:[0,1]
	v_pk_add_f32 v[112:113], v[76:77], v[100:101]
	v_pk_add_f32 v[72:73], v[76:77], v[100:101] neg_lo:[0,1] neg_hi:[0,1]
	v_cvt_f32_u32_e32 v76, v70
	v_pk_add_f32 v[92:93], v[124:125], v[96:97]
	v_pk_add_f32 v[96:97], v[124:125], v[96:97] neg_lo:[0,1] neg_hi:[0,1]
	v_pk_add_f32 v[124:125], v[138:139], v[74:75]
	v_mul_f32_e32 v76, 0x38800000, v76
	v_pk_add_f32 v[70:71], v[138:139], v[74:75] neg_lo:[0,1] neg_hi:[0,1]
	v_sin_f32_e32 v75, v76
	v_ashrrev_i32_e32 v74, 2, v105
	v_lshlrev_b32_e32 v0, 8, v0
	v_add3_u32 v0, 0, v74, v0
	v_cos_f32_e32 v74, v76
	v_xor_b32_e32 v76, 0x80000000, v75
	v_mov_b32_e32 v77, v75
	v_pk_mul_f32 v[130:131], v[76:77], v[102:103] op_sel:[0,1] op_sel_hi:[1,0]
	v_pk_add_f32 v[100:101], v[136:137], v[108:109]
	v_pk_fma_f32 v[102:103], v[102:103], v[74:75], v[130:131] op_sel_hi:[1,0,1]
	ds_write2_b64 v0, v[142:143], v[102:103] offset1:1
	v_pk_mul_f32 v[102:103], v[76:77], v[74:75] op_sel:[0,1] op_sel_hi:[1,0]
	v_pk_add_f32 v[88:89], v[86:87], v[140:141]
	v_pk_fma_f32 v[102:103], v[74:75], v[74:75], v[102:103] op_sel_hi:[1,0,1]
	v_pk_add_f32 v[108:109], v[136:137], v[108:109] neg_lo:[0,1] neg_hi:[0,1]
	v_pk_mul_f32 v[130:131], v[118:119], v[102:103] op_sel:[1,1] op_sel_hi:[0,1] neg_lo:[0,1]
	v_pk_fma_f32 v[118:119], v[118:119], v[102:103], v[130:131] op_sel_hi:[1,0,1]
	v_pk_mul_f32 v[130:131], v[76:77], v[102:103] op_sel:[0,1] op_sel_hi:[1,0]
	v_pk_add_f32 v[86:87], v[86:87], v[140:141] neg_lo:[0,1] neg_hi:[0,1]
	v_pk_fma_f32 v[102:103], v[102:103], v[74:75], v[130:131] op_sel_hi:[1,0,1]
	s_nop 0
	v_pk_mul_f32 v[130:131], v[100:101], v[102:103] op_sel:[1,1] op_sel_hi:[0,1] neg_lo:[0,1]
	v_pk_fma_f32 v[100:101], v[100:101], v[102:103], v[130:131] op_sel_hi:[1,0,1]
	ds_write2_b64 v0, v[118:119], v[100:101] offset0:2 offset1:3
	v_pk_mul_f32 v[100:101], v[76:77], v[102:103] op_sel:[0,1] op_sel_hi:[1,0]
	s_nop 0
	v_pk_fma_f32 v[100:101], v[102:103], v[74:75], v[100:101] op_sel_hi:[1,0,1]
	s_nop 0
	v_pk_mul_f32 v[102:103], v[90:91], v[100:101] op_sel:[1,1] op_sel_hi:[0,1] neg_lo:[0,1]
	v_pk_fma_f32 v[90:91], v[90:91], v[100:101], v[102:103] op_sel_hi:[1,0,1]
	v_pk_mul_f32 v[102:103], v[76:77], v[100:101] op_sel:[0,1] op_sel_hi:[1,0]
	s_nop 0
	v_pk_fma_f32 v[100:101], v[100:101], v[74:75], v[102:103] op_sel_hi:[1,0,1]
	s_nop 0
	v_pk_mul_f32 v[102:103], v[92:93], v[100:101] op_sel:[1,1] op_sel_hi:[0,1] neg_lo:[0,1]
	v_pk_fma_f32 v[92:93], v[92:93], v[100:101], v[102:103] op_sel_hi:[1,0,1]
	ds_write2_b64 v0, v[90:91], v[92:93] offset0:4 offset1:5
	v_pk_mul_f32 v[90:91], v[76:77], v[100:101] op_sel:[0,1] op_sel_hi:[1,0]
	s_nop 0
	v_pk_fma_f32 v[90:91], v[100:101], v[74:75], v[90:91] op_sel_hi:[1,0,1]
	s_nop 0
	v_pk_mul_f32 v[92:93], v[98:99], v[90:91] op_sel:[1,1] op_sel_hi:[0,1] neg_lo:[0,1]
	v_pk_fma_f32 v[92:93], v[98:99], v[90:91], v[92:93] op_sel_hi:[1,0,1]
	v_pk_mul_f32 v[98:99], v[76:77], v[90:91] op_sel:[0,1] op_sel_hi:[1,0]
	s_nop 0
	v_pk_fma_f32 v[90:91], v[90:91], v[74:75], v[98:99] op_sel_hi:[1,0,1]
	s_nop 0
	v_pk_mul_f32 v[98:99], v[88:89], v[90:91] op_sel:[1,1] op_sel_hi:[0,1] neg_lo:[0,1]
	v_pk_fma_f32 v[88:89], v[88:89], v[90:91], v[98:99] op_sel_hi:[1,0,1]
	ds_write2_b64 v0, v[92:93], v[88:89] offset0:6 offset1:7
	v_pk_mul_f32 v[88:89], v[76:77], v[90:91] op_sel:[0,1] op_sel_hi:[1,0]
	s_nop 0
	v_pk_fma_f32 v[88:89], v[90:91], v[74:75], v[88:89] op_sel_hi:[1,0,1]
	s_nop 0
	v_pk_mul_f32 v[90:91], v[144:145], v[88:89] op_sel:[1,1] op_sel_hi:[0,1] neg_lo:[0,1]
	v_pk_mul_f32 v[92:93], v[76:77], v[88:89] op_sel:[0,1] op_sel_hi:[1,0]
	v_pk_fma_f32 v[90:91], v[144:145], v[88:89], v[90:91] op_sel_hi:[1,0,1]
	v_pk_fma_f32 v[88:89], v[88:89], v[74:75], v[92:93] op_sel_hi:[1,0,1]
	s_nop 0
	v_pk_mul_f32 v[92:93], v[114:115], v[88:89] op_sel:[1,1] op_sel_hi:[0,1] neg_lo:[0,1]
	v_pk_fma_f32 v[92:93], v[114:115], v[88:89], v[92:93] op_sel_hi:[1,0,1]
	ds_write2_b64 v0, v[90:91], v[92:93] offset0:8 offset1:9
	v_pk_mul_f32 v[90:91], v[76:77], v[88:89] op_sel:[0,1] op_sel_hi:[1,0]
	s_nop 0
	v_pk_fma_f32 v[88:89], v[88:89], v[74:75], v[90:91] op_sel_hi:[1,0,1]
	s_nop 0
	v_pk_mul_f32 v[90:91], v[126:127], v[88:89] op_sel:[1,1] op_sel_hi:[0,1] neg_lo:[0,1]
	v_pk_mul_f32 v[92:93], v[76:77], v[88:89] op_sel:[0,1] op_sel_hi:[1,0]
	v_pk_fma_f32 v[90:91], v[126:127], v[88:89], v[90:91] op_sel_hi:[1,0,1]
	v_pk_fma_f32 v[88:89], v[88:89], v[74:75], v[92:93] op_sel_hi:[1,0,1]
	s_nop 0
	v_pk_mul_f32 v[92:93], v[116:117], v[88:89] op_sel:[1,1] op_sel_hi:[0,1] neg_lo:[0,1]
	v_pk_fma_f32 v[92:93], v[116:117], v[88:89], v[92:93] op_sel_hi:[1,0,1]
	ds_write2_b64 v0, v[90:91], v[92:93] offset0:10 offset1:11
	v_pk_mul_f32 v[90:91], v[76:77], v[88:89] op_sel:[0,1] op_sel_hi:[1,0]
	s_nop 0
	v_pk_fma_f32 v[88:89], v[88:89], v[74:75], v[90:91] op_sel_hi:[1,0,1]
	s_nop 0
	v_pk_mul_f32 v[90:91], v[128:129], v[88:89] op_sel:[1,1] op_sel_hi:[0,1] neg_lo:[0,1]
	v_pk_mul_f32 v[92:93], v[76:77], v[88:89] op_sel:[0,1] op_sel_hi:[1,0]
	v_pk_fma_f32 v[90:91], v[128:129], v[88:89], v[90:91] op_sel_hi:[1,0,1]
	v_pk_fma_f32 v[88:89], v[88:89], v[74:75], v[92:93] op_sel_hi:[1,0,1]
	s_nop 0
	v_pk_mul_f32 v[92:93], v[112:113], v[88:89] op_sel:[1,1] op_sel_hi:[0,1] neg_lo:[0,1]
	v_pk_fma_f32 v[92:93], v[112:113], v[88:89], v[92:93] op_sel_hi:[1,0,1]
	ds_write2_b64 v0, v[90:91], v[92:93] offset0:12 offset1:13
	v_pk_mul_f32 v[90:91], v[76:77], v[88:89] op_sel:[0,1] op_sel_hi:[1,0]
	s_nop 0
	v_pk_fma_f32 v[88:89], v[88:89], v[74:75], v[90:91] op_sel_hi:[1,0,1]
	s_nop 0
	v_pk_mul_f32 v[90:91], v[106:107], v[88:89] op_sel:[1,1] op_sel_hi:[0,1] neg_lo:[0,1]
	v_pk_mul_f32 v[92:93], v[76:77], v[88:89] op_sel:[0,1] op_sel_hi:[1,0]
	v_pk_fma_f32 v[90:91], v[106:107], v[88:89], v[90:91] op_sel_hi:[1,0,1]
	v_pk_fma_f32 v[88:89], v[88:89], v[74:75], v[92:93] op_sel_hi:[1,0,1]
	s_nop 0
	v_pk_mul_f32 v[92:93], v[124:125], v[88:89] op_sel:[1,1] op_sel_hi:[0,1] neg_lo:[0,1]
	v_pk_fma_f32 v[92:93], v[124:125], v[88:89], v[92:93] op_sel_hi:[1,0,1]
	ds_write2_b64 v0, v[90:91], v[92:93] offset0:14 offset1:15
	v_pk_mul_f32 v[90:91], v[76:77], v[88:89] op_sel:[0,1] op_sel_hi:[1,0]
	s_nop 0
	v_pk_fma_f32 v[88:89], v[88:89], v[74:75], v[90:91] op_sel_hi:[1,0,1]
	s_nop 0
	v_pk_mul_f32 v[90:91], v[132:133], v[88:89] op_sel:[1,1] op_sel_hi:[0,1] neg_lo:[0,1]
	v_pk_mul_f32 v[92:93], v[76:77], v[88:89] op_sel:[0,1] op_sel_hi:[1,0]
	v_pk_fma_f32 v[90:91], v[132:133], v[88:89], v[90:91] op_sel_hi:[1,0,1]
	v_pk_fma_f32 v[88:89], v[88:89], v[74:75], v[92:93] op_sel_hi:[1,0,1]
	s_nop 0
	v_pk_mul_f32 v[92:93], v[110:111], v[88:89] op_sel:[1,1] op_sel_hi:[0,1] neg_lo:[0,1]
	v_pk_fma_f32 v[92:93], v[110:111], v[88:89], v[92:93] op_sel_hi:[1,0,1]
	ds_write2_b64 v0, v[90:91], v[92:93] offset0:16 offset1:17
	v_pk_mul_f32 v[90:91], v[76:77], v[88:89] op_sel:[0,1] op_sel_hi:[1,0]
	s_nop 0
	v_pk_fma_f32 v[88:89], v[88:89], v[74:75], v[90:91] op_sel_hi:[1,0,1]
	s_nop 0
	v_pk_mul_f32 v[90:91], v[122:123], v[88:89] op_sel:[1,1] op_sel_hi:[0,1] neg_lo:[0,1]
	v_pk_mul_f32 v[92:93], v[76:77], v[88:89] op_sel:[0,1] op_sel_hi:[1,0]
	v_pk_fma_f32 v[90:91], v[122:123], v[88:89], v[90:91] op_sel_hi:[1,0,1]
	v_pk_fma_f32 v[88:89], v[88:89], v[74:75], v[92:93] op_sel_hi:[1,0,1]
	s_nop 0
	v_pk_mul_f32 v[92:93], v[108:109], v[88:89] op_sel:[1,1] op_sel_hi:[0,1] neg_lo:[0,1]
	v_pk_fma_f32 v[92:93], v[108:109], v[88:89], v[92:93] op_sel_hi:[1,0,1]
	ds_write2_b64 v0, v[90:91], v[92:93] offset0:18 offset1:19
	v_pk_mul_f32 v[90:91], v[76:77], v[88:89] op_sel:[0,1] op_sel_hi:[1,0]
	s_nop 0
	v_pk_fma_f32 v[88:89], v[88:89], v[74:75], v[90:91] op_sel_hi:[1,0,1]
	s_nop 0
	v_pk_mul_f32 v[90:91], v[120:121], v[88:89] op_sel:[1,1] op_sel_hi:[0,1] neg_lo:[0,1]
	v_pk_mul_f32 v[92:93], v[76:77], v[88:89] op_sel:[0,1] op_sel_hi:[1,0]
	v_pk_fma_f32 v[90:91], v[120:121], v[88:89], v[90:91] op_sel_hi:[1,0,1]
	v_pk_fma_f32 v[88:89], v[88:89], v[74:75], v[92:93] op_sel_hi:[1,0,1]
	s_nop 0
	v_pk_mul_f32 v[92:93], v[96:97], v[88:89] op_sel:[1,1] op_sel_hi:[0,1] neg_lo:[0,1]
	v_pk_fma_f32 v[92:93], v[96:97], v[88:89], v[92:93] op_sel_hi:[1,0,1]
	ds_write2_b64 v0, v[90:91], v[92:93] offset0:20 offset1:21
	v_pk_mul_f32 v[90:91], v[76:77], v[88:89] op_sel:[0,1] op_sel_hi:[1,0]
	s_nop 0
	v_pk_fma_f32 v[88:89], v[88:89], v[74:75], v[90:91] op_sel_hi:[1,0,1]
	s_nop 0
	v_pk_mul_f32 v[90:91], v[94:95], v[88:89] op_sel:[1,1] op_sel_hi:[0,1] neg_lo:[0,1]
	v_pk_mul_f32 v[92:93], v[76:77], v[88:89] op_sel:[0,1] op_sel_hi:[1,0]
	v_pk_fma_f32 v[90:91], v[94:95], v[88:89], v[90:91] op_sel_hi:[1,0,1]
	v_pk_fma_f32 v[88:89], v[88:89], v[74:75], v[92:93] op_sel_hi:[1,0,1]
	s_nop 0
	v_pk_mul_f32 v[92:93], v[86:87], v[88:89] op_sel:[1,1] op_sel_hi:[0,1] neg_lo:[0,1]
	v_pk_fma_f32 v[86:87], v[86:87], v[88:89], v[92:93] op_sel_hi:[1,0,1]
	ds_write2_b64 v0, v[90:91], v[86:87] offset0:22 offset1:23
	v_pk_mul_f32 v[86:87], v[76:77], v[88:89] op_sel:[0,1] op_sel_hi:[1,0]
	s_nop 0
	v_pk_fma_f32 v[86:87], v[88:89], v[74:75], v[86:87] op_sel_hi:[1,0,1]
	s_nop 0
	v_pk_mul_f32 v[88:89], v[82:83], v[86:87] op_sel:[1,1] op_sel_hi:[0,1] neg_lo:[0,1]
	v_pk_fma_f32 v[82:83], v[82:83], v[86:87], v[88:89] op_sel_hi:[1,0,1]
	v_pk_mul_f32 v[88:89], v[76:77], v[86:87] op_sel:[0,1] op_sel_hi:[1,0]
	s_nop 0
	v_pk_fma_f32 v[86:87], v[86:87], v[74:75], v[88:89] op_sel_hi:[1,0,1]
	s_nop 0
	v_pk_mul_f32 v[88:89], v[84:85], v[86:87] op_sel:[1,1] op_sel_hi:[0,1] neg_lo:[0,1]
	v_pk_fma_f32 v[84:85], v[84:85], v[86:87], v[88:89] op_sel_hi:[1,0,1]
	ds_write2_b64 v0, v[82:83], v[84:85] offset0:24 offset1:25
	v_pk_mul_f32 v[82:83], v[76:77], v[86:87] op_sel:[0,1] op_sel_hi:[1,0]
	s_nop 0
	v_pk_fma_f32 v[82:83], v[86:87], v[74:75], v[82:83] op_sel_hi:[1,0,1]
	s_nop 0
	v_pk_mul_f32 v[84:85], v[78:79], v[82:83] op_sel:[1,1] op_sel_hi:[0,1] neg_lo:[0,1]
	v_pk_fma_f32 v[78:79], v[78:79], v[82:83], v[84:85] op_sel_hi:[1,0,1]
	v_pk_mul_f32 v[84:85], v[76:77], v[82:83] op_sel:[0,1] op_sel_hi:[1,0]
	s_nop 0
	v_pk_fma_f32 v[82:83], v[82:83], v[74:75], v[84:85] op_sel_hi:[1,0,1]
	s_nop 0
	v_pk_mul_f32 v[84:85], v[80:81], v[82:83] op_sel:[1,1] op_sel_hi:[0,1] neg_lo:[0,1]
	v_pk_fma_f32 v[80:81], v[80:81], v[82:83], v[84:85] op_sel_hi:[1,0,1]
	ds_write2_b64 v0, v[78:79], v[80:81] offset0:26 offset1:27
	v_pk_mul_f32 v[78:79], v[76:77], v[82:83] op_sel:[0,1] op_sel_hi:[1,0]
	s_nop 0
	v_pk_fma_f32 v[78:79], v[82:83], v[74:75], v[78:79] op_sel_hi:[1,0,1]
	s_nop 0
	v_pk_mul_f32 v[80:81], v[68:69], v[78:79] op_sel:[1,1] op_sel_hi:[0,1] neg_lo:[0,1]
	v_pk_fma_f32 v[68:69], v[68:69], v[78:79], v[80:81] op_sel_hi:[1,0,1]
	v_pk_mul_f32 v[80:81], v[76:77], v[78:79] op_sel:[0,1] op_sel_hi:[1,0]
	s_nop 0
	v_pk_fma_f32 v[78:79], v[78:79], v[74:75], v[80:81] op_sel_hi:[1,0,1]
	s_nop 0
	v_pk_mul_f32 v[80:81], v[72:73], v[78:79] op_sel:[1,1] op_sel_hi:[0,1] neg_lo:[0,1]
	v_pk_fma_f32 v[72:73], v[72:73], v[78:79], v[80:81] op_sel_hi:[1,0,1]
	ds_write2_b64 v0, v[68:69], v[72:73] offset0:28 offset1:29
	v_pk_mul_f32 v[68:69], v[76:77], v[78:79] op_sel:[0,1] op_sel_hi:[1,0]
	s_nop 0
	v_pk_fma_f32 v[68:69], v[78:79], v[74:75], v[68:69] op_sel_hi:[1,0,1]
	s_nop 0
	v_pk_mul_f32 v[72:73], v[66:67], v[68:69] op_sel:[1,1] op_sel_hi:[0,1] neg_lo:[0,1]
	v_pk_fma_f32 v[66:67], v[66:67], v[68:69], v[72:73] op_sel_hi:[1,0,1]
	v_pk_mul_f32 v[72:73], v[76:77], v[68:69] op_sel:[0,1] op_sel_hi:[1,0]
	s_nop 0
	v_pk_fma_f32 v[68:69], v[68:69], v[74:75], v[72:73] op_sel_hi:[1,0,1]
	s_nop 0
	v_pk_mul_f32 v[72:73], v[70:71], v[68:69] op_sel:[1,1] op_sel_hi:[0,1] neg_lo:[0,1]
	v_pk_fma_f32 v[68:69], v[70:71], v[68:69], v[72:73] op_sel_hi:[1,0,1]
	ds_write2_b64 v0, v[66:67], v[68:69] offset0:30 offset1:31
	s_waitcnt lgkmcnt(0)
	s_barrier
	v_mov_b32 v0, 0
	s_nop 0
	v_add_u32_e32 v71, v0, v170
	v_ashrrev_i32_e32 v105, 5, v71
	v_lshlrev_b32_e32 v0, 10, v105
	v_and_b32_e32 v140, 31, v71
	v_ashrrev_i32_e32 v0, 2, v0
	v_lshlrev_b32_e32 v67, 13, v105
	v_lshlrev_b32_e32 v68, 3, v140
	v_add_u32_e32 v0, 0, v0
	v_lshl_add_u32 v66, v105, 8, 0
	v_add3_u32 v0, v0, v67, v68
	v_add3_u32 v142, v66, v67, v68
	v_add_u32_e32 v143, 0x400, v0
	v_add_u32_e32 v144, 0x800, v0
	v_add_u32_e32 v145, 0xc00, v0
	ds_read_b64 v[130:131], v142
	ds_read2_b64 v[66:69], v0 offset0:33 offset1:66
	ds_read2_b64 v[72:75], v0 offset0:99 offset1:132
	ds_read2_b64 v[76:79], v0 offset0:165 offset1:198
	ds_read2_b64 v[80:83], v143 offset0:103 offset1:136
	ds_read2_b64 v[84:87], v144 offset0:41 offset1:74
	ds_read2_b64 v[88:91], v144 offset0:107 offset1:140
	ds_read2_b64 v[92:95], v144 offset0:173 offset1:206
	ds_read2_b64 v[96:99], v145 offset0:111 offset1:144
	v_add_u32_e32 v146, 0x1000, v0
	ds_read2_b64 v[100:103], v146 offset0:49 offset1:82
	ds_read2_b64 v[106:109], v146 offset0:115 offset1:148
	ds_read2_b64 v[110:113], v146 offset0:181 offset1:214
	v_add_u32_e32 v147, 0x1400, v0
	ds_read2_b64 v[114:117], v147 offset0:119 offset1:152
	s_waitcnt lgkmcnt(4)
	v_pk_add_f32 v[134:135], v[130:131], v[98:99]
	v_pk_add_f32 v[98:99], v[130:131], v[98:99] neg_lo:[0,1] neg_hi:[0,1]
	s_waitcnt lgkmcnt(3)
	v_pk_add_f32 v[130:131], v[66:67], v[100:101]
	v_pk_add_f32 v[66:67], v[66:67], v[100:101] neg_lo:[0,1] neg_hi:[0,1]
	v_add_u32_e32 v70, 0x1800, v0
	v_pk_mul_f32 v[100:101], v[66:67], s[50:51]
	ds_read2_b64 v[118:121], v70 offset0:57 offset1:90
	ds_read2_b64 v[122:125], v70 offset0:123 offset1:156
	ds_read2_b64 v[126:129], v70 offset0:189 offset1:222
	ds_read_b64 v[132:133], v0 offset:8184
	v_pk_fma_f32 v[66:67], v[66:67], s[20:21], v[100:101] op_sel:[0,0,1] op_sel_hi:[1,0,0]
	v_pk_add_f32 v[100:101], v[68:69], v[102:103]
	v_pk_add_f32 v[68:69], v[68:69], v[102:103] neg_lo:[0,1] neg_hi:[0,1]
	v_mul_lo_u32 v105, v140, v105
	v_pk_mul_f32 v[102:103], v[68:69], s[14:15]
	v_cvt_f32_i32_e32 v105, v105
	v_pk_fma_f32 v[68:69], v[68:69], s[6:7], v[102:103] op_sel:[0,0,1] op_sel_hi:[1,0,0]
	s_waitcnt lgkmcnt(6)
	v_pk_add_f32 v[102:103], v[72:73], v[106:107]
	v_pk_add_f32 v[72:73], v[72:73], v[106:107] neg_lo:[0,1] neg_hi:[0,1]
	v_and_b32_e32 v71, 0xffffffe0, v71
	v_pk_mul_f32 v[106:107], v[72:73], s[52:53]
	v_cvt_f32_i32_e32 v71, v71
	v_pk_fma_f32 v[72:73], v[72:73], s[24:25], v[106:107] op_sel:[0,0,1] op_sel_hi:[1,0,0]
	v_pk_add_f32 v[106:107], v[74:75], v[108:109]
	v_pk_add_f32 v[74:75], v[74:75], v[108:109] neg_lo:[0,1] neg_hi:[0,1]
	v_mul_f32_e32 v71, 0x38800000, v71
	v_pk_mul_f32 v[108:109], v[74:75], s[10:11]
	s_nop 0
	v_pk_fma_f32 v[74:75], v[74:75], s[10:11], v[108:109] op_sel:[0,0,1] op_sel_hi:[1,0,0]
	s_waitcnt lgkmcnt(5)
	v_pk_add_f32 v[108:109], v[76:77], v[110:111]
	v_pk_add_f32 v[76:77], v[76:77], v[110:111] neg_lo:[0,1] neg_hi:[0,1]
	s_nop 0
	v_pk_mul_f32 v[110:111], v[76:77], s[24:25]
	s_nop 0
	v_pk_fma_f32 v[76:77], v[76:77], s[0:1], v[110:111] op_sel:[0,0,1] op_sel_hi:[1,0,0]
	v_pk_add_f32 v[110:111], v[78:79], v[112:113]
	v_pk_add_f32 v[78:79], v[78:79], v[112:113] neg_lo:[0,1] neg_hi:[0,1]
	s_nop 0
	v_pk_mul_f32 v[112:113], v[78:79], s[6:7]
	s_nop 0
	v_pk_fma_f32 v[78:79], v[78:79], s[14:15], v[112:113] op_sel:[0,0,1] op_sel_hi:[1,0,0]
	s_waitcnt lgkmcnt(4)
	v_pk_add_f32 v[112:113], v[80:81], v[114:115]
	v_pk_add_f32 v[80:81], v[80:81], v[114:115] neg_lo:[0,1] neg_hi:[0,1]
	s_nop 0
	v_pk_mul_f32 v[114:115], v[80:81], s[20:21]
	s_nop 0
	v_pk_fma_f32 v[80:81], v[80:81], s[48:49], v[114:115] op_sel:[0,0,1] op_sel_hi:[1,0,0]
	v_pk_add_f32 v[114:115], v[82:83], v[116:117]
	v_pk_add_f32 v[116:117], v[82:83], v[116:117] op_sel:[1,1] op_sel_hi:[0,0] neg_lo:[1,0] neg_hi:[0,1]
	s_mov_b64 s[48:49], -1
	s_waitcnt lgkmcnt(3)
	v_pk_add_f32 v[82:83], v[84:85], v[118:119]
	v_pk_add_f32 v[84:85], v[84:85], v[118:119] neg_lo:[0,1] neg_hi:[0,1]
	s_nop 0
	v_pk_mul_f32 v[118:119], v[84:85], s[20:21]
	s_nop 0
	v_pk_fma_f32 v[84:85], v[84:85], s[18:19], v[118:119] op_sel:[0,0,1] op_sel_hi:[1,0,0]
	v_pk_add_f32 v[118:119], v[86:87], v[120:121]
	v_pk_add_f32 v[86:87], v[86:87], v[120:121] neg_lo:[0,1] neg_hi:[0,1]
	s_nop 0
	v_pk_mul_f32 v[120:121], v[86:87], s[6:7]
	s_nop 0
	v_pk_fma_f32 v[86:87], v[86:87], s[4:5], v[120:121] op_sel:[0,0,1] op_sel_hi:[1,0,0]
	s_waitcnt lgkmcnt(2)
	v_pk_add_f32 v[120:121], v[88:89], v[122:123]
	v_pk_add_f32 v[88:89], v[88:89], v[122:123] neg_lo:[0,1] neg_hi:[0,1]
	s_nop 0
	v_pk_mul_f32 v[122:123], v[88:89], s[24:25]
	s_nop 0
	v_pk_fma_f32 v[88:89], v[88:89], s[22:23], v[122:123] op_sel:[0,0,1] op_sel_hi:[1,0,0]
	v_pk_add_f32 v[122:123], v[90:91], v[124:125]
	v_pk_add_f32 v[90:91], v[90:91], v[124:125] neg_lo:[0,1] neg_hi:[0,1]
	s_nop 0
	v_pk_mul_f32 v[124:125], v[90:91], s[10:11]
	s_nop 0
	v_pk_fma_f32 v[90:91], v[90:91], s[8:9], v[124:125] op_sel:[0,0,1] op_sel_hi:[1,0,0]
	s_waitcnt lgkmcnt(1)
	v_pk_add_f32 v[124:125], v[92:93], v[126:127]
	v_pk_add_f32 v[92:93], v[92:93], v[126:127] neg_lo:[0,1] neg_hi:[0,1]
	s_nop 0
	v_pk_mul_f32 v[126:127], v[92:93], s[52:53]
	s_nop 0
	v_pk_fma_f32 v[92:93], v[92:93], s[26:27], v[126:127] op_sel:[0,0,1] op_sel_hi:[1,0,0]
	v_pk_add_f32 v[126:127], v[94:95], v[128:129]
	v_pk_add_f32 v[94:95], v[94:95], v[128:129] neg_lo:[0,1] neg_hi:[0,1]
	s_nop 0
	v_pk_mul_f32 v[128:129], v[94:95], s[14:15]
	s_nop 0
	v_pk_fma_f32 v[94:95], v[94:95], s[12:13], v[128:129] op_sel:[0,0,1] op_sel_hi:[1,0,0]
	s_waitcnt lgkmcnt(0)
	v_pk_add_f32 v[128:129], v[96:97], v[132:133]
	v_pk_add_f32 v[96:97], v[96:97], v[132:133] neg_lo:[0,1] neg_hi:[0,1]
	s_nop 0
	v_pk_mul_f32 v[132:133], v[96:97], s[50:51]
	s_nop 0
	v_pk_fma_f32 v[96:97], v[96:97], s[34:35], v[132:133] op_sel:[0,0,1] op_sel_hi:[1,0,0]
	v_pk_add_f32 v[132:133], v[134:135], v[114:115]
	v_pk_add_f32 v[114:115], v[134:135], v[114:115] neg_lo:[0,1] neg_hi:[0,1]
	v_pk_add_f32 v[134:135], v[130:131], v[82:83]
	v_pk_add_f32 v[82:83], v[130:131], v[82:83] neg_lo:[0,1] neg_hi:[0,1]
	s_nop 0
	v_pk_mul_f32 v[130:131], v[82:83], s[14:15]
	s_nop 0
	v_pk_fma_f32 v[82:83], v[82:83], s[6:7], v[130:131] op_sel:[0,0,1] op_sel_hi:[1,0,0]
	v_pk_add_f32 v[130:131], v[100:101], v[118:119]
	v_pk_add_f32 v[100:101], v[100:101], v[118:119] neg_lo:[0,1] neg_hi:[0,1]
	s_nop 0
	v_pk_mul_f32 v[118:119], v[100:101], s[10:11]
	s_nop 0
	v_pk_fma_f32 v[100:101], v[100:101], s[10:11], v[118:119] op_sel:[0,0,1] op_sel_hi:[1,0,0]
	v_pk_add_f32 v[118:119], v[102:103], v[120:121]
	v_pk_add_f32 v[102:103], v[102:103], v[120:121] neg_lo:[0,1] neg_hi:[0,1]
	s_nop 0
	v_pk_mul_f32 v[120:121], v[102:103], s[6:7]
	s_nop 0
	v_pk_fma_f32 v[102:103], v[102:103], s[14:15], v[120:121] op_sel:[0,0,1] op_sel_hi:[1,0,0]
	v_pk_add_f32 v[120:121], v[106:107], v[122:123]
	v_pk_add_f32 v[122:123], v[106:107], v[122:123] op_sel:[1,1] op_sel_hi:[0,0] neg_lo:[1,0] neg_hi:[0,1]
	s_nop 0
	v_pk_add_f32 v[106:107], v[108:109], v[124:125]
	v_pk_add_f32 v[108:109], v[108:109], v[124:125] neg_lo:[0,1] neg_hi:[0,1]
	s_nop 0
	v_pk_mul_f32 v[124:125], v[108:109], s[6:7]
	s_nop 0
	v_pk_fma_f32 v[108:109], v[108:109], s[4:5], v[124:125] op_sel:[0,0,1] op_sel_hi:[1,0,0]
	v_pk_add_f32 v[124:125], v[110:111], v[126:127]
	v_pk_add_f32 v[110:111], v[110:111], v[126:127] neg_lo:[0,1] neg_hi:[0,1]
	s_nop 0
	v_pk_mul_f32 v[126:127], v[110:111], s[10:11]
	s_nop 0
	v_pk_fma_f32 v[110:111], v[110:111], s[8:9], v[126:127] op_sel:[0,0,1] op_sel_hi:[1,0,0]
	v_pk_add_f32 v[126:127], v[112:113], v[128:129]
	v_pk_add_f32 v[112:113], v[112:113], v[128:129] neg_lo:[0,1] neg_hi:[0,1]
	s_nop 0
	v_pk_mul_f32 v[128:129], v[112:113], s[14:15]
	s_nop 0
	v_pk_fma_f32 v[112:113], v[112:113], s[12:13], v[128:129] op_sel:[0,0,1] op_sel_hi:[1,0,0]
	v_pk_add_f32 v[128:129], v[98:99], v[116:117]
	v_pk_add_f32 v[98:99], v[98:99], v[116:117] neg_lo:[0,1] neg_hi:[0,1]
	v_pk_add_f32 v[116:117], v[66:67], v[84:85]
	v_pk_add_f32 v[66:67], v[66:67], v[84:85] neg_lo:[0,1] neg_hi:[0,1]
	s_nop 0
	v_pk_mul_f32 v[84:85], v[66:67], s[14:15]
	s_nop 0
	v_pk_fma_f32 v[66:67], v[66:67], s[6:7], v[84:85] op_sel:[0,0,1] op_sel_hi:[1,0,0]
	v_pk_add_f32 v[84:85], v[68:69], v[86:87]
	v_pk_add_f32 v[68:69], v[68:69], v[86:87] neg_lo:[0,1] neg_hi:[0,1]
	s_nop 0
	v_pk_mul_f32 v[86:87], v[68:69], s[10:11]
	s_nop 0
	v_pk_fma_f32 v[68:69], v[68:69], s[10:11], v[86:87] op_sel:[0,0,1] op_sel_hi:[1,0,0]
	v_pk_add_f32 v[86:87], v[72:73], v[88:89]
	v_pk_add_f32 v[72:73], v[72:73], v[88:89] neg_lo:[0,1] neg_hi:[0,1]
	s_nop 0
	v_pk_mul_f32 v[88:89], v[72:73], s[6:7]
	s_nop 0
	v_pk_fma_f32 v[72:73], v[72:73], s[14:15], v[88:89] op_sel:[0,0,1] op_sel_hi:[1,0,0]
	v_pk_add_f32 v[88:89], v[74:75], v[90:91]
	v_pk_add_f32 v[90:91], v[74:75], v[90:91] op_sel:[1,1] op_sel_hi:[0,0] neg_lo:[1,0] neg_hi:[0,1]
	s_nop 0
	v_pk_add_f32 v[74:75], v[76:77], v[92:93]
	v_pk_add_f32 v[76:77], v[76:77], v[92:93] neg_lo:[0,1] neg_hi:[0,1]
	s_nop 0
	v_pk_mul_f32 v[92:93], v[76:77], s[6:7]
	s_nop 0
	v_pk_fma_f32 v[76:77], v[76:77], s[4:5], v[92:93] op_sel:[0,0,1] op_sel_hi:[1,0,0]
	v_pk_add_f32 v[92:93], v[78:79], v[94:95]
	v_pk_add_f32 v[78:79], v[78:79], v[94:95] neg_lo:[0,1] neg_hi:[0,1]
	s_mov_b32 s5, 0
	v_pk_mul_f32 v[94:95], v[78:79], s[10:11]
	s_nop 0
	v_pk_fma_f32 v[78:79], v[78:79], s[8:9], v[94:95] op_sel:[0,0,1] op_sel_hi:[1,0,0]
	v_pk_add_f32 v[94:95], v[80:81], v[96:97]
	v_pk_add_f32 v[80:81], v[80:81], v[96:97] neg_lo:[0,1] neg_hi:[0,1]
	s_nop 0
	v_pk_mul_f32 v[96:97], v[80:81], s[14:15]
	s_nop 0
	v_pk_fma_f32 v[80:81], v[80:81], s[12:13], v[96:97] op_sel:[0,0,1] op_sel_hi:[1,0,0]
	v_pk_add_f32 v[96:97], v[132:133], v[120:121]
	v_pk_add_f32 v[120:121], v[132:133], v[120:121] neg_lo:[0,1] neg_hi:[0,1]
	v_pk_add_f32 v[132:133], v[134:135], v[106:107]
	v_pk_add_f32 v[106:107], v[134:135], v[106:107] neg_lo:[0,1] neg_hi:[0,1]
	s_nop 0
	v_pk_mul_f32 v[134:135], v[106:107], s[10:11]
	s_nop 0
	v_pk_fma_f32 v[106:107], v[106:107], s[10:11], v[134:135] op_sel:[0,0,1] op_sel_hi:[1,0,0]
	v_pk_add_f32 v[134:135], v[130:131], v[124:125]
	v_pk_add_f32 v[130:131], v[130:131], v[124:125] op_sel:[1,1] op_sel_hi:[0,0] neg_lo:[1,0] neg_hi:[0,1]
	s_nop 0
	v_pk_add_f32 v[124:125], v[118:119], v[126:127]
	v_pk_add_f32 v[118:119], v[118:119], v[126:127] neg_lo:[0,1] neg_hi:[0,1]
	s_nop 0
	v_pk_mul_f32 v[126:127], v[118:119], s[10:11]
	s_nop 0
	v_pk_fma_f32 v[118:119], v[118:119], s[8:9], v[126:127] op_sel:[0,0,1] op_sel_hi:[1,0,0]
	v_pk_add_f32 v[126:127], v[114:115], v[122:123]
	v_pk_add_f32 v[114:115], v[114:115], v[122:123] neg_lo:[0,1] neg_hi:[0,1]
	v_pk_add_f32 v[122:123], v[82:83], v[108:109]
	v_pk_add_f32 v[82:83], v[82:83], v[108:109] neg_lo:[0,1] neg_hi:[0,1]
	s_nop 0
	v_pk_mul_f32 v[108:109], v[82:83], s[10:11]
	s_nop 0
	v_pk_fma_f32 v[82:83], v[82:83], s[10:11], v[108:109] op_sel:[0,0,1] op_sel_hi:[1,0,0]
	v_pk_add_f32 v[108:109], v[100:101], v[110:111]
	v_pk_add_f32 v[110:111], v[100:101], v[110:111] op_sel:[1,1] op_sel_hi:[0,0] neg_lo:[1,0] neg_hi:[0,1]
	s_nop 0
	v_pk_add_f32 v[100:101], v[102:103], v[112:113]
	v_pk_add_f32 v[102:103], v[102:103], v[112:113] neg_lo:[0,1] neg_hi:[0,1]
	s_nop 0
	v_pk_mul_f32 v[112:113], v[102:103], s[10:11]
	s_nop 0
	v_pk_fma_f32 v[102:103], v[102:103], s[8:9], v[112:113] op_sel:[0,0,1] op_sel_hi:[1,0,0]
	v_pk_add_f32 v[112:113], v[128:129], v[88:89]
	v_pk_add_f32 v[88:89], v[128:129], v[88:89] neg_lo:[0,1] neg_hi:[0,1]
	v_pk_add_f32 v[128:129], v[116:117], v[74:75]
	v_pk_add_f32 v[74:75], v[116:117], v[74:75] neg_lo:[0,1] neg_hi:[0,1]
	s_nop 0
	v_pk_mul_f32 v[116:117], v[74:75], s[10:11]
	s_nop 0
	v_pk_fma_f32 v[74:75], v[74:75], s[10:11], v[116:117] op_sel:[0,0,1] op_sel_hi:[1,0,0]
	v_pk_add_f32 v[116:117], v[84:85], v[92:93]
	v_pk_add_f32 v[92:93], v[84:85], v[92:93] op_sel:[1,1] op_sel_hi:[0,0] neg_lo:[1,0] neg_hi:[0,1]
	s_nop 0
	v_pk_add_f32 v[84:85], v[86:87], v[94:95]
	v_pk_add_f32 v[86:87], v[86:87], v[94:95] neg_lo:[0,1] neg_hi:[0,1]
	s_nop 0
	v_pk_mul_f32 v[94:95], v[86:87], s[10:11]
	s_nop 0
	v_pk_fma_f32 v[86:87], v[86:87], s[8:9], v[94:95] op_sel:[0,0,1] op_sel_hi:[1,0,0]
	v_pk_add_f32 v[94:95], v[98:99], v[90:91]
	v_pk_add_f32 v[90:91], v[98:99], v[90:91] neg_lo:[0,1] neg_hi:[0,1]
	v_pk_add_f32 v[98:99], v[66:67], v[76:77]
	v_pk_add_f32 v[66:67], v[66:67], v[76:77] neg_lo:[0,1] neg_hi:[0,1]
	s_nop 0
	v_pk_mul_f32 v[76:77], v[66:67], s[10:11]
	s_nop 0
	v_pk_fma_f32 v[66:67], v[66:67], s[10:11], v[76:77] op_sel:[0,0,1] op_sel_hi:[1,0,0]
	v_pk_add_f32 v[76:77], v[68:69], v[78:79]
	v_pk_add_f32 v[78:79], v[68:69], v[78:79] op_sel:[1,1] op_sel_hi:[0,0] neg_lo:[1,0] neg_hi:[0,1]
	s_nop 0
	v_pk_add_f32 v[68:69], v[72:73], v[80:81]
	v_pk_add_f32 v[72:73], v[72:73], v[80:81] neg_lo:[0,1] neg_hi:[0,1]
	v_pk_add_f32 v[136:137], v[90:91], v[78:79]
	v_pk_mul_f32 v[80:81], v[72:73], s[10:11]
	v_pk_add_f32 v[78:79], v[90:91], v[78:79] neg_lo:[0,1] neg_hi:[0,1]
	v_pk_fma_f32 v[72:73], v[72:73], s[8:9], v[80:81] op_sel:[0,0,1] op_sel_hi:[1,0,0]
	v_pk_add_f32 v[80:81], v[96:97], v[134:135]
	v_pk_add_f32 v[96:97], v[96:97], v[134:135] neg_lo:[0,1] neg_hi:[0,1]
	v_pk_add_f32 v[134:135], v[132:133], v[124:125]
	v_pk_add_f32 v[132:133], v[132:133], v[124:125] op_sel:[1,1] op_sel_hi:[0,0] neg_lo:[1,0] neg_hi:[0,1]
	v_pk_add_f32 v[90:91], v[66:67], v[72:73]
	v_pk_add_f32 v[124:125], v[120:121], v[130:131]
	v_pk_add_f32 v[120:121], v[120:121], v[130:131] neg_lo:[0,1] neg_hi:[0,1]
	v_pk_add_f32 v[130:131], v[106:107], v[118:119]
	v_pk_add_f32 v[118:119], v[106:107], v[118:119] op_sel:[1,1] op_sel_hi:[0,0] neg_lo:[1,0] neg_hi:[0,1]
	v_pk_add_f32 v[66:67], v[66:67], v[72:73] neg_lo:[0,1] neg_hi:[0,1]
	v_pk_add_f32 v[106:107], v[126:127], v[108:109]
	v_pk_add_f32 v[108:109], v[126:127], v[108:109] neg_lo:[0,1] neg_hi:[0,1]
	v_pk_add_f32 v[126:127], v[122:123], v[100:101]
	v_pk_add_f32 v[122:123], v[122:123], v[100:101] op_sel:[1,1] op_sel_hi:[0,0] neg_lo:[1,0] neg_hi:[0,1]
	v_xor_b32_e32 v72, 0x80000000, v67
	v_pk_add_f32 v[100:101], v[114:115], v[110:111]
	v_pk_add_f32 v[110:111], v[114:115], v[110:111] neg_lo:[0,1] neg_hi:[0,1]
	v_pk_add_f32 v[114:115], v[82:83], v[102:103]
	v_pk_add_f32 v[102:103], v[82:83], v[102:103] op_sel:[1,1] op_sel_hi:[0,0] neg_lo:[1,0] neg_hi:[0,1]
	v_mov_b32_e32 v73, v66
	v_pk_add_f32 v[82:83], v[112:113], v[116:117]
	v_pk_add_f32 v[112:113], v[112:113], v[116:117] neg_lo:[0,1] neg_hi:[0,1]
	v_pk_add_f32 v[116:117], v[128:129], v[84:85]
	v_pk_add_f32 v[128:129], v[128:129], v[84:85] op_sel:[1,1] op_sel_hi:[0,0] neg_lo:[1,0] neg_hi:[0,1]
	v_pk_add_f32 v[138:139], v[80:81], v[134:135]
	v_pk_add_f32 v[84:85], v[88:89], v[92:93]
	v_pk_add_f32 v[88:89], v[88:89], v[92:93] neg_lo:[0,1] neg_hi:[0,1]
	v_pk_add_f32 v[92:93], v[74:75], v[86:87]
	v_pk_add_f32 v[86:87], v[74:75], v[86:87] op_sel:[1,1] op_sel_hi:[0,0] neg_lo:[1,0] neg_hi:[0,1]
	v_pk_add_f32 v[80:81], v[80:81], v[134:135] neg_lo:[0,1] neg_hi:[0,1]
	v_pk_add_f32 v[74:75], v[94:95], v[76:77]
	v_pk_add_f32 v[76:77], v[94:95], v[76:77] neg_lo:[0,1] neg_hi:[0,1]
	v_pk_add_f32 v[94:95], v[98:99], v[68:69]
	v_pk_add_f32 v[98:99], v[98:99], v[68:69] op_sel:[1,1] op_sel_hi:[0,0] neg_lo:[1,0] neg_hi:[0,1]
	v_pk_add_f32 v[134:135], v[96:97], v[132:133]
	v_pk_add_f32 v[96:97], v[96:97], v[132:133] neg_lo:[0,1] neg_hi:[0,1]
	v_pk_add_f32 v[132:133], v[124:125], v[130:131]
	v_pk_add_f32 v[124:125], v[124:125], v[130:131] neg_lo:[0,1] neg_hi:[0,1]
	v_pk_add_f32 v[130:131], v[120:121], v[118:119]
	v_pk_add_f32 v[68:69], v[120:121], v[118:119] neg_lo:[0,1] neg_hi:[0,1]
	v_pk_add_f32 v[118:119], v[106:107], v[126:127]
	v_pk_add_f32 v[106:107], v[106:107], v[126:127] neg_lo:[0,1] neg_hi:[0,1]
	v_pk_add_f32 v[126:127], v[78:79], v[72:73]
	v_pk_add_f32 v[72:73], v[78:79], v[72:73] neg_lo:[0,1] neg_hi:[0,1]
	v_mul_f32_e32 v78, 0x38800000, v105
	v_sin_f32_e32 v79, v78
	v_cos_f32_e32 v78, v78
	v_pk_add_f32 v[120:121], v[108:109], v[122:123]
	v_pk_add_f32 v[108:109], v[108:109], v[122:123] neg_lo:[0,1] neg_hi:[0,1]
	v_pk_add_f32 v[122:123], v[100:101], v[114:115]
	v_pk_add_f32 v[100:101], v[100:101], v[114:115] neg_lo:[0,1] neg_hi:[0,1]
	v_pk_add_f32 v[114:115], v[110:111], v[102:103]
	v_pk_add_f32 v[66:67], v[110:111], v[102:103] neg_lo:[0,1] neg_hi:[0,1]
	v_pk_add_f32 v[102:103], v[82:83], v[116:117]
	v_pk_add_f32 v[82:83], v[82:83], v[116:117] neg_lo:[0,1] neg_hi:[0,1]
	v_pk_add_f32 v[116:117], v[84:85], v[92:93]
	v_pk_add_f32 v[84:85], v[84:85], v[92:93] neg_lo:[0,1] neg_hi:[0,1]
	v_pk_add_f32 v[92:93], v[88:89], v[86:87]
	v_pk_add_f32 v[86:87], v[88:89], v[86:87] neg_lo:[0,1] neg_hi:[0,1]
	v_pk_add_f32 v[88:89], v[74:75], v[94:95]
	v_pk_add_f32 v[74:75], v[74:75], v[94:95] neg_lo:[0,1] neg_hi:[0,1]
	v_pk_add_f32 v[94:95], v[76:77], v[98:99]
	v_pk_add_f32 v[76:77], v[76:77], v[98:99] neg_lo:[0,1] neg_hi:[0,1]
	v_pk_add_f32 v[98:99], v[136:137], v[90:91]
	v_pk_add_f32 v[90:91], v[136:137], v[90:91] neg_lo:[0,1] neg_hi:[0,1]
	v_sin_f32_e32 v136, v71
	v_pk_add_f32 v[110:111], v[112:113], v[128:129]
	v_pk_add_f32 v[112:113], v[112:113], v[128:129] neg_lo:[0,1] neg_hi:[0,1]
	v_cos_f32_e32 v128, v71
	v_pk_mul_f32 v[140:141], v[138:139], v[78:79] op_sel:[1,1] op_sel_hi:[0,1] neg_lo:[0,1]
	s_nop 0
	v_pk_fma_f32 v[138:139], v[138:139], v[78:79], v[140:141] op_sel_hi:[1,0,1]
	ds_write_b64 v142, v[138:139]
	v_pk_mul_f32 v[138:139], v[136:137], v[78:79] op_sel:[0,1] op_sel_hi:[0,0] neg_lo:[1,0]
	v_pk_fma_f32 v[78:79], v[78:79], v[128:129], v[138:139] op_sel_hi:[1,0,1]
	s_nop 0
	v_pk_mul_f32 v[138:139], v[102:103], v[78:79] op_sel:[1,1] op_sel_hi:[0,1] neg_lo:[0,1]
	s_nop 0
	v_pk_fma_f32 v[102:103], v[102:103], v[78:79], v[138:139] op_sel_hi:[1,0,1]
	v_pk_mul_f32 v[138:139], v[136:137], v[78:79] op_sel:[0,1] op_sel_hi:[0,0] neg_lo:[1,0]
	v_pk_fma_f32 v[78:79], v[78:79], v[128:129], v[138:139] op_sel_hi:[1,0,1]
	s_nop 0
	v_pk_mul_f32 v[138:139], v[118:119], v[78:79] op_sel:[1,1] op_sel_hi:[0,1] neg_lo:[0,1]
	s_nop 0
	v_pk_fma_f32 v[118:119], v[118:119], v[78:79], v[138:139] op_sel_hi:[1,0,1]
	ds_write2_b64 v0, v[102:103], v[118:119] offset0:33 offset1:66
	v_pk_mul_f32 v[102:103], v[136:137], v[78:79] op_sel:[0,1] op_sel_hi:[0,0] neg_lo:[1,0]
	v_pk_fma_f32 v[78:79], v[78:79], v[128:129], v[102:103] op_sel_hi:[1,0,1]
	s_nop 0
	v_pk_mul_f32 v[102:103], v[88:89], v[78:79] op_sel:[1,1] op_sel_hi:[0,1] neg_lo:[0,1]
	s_nop 0
	v_pk_fma_f32 v[88:89], v[88:89], v[78:79], v[102:103] op_sel_hi:[1,0,1]
	v_pk_mul_f32 v[102:103], v[136:137], v[78:79] op_sel:[0,1] op_sel_hi:[0,0] neg_lo:[1,0]
	v_pk_fma_f32 v[78:79], v[78:79], v[128:129], v[102:103] op_sel_hi:[1,0,1]
	s_nop 0
	v_pk_mul_f32 v[102:103], v[132:133], v[78:79] op_sel:[1,1] op_sel_hi:[0,1] neg_lo:[0,1]
	s_nop 0
	v_pk_fma_f32 v[102:103], v[132:133], v[78:79], v[102:103] op_sel_hi:[1,0,1]
	ds_write2_b64 v0, v[88:89], v[102:103] offset0:99 offset1:132
	v_pk_mul_f32 v[88:89], v[136:137], v[78:79] op_sel:[0,1] op_sel_hi:[0,0] neg_lo:[1,0]
	v_pk_fma_f32 v[78:79], v[78:79], v[128:129], v[88:89] op_sel_hi:[1,0,1]
	s_nop 0
	v_pk_mul_f32 v[88:89], v[116:117], v[78:79] op_sel:[1,1] op_sel_hi:[0,1] neg_lo:[0,1]
	v_pk_mul_f32 v[102:103], v[136:137], v[78:79] op_sel:[0,1] op_sel_hi:[0,0] neg_lo:[1,0]
	v_pk_fma_f32 v[88:89], v[116:117], v[78:79], v[88:89] op_sel_hi:[1,0,1]
	v_pk_fma_f32 v[78:79], v[78:79], v[128:129], v[102:103] op_sel_hi:[1,0,1]
	s_nop 0
	v_pk_mul_f32 v[102:103], v[122:123], v[78:79] op_sel:[1,1] op_sel_hi:[0,1] neg_lo:[0,1]
	s_nop 0
	v_pk_fma_f32 v[102:103], v[122:123], v[78:79], v[102:103] op_sel_hi:[1,0,1]
	ds_write2_b64 v0, v[88:89], v[102:103] offset0:165 offset1:198
	v_pk_mul_f32 v[88:89], v[136:137], v[78:79] op_sel:[0,1] op_sel_hi:[0,0] neg_lo:[1,0]
	v_pk_fma_f32 v[78:79], v[78:79], v[128:129], v[88:89] op_sel_hi:[1,0,1]
	s_nop 0
	v_pk_mul_f32 v[88:89], v[98:99], v[78:79] op_sel:[1,1] op_sel_hi:[0,1] neg_lo:[0,1]
	s_nop 0
	v_pk_fma_f32 v[88:89], v[98:99], v[78:79], v[88:89] op_sel_hi:[1,0,1]
	v_pk_mul_f32 v[98:99], v[136:137], v[78:79] op_sel:[0,1] op_sel_hi:[0,0] neg_lo:[1,0]
	v_pk_fma_f32 v[78:79], v[78:79], v[128:129], v[98:99] op_sel_hi:[1,0,1]
	s_nop 0
	v_pk_mul_f32 v[98:99], v[134:135], v[78:79] op_sel:[1,1] op_sel_hi:[0,1] neg_lo:[0,1]
	s_nop 0
	v_pk_fma_f32 v[98:99], v[134:135], v[78:79], v[98:99] op_sel_hi:[1,0,1]
	ds_write2_b64 v143, v[88:89], v[98:99] offset0:103 offset1:136
	v_pk_mul_f32 v[88:89], v[136:137], v[78:79] op_sel:[0,1] op_sel_hi:[0,0] neg_lo:[1,0]
	v_pk_fma_f32 v[78:79], v[78:79], v[128:129], v[88:89] op_sel_hi:[1,0,1]
	s_nop 0
	v_pk_mul_f32 v[88:89], v[110:111], v[78:79] op_sel:[1,1] op_sel_hi:[0,1] neg_lo:[0,1]
	v_pk_mul_f32 v[98:99], v[136:137], v[78:79] op_sel:[0,1] op_sel_hi:[0,0] neg_lo:[1,0]
	v_pk_fma_f32 v[88:89], v[110:111], v[78:79], v[88:89] op_sel_hi:[1,0,1]
	v_pk_fma_f32 v[78:79], v[78:79], v[128:129], v[98:99] op_sel_hi:[1,0,1]
	s_nop 0
	v_pk_mul_f32 v[98:99], v[120:121], v[78:79] op_sel:[1,1] op_sel_hi:[0,1] neg_lo:[0,1]
	s_nop 0
	v_pk_fma_f32 v[98:99], v[120:121], v[78:79], v[98:99] op_sel_hi:[1,0,1]
	ds_write2_b64 v144, v[88:89], v[98:99] offset0:41 offset1:74
	v_pk_mul_f32 v[88:89], v[136:137], v[78:79] op_sel:[0,1] op_sel_hi:[0,0] neg_lo:[1,0]
	v_pk_fma_f32 v[78:79], v[78:79], v[128:129], v[88:89] op_sel_hi:[1,0,1]
	s_nop 0
	v_pk_mul_f32 v[88:89], v[94:95], v[78:79] op_sel:[1,1] op_sel_hi:[0,1] neg_lo:[0,1]
	s_nop 0
	v_pk_fma_f32 v[88:89], v[94:95], v[78:79], v[88:89] op_sel_hi:[1,0,1]
	v_pk_mul_f32 v[94:95], v[136:137], v[78:79] op_sel:[0,1] op_sel_hi:[0,0] neg_lo:[1,0]
	v_pk_fma_f32 v[78:79], v[78:79], v[128:129], v[94:95] op_sel_hi:[1,0,1]
	s_nop 0
	v_pk_mul_f32 v[94:95], v[130:131], v[78:79] op_sel:[1,1] op_sel_hi:[0,1] neg_lo:[0,1]
	v_pk_fma_f32 v[94:95], v[130:131], v[78:79], v[94:95] op_sel_hi:[1,0,1]
	ds_write2_b64 v144, v[88:89], v[94:95] offset0:107 offset1:140
	v_pk_mul_f32 v[88:89], v[136:137], v[78:79] op_sel:[0,1] op_sel_hi:[0,0] neg_lo:[1,0]
	v_pk_fma_f32 v[78:79], v[78:79], v[128:129], v[88:89] op_sel_hi:[1,0,1]
	s_nop 0
	v_pk_mul_f32 v[88:89], v[92:93], v[78:79] op_sel:[1,1] op_sel_hi:[0,1] neg_lo:[0,1]
	v_pk_fma_f32 v[88:89], v[92:93], v[78:79], v[88:89] op_sel_hi:[1,0,1]
	v_pk_mul_f32 v[92:93], v[136:137], v[78:79] op_sel:[0,1] op_sel_hi:[0,0] neg_lo:[1,0]
	v_pk_fma_f32 v[78:79], v[78:79], v[128:129], v[92:93] op_sel_hi:[1,0,1]
	s_nop 0
	v_pk_mul_f32 v[92:93], v[114:115], v[78:79] op_sel:[1,1] op_sel_hi:[0,1] neg_lo:[0,1]
	v_pk_fma_f32 v[92:93], v[114:115], v[78:79], v[92:93] op_sel_hi:[1,0,1]
	ds_write2_b64 v144, v[88:89], v[92:93] offset0:173 offset1:206
	v_pk_mul_f32 v[88:89], v[136:137], v[78:79] op_sel:[0,1] op_sel_hi:[0,0] neg_lo:[1,0]
	v_pk_fma_f32 v[78:79], v[78:79], v[128:129], v[88:89] op_sel_hi:[1,0,1]
	s_nop 0
	v_pk_mul_f32 v[88:89], v[126:127], v[78:79] op_sel:[1,1] op_sel_hi:[0,1] neg_lo:[0,1]
	v_pk_mul_f32 v[92:93], v[136:137], v[78:79] op_sel:[0,1] op_sel_hi:[0,0] neg_lo:[1,0]
	v_pk_fma_f32 v[88:89], v[126:127], v[78:79], v[88:89] op_sel_hi:[1,0,1]
	v_pk_fma_f32 v[78:79], v[78:79], v[128:129], v[92:93] op_sel_hi:[1,0,1]
	s_nop 0
	v_pk_mul_f32 v[92:93], v[80:81], v[78:79] op_sel:[1,1] op_sel_hi:[0,1] neg_lo:[0,1]
	v_pk_fma_f32 v[80:81], v[80:81], v[78:79], v[92:93] op_sel_hi:[1,0,1]
	ds_write2_b64 v145, v[88:89], v[80:81] offset0:111 offset1:144
	v_pk_mul_f32 v[80:81], v[136:137], v[78:79] op_sel:[0,1] op_sel_hi:[0,0] neg_lo:[1,0]
	v_pk_fma_f32 v[78:79], v[78:79], v[128:129], v[80:81] op_sel_hi:[1,0,1]
	s_nop 0
	v_pk_mul_f32 v[80:81], v[82:83], v[78:79] op_sel:[1,1] op_sel_hi:[0,1] neg_lo:[0,1]
	v_pk_fma_f32 v[80:81], v[82:83], v[78:79], v[80:81] op_sel_hi:[1,0,1]
	v_pk_mul_f32 v[82:83], v[136:137], v[78:79] op_sel:[0,1] op_sel_hi:[0,0] neg_lo:[1,0]
	v_pk_fma_f32 v[78:79], v[78:79], v[128:129], v[82:83] op_sel_hi:[1,0,1]
	s_nop 0
	v_pk_mul_f32 v[82:83], v[106:107], v[78:79] op_sel:[1,1] op_sel_hi:[0,1] neg_lo:[0,1]
	v_pk_fma_f32 v[82:83], v[106:107], v[78:79], v[82:83] op_sel_hi:[1,0,1]
	ds_write2_b64 v146, v[80:81], v[82:83] offset0:49 offset1:82
	v_pk_mul_f32 v[80:81], v[136:137], v[78:79] op_sel:[0,1] op_sel_hi:[0,0] neg_lo:[1,0]
	v_pk_fma_f32 v[78:79], v[78:79], v[128:129], v[80:81] op_sel_hi:[1,0,1]
	s_nop 0
	v_pk_mul_f32 v[80:81], v[74:75], v[78:79] op_sel:[1,1] op_sel_hi:[0,1] neg_lo:[0,1]
	v_pk_fma_f32 v[74:75], v[74:75], v[78:79], v[80:81] op_sel_hi:[1,0,1]
	v_pk_mul_f32 v[80:81], v[136:137], v[78:79] op_sel:[0,1] op_sel_hi:[0,0] neg_lo:[1,0]
	v_pk_fma_f32 v[78:79], v[78:79], v[128:129], v[80:81] op_sel_hi:[1,0,1]
	s_nop 0
	v_pk_mul_f32 v[80:81], v[124:125], v[78:79] op_sel:[1,1] op_sel_hi:[0,1] neg_lo:[0,1]
	v_pk_fma_f32 v[80:81], v[124:125], v[78:79], v[80:81] op_sel_hi:[1,0,1]
	ds_write2_b64 v146, v[74:75], v[80:81] offset0:115 offset1:148
	v_pk_mul_f32 v[74:75], v[136:137], v[78:79] op_sel:[0,1] op_sel_hi:[0,0] neg_lo:[1,0]
	v_pk_fma_f32 v[74:75], v[78:79], v[128:129], v[74:75] op_sel_hi:[1,0,1]
	s_nop 0
	v_pk_mul_f32 v[78:79], v[84:85], v[74:75] op_sel:[1,1] op_sel_hi:[0,1] neg_lo:[0,1]
	v_pk_mul_f32 v[80:81], v[136:137], v[74:75] op_sel:[0,1] op_sel_hi:[0,0] neg_lo:[1,0]
	v_pk_fma_f32 v[78:79], v[84:85], v[74:75], v[78:79] op_sel_hi:[1,0,1]
	v_pk_fma_f32 v[74:75], v[74:75], v[128:129], v[80:81] op_sel_hi:[1,0,1]
	s_nop 0
	v_pk_mul_f32 v[80:81], v[100:101], v[74:75] op_sel:[1,1] op_sel_hi:[0,1] neg_lo:[0,1]
	v_pk_fma_f32 v[80:81], v[100:101], v[74:75], v[80:81] op_sel_hi:[1,0,1]
	ds_write2_b64 v146, v[78:79], v[80:81] offset0:181 offset1:214
	v_pk_mul_f32 v[78:79], v[136:137], v[74:75] op_sel:[0,1] op_sel_hi:[0,0] neg_lo:[1,0]
	v_pk_fma_f32 v[74:75], v[74:75], v[128:129], v[78:79] op_sel_hi:[1,0,1]
	s_nop 0
	v_pk_mul_f32 v[78:79], v[90:91], v[74:75] op_sel:[1,1] op_sel_hi:[0,1] neg_lo:[0,1]
	v_pk_mul_f32 v[80:81], v[136:137], v[74:75] op_sel:[0,1] op_sel_hi:[0,0] neg_lo:[1,0]
	v_pk_fma_f32 v[78:79], v[90:91], v[74:75], v[78:79] op_sel_hi:[1,0,1]
	v_pk_fma_f32 v[74:75], v[74:75], v[128:129], v[80:81] op_sel_hi:[1,0,1]
	s_nop 0
	v_pk_mul_f32 v[80:81], v[96:97], v[74:75] op_sel:[1,1] op_sel_hi:[0,1] neg_lo:[0,1]
	v_pk_fma_f32 v[80:81], v[96:97], v[74:75], v[80:81] op_sel_hi:[1,0,1]
	ds_write2_b64 v147, v[78:79], v[80:81] offset0:119 offset1:152
	v_pk_mul_f32 v[78:79], v[136:137], v[74:75] op_sel:[0,1] op_sel_hi:[0,0] neg_lo:[1,0]
	v_pk_fma_f32 v[74:75], v[74:75], v[128:129], v[78:79] op_sel_hi:[1,0,1]
	s_nop 0
	v_pk_mul_f32 v[78:79], v[112:113], v[74:75] op_sel:[1,1] op_sel_hi:[0,1] neg_lo:[0,1]
	v_pk_mul_f32 v[80:81], v[136:137], v[74:75] op_sel:[0,1] op_sel_hi:[0,0] neg_lo:[1,0]
	v_pk_fma_f32 v[78:79], v[112:113], v[74:75], v[78:79] op_sel_hi:[1,0,1]
	v_pk_fma_f32 v[74:75], v[74:75], v[128:129], v[80:81] op_sel_hi:[1,0,1]
	s_nop 0
	v_pk_mul_f32 v[80:81], v[108:109], v[74:75] op_sel:[1,1] op_sel_hi:[0,1] neg_lo:[0,1]
	v_pk_fma_f32 v[80:81], v[108:109], v[74:75], v[80:81] op_sel_hi:[1,0,1]
	ds_write2_b64 v70, v[78:79], v[80:81] offset0:57 offset1:90
	v_pk_mul_f32 v[78:79], v[136:137], v[74:75] op_sel:[0,1] op_sel_hi:[0,0] neg_lo:[1,0]
	v_pk_fma_f32 v[74:75], v[74:75], v[128:129], v[78:79] op_sel_hi:[1,0,1]
	s_nop 0
	v_pk_mul_f32 v[78:79], v[76:77], v[74:75] op_sel:[1,1] op_sel_hi:[0,1] neg_lo:[0,1]
	v_pk_fma_f32 v[76:77], v[76:77], v[74:75], v[78:79] op_sel_hi:[1,0,1]
	v_pk_mul_f32 v[78:79], v[136:137], v[74:75] op_sel:[0,1] op_sel_hi:[0,0] neg_lo:[1,0]
	v_pk_fma_f32 v[74:75], v[74:75], v[128:129], v[78:79] op_sel_hi:[1,0,1]
	s_nop 0
	v_pk_mul_f32 v[78:79], v[68:69], v[74:75] op_sel:[1,1] op_sel_hi:[0,1] neg_lo:[0,1]
	v_pk_fma_f32 v[68:69], v[68:69], v[74:75], v[78:79] op_sel_hi:[1,0,1]
	ds_write2_b64 v70, v[76:77], v[68:69] offset0:123 offset1:156
	v_pk_mul_f32 v[68:69], v[136:137], v[74:75] op_sel:[0,1] op_sel_hi:[0,0] neg_lo:[1,0]
	v_pk_fma_f32 v[68:69], v[74:75], v[128:129], v[68:69] op_sel_hi:[1,0,1]
	s_nop 0
	v_pk_mul_f32 v[74:75], v[86:87], v[68:69] op_sel:[1,1] op_sel_hi:[0,1] neg_lo:[0,1]
	v_pk_mul_f32 v[76:77], v[136:137], v[68:69] op_sel:[0,1] op_sel_hi:[0,0] neg_lo:[1,0]
	v_pk_fma_f32 v[74:75], v[86:87], v[68:69], v[74:75] op_sel_hi:[1,0,1]
	v_pk_fma_f32 v[68:69], v[68:69], v[128:129], v[76:77] op_sel_hi:[1,0,1]
	s_nop 0
	v_pk_mul_f32 v[76:77], v[66:67], v[68:69] op_sel:[1,1] op_sel_hi:[0,1] neg_lo:[0,1]
	v_pk_fma_f32 v[66:67], v[66:67], v[68:69], v[76:77] op_sel_hi:[1,0,1]
	ds_write2_b64 v70, v[74:75], v[66:67] offset0:189 offset1:222
	v_pk_mul_f32 v[66:67], v[136:137], v[68:69] op_sel:[0,1] op_sel_hi:[0,0] neg_lo:[1,0]
	v_pk_fma_f32 v[66:67], v[68:69], v[128:129], v[66:67] op_sel_hi:[1,0,1]
	s_nop 0
	v_pk_mul_f32 v[68:69], v[72:73], v[66:67] op_sel:[1,1] op_sel_hi:[0,1] neg_lo:[0,1]
	v_pk_fma_f32 v[66:67], v[72:73], v[66:67], v[68:69] op_sel_hi:[1,0,1]
	ds_write_b64 v0, v[66:67] offset:8184
	s_waitcnt lgkmcnt(0)
	s_barrier
